# DPP strategy extended: attention-sample xor-1/2/4/8 lane butterflies via DPP moves instead of ds_bpermute round trips (non-SSD half of phase C), on top of the SSD DPP scan and permlane partial sums
# speedup vs baseline: 1.0023x; 1.0023x over previous
; __device__ __forceinline__ u32x2 pack4(f32x4 v) { u32x2 r; r.x = cvt_pk(v[0], v[1]); r.y = cvt_pk(v[2], v[3]); return r; }
; __device__ __forceinline__ float shfl_xor_f(float v, int mask) { const int l = lane_fresh(); return __int_as_float(__builtin_amdgcn_ds_bpermute((l ^ mask) << 2, __float_as_int(v))); }
; __device__ __forceinline__ float wave_sum(float v) {
; #pragma unroll
;   for (int o = 32; o >= 1; o >>= 1) v += shfl_xor_f(v, o);
;   return v;
; }
; __device__ __forceinline__ void phaseA(const Params& p, const int wv, const int rep) {
;     ...
;     while (r_ < rend) {
;       const int rn = r_ + nw;
;       f32x4 vn[4] = {v[0], v[1], v[2], v[3]};
;       if (rn < rend) { const float* x = rowsrc(rn);
; #pragma unroll
;         for (int i = 0; i < 4; ++i) vn[i] = *(const f32x4*)(x + (i * 64 + lane) * 4); }
;       const int r = r_ >= T + 2048 ? r_ - (T + 2048) : r_;
;       const float* w = r < T ? p.in[7] : p.in[19];
;       u16* dst = r < T ? XN + (size_t)r * 1024 : MN + (size_t)(r - T) * 1024;
;       float ss = 0.f;
; #pragma unroll
;       for (int i = 0; i < 4; ++i) ss += v[i][0] * v[i][0] + v[i][1] * v[i][1] + v[i][2] * v[i][2] + v[i][3] * v[i][3];
;       ss = wave_sum(ss);
;       const float rstd = rsqrtf(ss * (1.f / 1024.f) + EPS);
; #pragma unroll
;       for (int i = 0; i < 4; ++i) { f32x4 wv4 = *(const f32x4*)(w + (i * 64 + lane) * 4); *(u32x2*)(dst + (i * 64 + lane) * 4) = pack4(v[i] * rstd * wv4); }
; #pragma unroll
;       for (int i = 0; i < 4; ++i) v[i] = vn[i];
;       r_ = rn;
;     }
.LBB0_100:
	s_add_i32 s0, s18, 0xffffb780
	s_cmpk_gt_i32 s18, 0x487f
	s_cselect_b32 s0, s0, s18
	s_add_i32 s8, s0, 0xffffbf80
	s_ashr_i32 s9, s0, 31
	v_readlane_b32 s56, v251, 6
	v_readlane_b32 s12, v251, 22
	s_cmpk_lt_i32 s0, 0x4080
	v_readlane_b32 s70, v251, 20
	v_readlane_b32 s71, v251, 21
	v_readlane_b32 s18, v251, 28
	v_readlane_b32 s19, v251, 29
	s_cselect_b32 s10, s71, s19
	s_cselect_b32 s11, s70, s18
	v_mov_b32_e32 v42, s11
	v_mov_b32_e32 v43, s10
	v_lshl_add_u64 v[42:43], v[34:35], 2, v[42:43]
	v_pk_mul_f32 v[44:45], v[38:39], v[38:39]
	v_pk_mul_f32 v[48:49], v[36:37], v[36:37]
	v_mbcnt_lo_u32_b32 v62, -1, 0
	v_mbcnt_hi_u32_b32 v62, -1, v62
	v_mbcnt_lo_u32_b32 v63, -1, 0
	v_mbcnt_hi_u32_b32 v63, -1, v63
	v_mbcnt_lo_u32_b32 v64, -1, 0
	v_mbcnt_hi_u32_b32 v64, -1, v64
	v_mbcnt_lo_u32_b32 v65, -1, 0
	v_mbcnt_hi_u32_b32 v65, -1, v65
	v_mbcnt_lo_u32_b32 v66, -1, 0
	v_mbcnt_hi_u32_b32 v66, -1, v66
	v_mbcnt_lo_u32_b32 v67, -1, 0
	v_mbcnt_hi_u32_b32 v67, -1, v67
	global_load_dwordx4 v[36:39], v[42:43], off
	v_pk_mul_f32 v[56:57], v[14:15], v[14:15]
	v_pk_mul_f32 v[58:59], v[10:11], v[10:11]
	v_pk_mul_f32 v[52:53], v[16:17], v[16:17]
	v_pk_mul_f32 v[54:55], v[12:13], v[12:13]
	v_mov_b32_e32 v60, v56
	v_mov_b32_e32 v61, v58
	v_mov_b32_e32 v58, v57
	v_pk_add_f32 v[56:57], v[60:61], v[58:59]
	v_mov_b32_e32 v58, v52
	v_mov_b32_e32 v59, v54
	v_pk_mul_f32 v[50:51], v[6:7], v[6:7]
	v_pk_add_f32 v[56:57], v[58:59], v[56:57]
	v_mov_b32_e32 v54, v53
	v_pk_mul_f32 v[46:47], v[8:9], v[8:9]
	v_pk_add_f32 v[52:53], v[54:55], v[56:57]
	v_mov_b32_e32 v54, v48
	v_mov_b32_e32 v55, v50
	v_mov_b32_e32 v50, v49
	v_pk_add_f32 v[48:49], v[54:55], v[50:51]
	v_mov_b32_e32 v50, v44
	v_mov_b32_e32 v51, v46
	v_pk_add_f32 v[48:49], v[50:51], v[48:49]
	v_mov_b32_e32 v46, v45
	v_pk_add_f32 v[44:45], v[46:47], v[48:49]
	v_add_f32_e32 v46, v52, v53
	v_add_f32_e32 v45, v45, v46
	v_add_f32_e32 v44, v44, v45
	v_lshlrev_b32_e32 v45, 2, v62
	v_xor_b32_e32 v45, 0x80, v45
	ds_bpermute_b32 v45, v45, v44
	v_lshlrev_b32_e32 v46, 2, v67
	v_xor_b32_e32 v46, 4, v46
	s_cselect_b32 s9, s9, 0
	s_cselect_b32 s8, s0, s8
	s_waitcnt lgkmcnt(0)
	v_add_f32_e32 v44, v44, v45
	v_lshlrev_b32_e32 v45, 2, v63
	v_xor_b32_e32 v45, 64, v45
	ds_bpermute_b32 v45, v45, v44
	s_cselect_b32 s0, s49, s55
	s_cselect_b32 s10, s48, s54
	s_lshl_b64 s[8:9], s[8:9], 11
	s_add_u32 s8, s10, s8
	s_waitcnt lgkmcnt(0)
	v_add_f32_e32 v44, v44, v45
	v_lshlrev_b32_e32 v45, 2, v64
	v_xor_b32_e32 v45, 32, v45
	s_nop 1
	v_mov_b32_dpp v45, v44 row_ror:8 row_mask:0xf bank_mask:0xf
	s_addc_u32 s9, s0, s9
	v_lshl_add_u64 v[48:49], v[34:35], 1, s[8:9]
	v_readlane_b32 s57, v251, 7
	v_readlane_b32 s58, v251, 8
	s_waitcnt lgkmcnt(0)
	v_add_f32_e32 v44, v44, v45
	v_lshlrev_b32_e32 v45, 2, v65
	v_xor_b32_e32 v45, 16, v45
	s_nop 1
	v_mov_b32_dpp v45, v44 row_shl:4 row_mask:0xf bank_mask:0x5
	v_mov_b32_dpp v45, v44 row_shr:4 row_mask:0xf bank_mask:0xa
	v_readlane_b32 s59, v251, 9
	v_readlane_b32 s60, v251, 10
	v_readlane_b32 s61, v251, 11
	v_readlane_b32 s62, v251, 12
	s_waitcnt lgkmcnt(0)
	v_add_f32_e32 v44, v44, v45
	v_lshlrev_b32_e32 v45, 2, v66
	v_xor_b32_e32 v45, 8, v45
	s_nop 1
	v_mov_b32_dpp v45, v44 quad_perm:[2,3,0,1] row_mask:0xf bank_mask:0xf
	v_readlane_b32 s63, v251, 13
	v_readlane_b32 s64, v251, 14
	v_readlane_b32 s65, v251, 15
	v_readlane_b32 s66, v251, 16
	s_waitcnt lgkmcnt(0)
	v_add_f32_e32 v44, v44, v45
	ds_bpermute_b32 v45, v46, v44
	v_readlane_b32 s67, v251, 17
	v_readlane_b32 s68, v251, 18
	v_readlane_b32 s69, v251, 19
	v_readlane_b32 s56, v251, 38
	s_waitcnt lgkmcnt(0)
	v_add_f32_e32 v44, v44, v45
	v_fmamk_f32 v44, v44, 0x3a800000, v41
	v_mul_f32_e32 v45, 0x4b800000, v44
	v_cmp_gt_f32_e32 vcc, s30, v44
	s_mov_b32 s18, s28
	v_readlane_b32 s57, v251, 39
	v_cndmask_b32_e32 v44, v44, v45, vcc
	v_rsq_f32_e32 v44, v44
	v_readlane_b32 s62, v251, 44
	v_readlane_b32 s63, v251, 45
	v_readlane_b32 s13, v251, 23
	v_mul_f32_e32 v45, 0x45800000, v44
	v_cndmask_b32_e32 v46, v44, v45, vcc
	v_pk_mul_f32 v[14:15], v[14:15], v[46:47] op_sel_hi:[1,0]
	v_pk_mul_f32 v[16:17], v[16:17], v[46:47] op_sel_hi:[1,0]
	s_waitcnt vmcnt(0)
	v_pk_mul_f32 v[14:15], v[36:37], v[14:15]
	v_pk_mul_f32 v[16:17], v[38:39], v[16:17]
	v_cvt_pk_bf16_f32 v14, v14, v15
	v_cvt_pk_bf16_f32 v15, v16, v17
	global_store_dwordx2 v[48:49], v[14:15], off
	global_load_dwordx4 v[14:17], v[42:43], off offset:1024
	v_pk_mul_f32 v[10:11], v[10:11], v[46:47] op_sel_hi:[1,0]
	v_pk_mul_f32 v[12:13], v[12:13], v[46:47] op_sel_hi:[1,0]
	v_pk_mul_f32 v[6:7], v[6:7], v[46:47] op_sel_hi:[1,0]
	v_pk_mul_f32 v[8:9], v[8:9], v[46:47] op_sel_hi:[1,0]
	v_pk_mul_f32 v[50:51], v[2:3], v[46:47] op_sel_hi:[1,0]
	v_pk_mul_f32 v[46:47], v[4:5], v[46:47] op_sel_hi:[1,0]
	v_mov_b64_e32 v[2:3], v[18:19]
	v_mov_b32_e32 v36, v18
	v_mov_b32_e32 v37, v19
	v_mov_b32_e32 v38, v20
	s_andn2_b64 vcc, exec, s[2:3]
	v_mov_b64_e32 v[4:5], v[20:21]
	v_mov_b32_e32 v39, v21
	v_readlane_b32 s14, v251, 24
	v_readlane_b32 s15, v251, 25
	v_readlane_b32 s16, v251, 26
	v_readlane_b32 s17, v251, 27
	v_readlane_b32 s20, v251, 30
	v_readlane_b32 s21, v251, 31
	v_readlane_b32 s22, v251, 32
	v_readlane_b32 s23, v251, 33
	v_readlane_b32 s24, v251, 34
	v_readlane_b32 s25, v251, 35
	v_readlane_b32 s26, v251, 36
	v_readlane_b32 s27, v251, 37
	v_readlane_b32 s58, v251, 40
	v_readlane_b32 s59, v251, 41
	v_readlane_b32 s60, v251, 42
	v_readlane_b32 s61, v251, 43
	v_readlane_b32 s64, v251, 46
	v_readlane_b32 s65, v251, 47
	v_readlane_b32 s66, v251, 48
	v_readlane_b32 s67, v251, 49
	v_readlane_b32 s68, v251, 50
	v_readlane_b32 s69, v251, 51
	v_readlane_b32 s70, v251, 52
	v_readlane_b32 s71, v251, 53
	s_waitcnt vmcnt(0)
	v_pk_mul_f32 v[12:13], v[16:17], v[12:13]
	v_pk_mul_f32 v[10:11], v[14:15], v[10:11]
	v_mov_b32_e32 v14, v22
	v_cvt_pk_bf16_f32 v10, v10, v11
	v_cvt_pk_bf16_f32 v11, v12, v13
	global_store_dwordx2 v[48:49], v[10:11], off offset:512
	global_load_dwordx4 v[10:13], v[42:43], off offset:2048
	v_mov_b32_e32 v15, v23
	v_mov_b32_e32 v16, v24
	v_mov_b32_e32 v17, v25
	s_waitcnt vmcnt(0)
	v_pk_mul_f32 v[8:9], v[12:13], v[8:9]
	v_pk_mul_f32 v[6:7], v[10:11], v[6:7]
	v_mov_b32_e32 v10, v26
	v_cvt_pk_bf16_f32 v6, v6, v7
	v_cvt_pk_bf16_f32 v7, v8, v9
	global_store_dwordx2 v[48:49], v[6:7], off offset:1024
	global_load_dwordx4 v[42:45], v[42:43], off offset:3072
	v_mov_b32_e32 v11, v27
	v_mov_b32_e32 v12, v28
	v_mov_b32_e32 v13, v29
	v_mov_b32_e32 v6, v30
	v_mov_b32_e32 v7, v31
	v_mov_b32_e32 v8, v32
	v_mov_b32_e32 v9, v33
	s_waitcnt vmcnt(0)
	v_pk_mul_f32 v[22:23], v[44:45], v[46:47]
	v_pk_mul_f32 v[24:25], v[42:43], v[50:51]
	s_nop 0
	v_cvt_pk_bf16_f32 v24, v24, v25
	v_cvt_pk_bf16_f32 v25, v22, v23
	global_store_dwordx2 v[48:49], v[24:25], off offset:1536
	s_cbranch_vccz .LBB0_109

; __device__ __forceinline__ float shfl_idx_f(float v, int src) { return __int_as_float(__builtin_amdgcn_ds_bpermute(src << 2, __float_as_int(v))); }
; __device__ __forceinline__ void ssd_sample_item(const Params& p, int item, const int wv) {
;     ...
;   const float dA = __expf(-dt * __expf(p.in[16][h]));
;   const float* st = p.in[6] + ((size_t)(b * 16 + h) * 64) * 128;
;   float* so = p.out + O_SSMS + ((size_t)(b * 16 + h) * 64) * 128;
;   float ymine = 0.f;
; #pragma unroll 8
;   for (int r = 0; r < 32; ++r) {
;     const int pp = 2 * r + hf;
;     f32x4 hv = *(const f32x4*)(st + (size_t)pp * 128 + n4);
;     const float xp = shfl_idx_f(x, pp) * dt;
;     f32x4 hn;
;     float yp = 0.f;
; #pragma unroll
;     for (int e = 0; e < 4; ++e) { hn[e] = dA * hv[e] + xp * Bv[e]; yp += hn[e] * Cv[e]; }
.LBB0_457:
	v_subrev_u32_e32 v65, 56, v32
	v_mbcnt_lo_u32_b32 v3, -1, 0
	v_mbcnt_hi_u32_b32 v3, -1, v3
	v_lshlrev_b32_e32 v3, 2, v3
	v_xor_b32_e32 v22, 64, v3
	v_xor_b32_e32 v23, 32, v3
	v_xor_b32_e32 v24, 16, v3
	v_xor_b32_e32 v25, 8, v3
	v_xor_b32_e32 v26, 4, v3
	s_mov_b64 s[12:13], 0x0
	v_lshl_add_u64 v[66:67], v[18:19], 0, s[12:13]
	global_load_dwordx4 v[84:87], v[66:67], off
	global_load_dwordx4 v[88:91], v[66:67], off offset:1024
	global_load_dwordx4 v[92:95], v[66:67], off offset:2048
	global_load_dwordx4 v[96:99], v[66:67], off offset:3072
	s_mov_b64 s[12:13], 0x1000
	v_lshl_add_u64 v[66:67], v[18:19], 0, s[12:13]
	global_load_dwordx4 v[100:103], v[66:67], off
	global_load_dwordx4 v[104:107], v[66:67], off offset:1024
	global_load_dwordx4 v[108:111], v[66:67], off offset:2048
	global_load_dwordx4 v[112:115], v[66:67], off offset:3072
	s_mov_b64 s[12:13], 0x2000
	v_lshl_add_u64 v[66:67], v[18:19], 0, s[12:13]
	global_load_dwordx4 v[116:119], v[66:67], off
	global_load_dwordx4 v[120:123], v[66:67], off offset:1024
	global_load_dwordx4 v[124:127], v[66:67], off offset:2048
	global_load_dwordx4 v[128:131], v[66:67], off offset:3072
	s_mov_b64 s[12:13], 0x3000
	v_lshl_add_u64 v[66:67], v[18:19], 0, s[12:13]
	global_load_dwordx4 v[132:135], v[66:67], off
	global_load_dwordx4 v[136:139], v[66:67], off offset:1024
	global_load_dwordx4 v[140:143], v[66:67], off offset:2048
	global_load_dwordx4 v[144:147], v[66:67], off offset:3072
	s_mov_b64 s[12:13], 0x4000
	v_lshl_add_u64 v[66:67], v[18:19], 0, s[12:13]
	global_load_dwordx4 v[148:151], v[66:67], off
	global_load_dwordx4 v[152:155], v[66:67], off offset:1024
	global_load_dwordx4 v[156:159], v[66:67], off offset:2048
	global_load_dwordx4 v[164:167], v[66:67], off offset:3072
	s_mov_b64 s[12:13], 0x5000
	v_lshl_add_u64 v[66:67], v[18:19], 0, s[12:13]
	global_load_dwordx4 v[168:171], v[66:67], off
	global_load_dwordx4 v[172:175], v[66:67], off offset:1024
	global_load_dwordx4 v[176:179], v[66:67], off offset:2048
	global_load_dwordx4 v[180:183], v[66:67], off offset:3072
	s_mov_b64 s[12:13], 0x6000
	v_lshl_add_u64 v[66:67], v[18:19], 0, s[12:13]
	global_load_dwordx4 v[184:187], v[66:67], off
	global_load_dwordx4 v[188:191], v[66:67], off offset:1024
	global_load_dwordx4 v[192:195], v[66:67], off offset:2048
	global_load_dwordx4 v[196:199], v[66:67], off offset:3072
	s_mov_b64 s[12:13], 0x7000
	v_lshl_add_u64 v[66:67], v[18:19], 0, s[12:13]
	global_load_dwordx4 v[200:203], v[66:67], off
	global_load_dwordx4 v[204:207], v[66:67], off offset:1024
	global_load_dwordx4 v[208:211], v[66:67], off offset:2048
	global_load_dwordx4 v[212:215], v[66:67], off offset:3072
	ds_bpermute_b32 v33, v65, v31
	ds_bpermute_b32 v34, v65, v31 offset:8
	ds_bpermute_b32 v35, v65, v31 offset:16
	ds_bpermute_b32 v36, v65, v31 offset:24
	ds_bpermute_b32 v37, v65, v31 offset:32
	ds_bpermute_b32 v38, v65, v31 offset:40
	ds_bpermute_b32 v39, v65, v31 offset:48
	ds_bpermute_b32 v40, v65, v31 offset:56
	ds_bpermute_b32 v41, v65, v31 offset:64
	ds_bpermute_b32 v42, v65, v31 offset:72
	ds_bpermute_b32 v43, v65, v31 offset:80
	ds_bpermute_b32 v44, v65, v31 offset:88
	ds_bpermute_b32 v45, v65, v31 offset:96
	ds_bpermute_b32 v46, v65, v31 offset:104
	ds_bpermute_b32 v47, v65, v31 offset:112
	ds_bpermute_b32 v48, v65, v31 offset:120
	s_waitcnt lgkmcnt(0)
	ds_bpermute_b32 v49, v65, v31 offset:128
	ds_bpermute_b32 v50, v65, v31 offset:136
	ds_bpermute_b32 v51, v65, v31 offset:144
	ds_bpermute_b32 v52, v65, v31 offset:152
	ds_bpermute_b32 v53, v65, v31 offset:160
	ds_bpermute_b32 v54, v65, v31 offset:168
	ds_bpermute_b32 v55, v65, v31 offset:176
	ds_bpermute_b32 v56, v65, v31 offset:184
	ds_bpermute_b32 v57, v65, v31 offset:192
	ds_bpermute_b32 v58, v65, v31 offset:200
	ds_bpermute_b32 v59, v65, v31 offset:208
	ds_bpermute_b32 v60, v65, v31 offset:216
	ds_bpermute_b32 v61, v65, v31 offset:224
	ds_bpermute_b32 v62, v65, v31 offset:232
	ds_bpermute_b32 v63, v65, v31 offset:240
	ds_bpermute_b32 v64, v65, v31 offset:248
	s_waitcnt lgkmcnt(0)
	v_mul_f32_e32 v33, v30, v33
	v_mul_f32_e32 v34, v30, v34
	v_mul_f32_e32 v35, v30, v35
	v_mul_f32_e32 v36, v30, v36
	v_mul_f32_e32 v37, v30, v37
	v_mul_f32_e32 v38, v30, v38
	v_mul_f32_e32 v39, v30, v39
	v_mul_f32_e32 v40, v30, v40
	v_mul_f32_e32 v41, v30, v41
	v_mul_f32_e32 v42, v30, v42
	v_mul_f32_e32 v43, v30, v43
	v_mul_f32_e32 v44, v30, v44
	v_mul_f32_e32 v45, v30, v45
	v_mul_f32_e32 v46, v30, v46
	v_mul_f32_e32 v47, v30, v47
	v_mul_f32_e32 v48, v30, v48
	v_mul_f32_e32 v49, v30, v49
	v_mul_f32_e32 v50, v30, v50
	v_mul_f32_e32 v51, v30, v51
	v_mul_f32_e32 v52, v30, v52
	v_mul_f32_e32 v53, v30, v53
	v_mul_f32_e32 v54, v30, v54
	v_mul_f32_e32 v55, v30, v55
	v_mul_f32_e32 v56, v30, v56
	v_mul_f32_e32 v57, v30, v57
	v_mul_f32_e32 v58, v30, v58
	v_mul_f32_e32 v59, v30, v59
	v_mul_f32_e32 v60, v30, v60
	v_mul_f32_e32 v61, v30, v61
	v_mul_f32_e32 v62, v30, v62
	v_mul_f32_e32 v63, v30, v63
	v_mul_f32_e32 v64, v30, v64
	s_mov_b64 s[12:13], 0x4ee4000
	v_lshl_add_u64 v[68:69], v[20:21], 0, s[12:13]
	s_waitcnt vmcnt(31)
	v_mul_f32_e32 v216, v6, v33
	v_mul_f32_e32 v217, v7, v33
	v_mul_f32_e32 v218, v10, v33
	v_mul_f32_e32 v219, v11, v33
	v_fma_f32 v84, v12, v84, v216
	v_fma_f32 v85, v12, v85, v217
	v_fma_f32 v86, v12, v86, v218
	v_fma_f32 v87, v12, v87, v219
	global_store_dwordx4 v[68:69], v[84:87], off
	v_mul_f32_e32 v216, v8, v84
	v_mul_f32_e32 v217, v9, v85
	v_mul_f32_e32 v218, v14, v86
	v_mul_f32_e32 v219, v15, v87
	v_add_f32_e32 v33, 0, v216
	v_add_f32_e32 v33, v217, v33
	v_add_f32_e32 v33, v218, v33
	v_add_f32_e32 v33, v219, v33
	s_waitcnt vmcnt(31)
; __device__ __forceinline__ float shfl_idx_f(float v, int src) { return __int_as_float(__builtin_amdgcn_ds_bpermute(src << 2, __float_as_int(v))); }
; __device__ __forceinline__ void ssd_sample_item(const Params& p, int item, const int wv) {
;     ...
;   for (int r = 0; r < 32; ++r) {
;     const int pp = 2 * r + hf;
;     f32x4 hv = *(const f32x4*)(st + (size_t)pp * 128 + n4);
;     const float xp = shfl_idx_f(x, pp) * dt;
;     f32x4 hn;
;     float yp = 0.f;
; #pragma unroll
;     for (int e = 0; e < 4; ++e) { hn[e] = dA * hv[e] + xp * Bv[e]; yp += hn[e] * Cv[e]; }
	v_mul_f32_e32 v216, v6, v34
	v_mul_f32_e32 v217, v7, v34
	v_mul_f32_e32 v218, v10, v34
	v_mul_f32_e32 v219, v11, v34
	v_fma_f32 v88, v12, v88, v216
	v_fma_f32 v89, v12, v89, v217
	v_fma_f32 v90, v12, v90, v218
	v_fma_f32 v91, v12, v91, v219
	global_store_dwordx4 v[68:69], v[88:91], off offset:1024
	v_mul_f32_e32 v216, v8, v88
	v_mul_f32_e32 v217, v9, v89
	v_mul_f32_e32 v218, v14, v90
	v_mul_f32_e32 v219, v15, v91
	v_add_f32_e32 v34, 0, v216
	v_add_f32_e32 v34, v217, v34
	v_add_f32_e32 v34, v218, v34
	v_add_f32_e32 v34, v219, v34
	s_waitcnt vmcnt(31)
	v_mul_f32_e32 v216, v6, v35
	v_mul_f32_e32 v217, v7, v35
	v_mul_f32_e32 v218, v10, v35
	v_mul_f32_e32 v219, v11, v35
	v_fma_f32 v92, v12, v92, v216
	v_fma_f32 v93, v12, v93, v217
	v_fma_f32 v94, v12, v94, v218
	v_fma_f32 v95, v12, v95, v219
	global_store_dwordx4 v[68:69], v[92:95], off offset:2048
	v_mul_f32_e32 v216, v8, v92
	v_mul_f32_e32 v217, v9, v93
	v_mul_f32_e32 v218, v14, v94
	v_mul_f32_e32 v219, v15, v95
	v_add_f32_e32 v35, 0, v216
	v_add_f32_e32 v35, v217, v35
	v_add_f32_e32 v35, v218, v35
	v_add_f32_e32 v35, v219, v35
	s_waitcnt vmcnt(31)
	v_mul_f32_e32 v216, v6, v36
	v_mul_f32_e32 v217, v7, v36
	v_mul_f32_e32 v218, v10, v36
	v_mul_f32_e32 v219, v11, v36
	v_fma_f32 v96, v12, v96, v216
	v_fma_f32 v97, v12, v97, v217
	v_fma_f32 v98, v12, v98, v218
	v_fma_f32 v99, v12, v99, v219
	global_store_dwordx4 v[68:69], v[96:99], off offset:3072
	v_mul_f32_e32 v216, v8, v96
	v_mul_f32_e32 v217, v9, v97
	v_mul_f32_e32 v218, v14, v98
	v_mul_f32_e32 v219, v15, v99
	v_add_f32_e32 v36, 0, v216
	v_add_f32_e32 v36, v217, v36
	v_add_f32_e32 v36, v218, v36
	v_add_f32_e32 v36, v219, v36
	s_mov_b64 s[12:13], 0x4ee5000
	v_lshl_add_u64 v[68:69], v[20:21], 0, s[12:13]
	s_waitcnt vmcnt(31)
	v_mul_f32_e32 v216, v6, v37
	v_mul_f32_e32 v217, v7, v37
	v_mul_f32_e32 v218, v10, v37
	v_mul_f32_e32 v219, v11, v37
	v_fma_f32 v100, v12, v100, v216
	v_fma_f32 v101, v12, v101, v217
	v_fma_f32 v102, v12, v102, v218
	v_fma_f32 v103, v12, v103, v219
	global_store_dwordx4 v[68:69], v[100:103], off
	v_mul_f32_e32 v216, v8, v100
	v_mul_f32_e32 v217, v9, v101
	v_mul_f32_e32 v218, v14, v102
	v_mul_f32_e32 v219, v15, v103
	v_add_f32_e32 v37, 0, v216
	v_add_f32_e32 v37, v217, v37
	v_add_f32_e32 v37, v218, v37
	v_add_f32_e32 v37, v219, v37
	s_waitcnt vmcnt(31)
	v_mul_f32_e32 v216, v6, v38
	v_mul_f32_e32 v217, v7, v38
	v_mul_f32_e32 v218, v10, v38
	v_mul_f32_e32 v219, v11, v38
	v_fma_f32 v104, v12, v104, v216
	v_fma_f32 v105, v12, v105, v217
	v_fma_f32 v106, v12, v106, v218
	v_fma_f32 v107, v12, v107, v219
	global_store_dwordx4 v[68:69], v[104:107], off offset:1024
	v_mul_f32_e32 v216, v8, v104
	v_mul_f32_e32 v217, v9, v105
	v_mul_f32_e32 v218, v14, v106
	v_mul_f32_e32 v219, v15, v107
	v_add_f32_e32 v38, 0, v216
	v_add_f32_e32 v38, v217, v38
	v_add_f32_e32 v38, v218, v38
	v_add_f32_e32 v38, v219, v38
	s_waitcnt vmcnt(31)
	v_mul_f32_e32 v216, v6, v39
	v_mul_f32_e32 v217, v7, v39
	v_mul_f32_e32 v218, v10, v39
	v_mul_f32_e32 v219, v11, v39
	v_fma_f32 v108, v12, v108, v216
	v_fma_f32 v109, v12, v109, v217
	v_fma_f32 v110, v12, v110, v218
	v_fma_f32 v111, v12, v111, v219
	global_store_dwordx4 v[68:69], v[108:111], off offset:2048
	v_mul_f32_e32 v216, v8, v108
	v_mul_f32_e32 v217, v9, v109
	v_mul_f32_e32 v218, v14, v110
	v_mul_f32_e32 v219, v15, v111
	v_add_f32_e32 v39, 0, v216
	v_add_f32_e32 v39, v217, v39
	v_add_f32_e32 v39, v218, v39
	v_add_f32_e32 v39, v219, v39
	s_waitcnt vmcnt(31)
	v_mul_f32_e32 v216, v6, v40
	v_mul_f32_e32 v217, v7, v40
	v_mul_f32_e32 v218, v10, v40
	v_mul_f32_e32 v219, v11, v40
	v_fma_f32 v112, v12, v112, v216
	v_fma_f32 v113, v12, v113, v217
	v_fma_f32 v114, v12, v114, v218
	v_fma_f32 v115, v12, v115, v219
	global_store_dwordx4 v[68:69], v[112:115], off offset:3072
	v_mul_f32_e32 v216, v8, v112
	v_mul_f32_e32 v217, v9, v113
	v_mul_f32_e32 v218, v14, v114
	v_mul_f32_e32 v219, v15, v115
	v_add_f32_e32 v40, 0, v216
	v_add_f32_e32 v40, v217, v40
	v_add_f32_e32 v40, v218, v40
	v_add_f32_e32 v40, v219, v40
	s_mov_b64 s[12:13], 0x4ee6000
	v_lshl_add_u64 v[68:69], v[20:21], 0, s[12:13]
	s_waitcnt vmcnt(31)
	v_mul_f32_e32 v216, v6, v41
	v_mul_f32_e32 v217, v7, v41
	v_mul_f32_e32 v218, v10, v41
	v_mul_f32_e32 v219, v11, v41
	v_fma_f32 v116, v12, v116, v216
	v_fma_f32 v117, v12, v117, v217
	v_fma_f32 v118, v12, v118, v218
	v_fma_f32 v119, v12, v119, v219
	global_store_dwordx4 v[68:69], v[116:119], off
	v_mul_f32_e32 v216, v8, v116
	v_mul_f32_e32 v217, v9, v117
	v_mul_f32_e32 v218, v14, v118
	v_mul_f32_e32 v219, v15, v119
	v_add_f32_e32 v41, 0, v216
	v_add_f32_e32 v41, v217, v41
	v_add_f32_e32 v41, v218, v41
	v_add_f32_e32 v41, v219, v41
	s_waitcnt vmcnt(31)
	v_mul_f32_e32 v216, v6, v42
	v_mul_f32_e32 v217, v7, v42
	v_mul_f32_e32 v218, v10, v42
	v_mul_f32_e32 v219, v11, v42
	v_fma_f32 v120, v12, v120, v216
	v_fma_f32 v121, v12, v121, v217
	v_fma_f32 v122, v12, v122, v218
	v_fma_f32 v123, v12, v123, v219
	global_store_dwordx4 v[68:69], v[120:123], off offset:1024
	v_mul_f32_e32 v216, v8, v120
	v_mul_f32_e32 v217, v9, v121
	v_mul_f32_e32 v218, v14, v122
	v_mul_f32_e32 v219, v15, v123
	v_add_f32_e32 v42, 0, v216
	v_add_f32_e32 v42, v217, v42
	v_add_f32_e32 v42, v218, v42
	v_add_f32_e32 v42, v219, v42
	s_waitcnt vmcnt(31)
	v_mul_f32_e32 v216, v6, v43
	v_mul_f32_e32 v217, v7, v43
	v_mul_f32_e32 v218, v10, v43
	v_mul_f32_e32 v219, v11, v43
	v_fma_f32 v124, v12, v124, v216
	v_fma_f32 v125, v12, v125, v217
	v_fma_f32 v126, v12, v126, v218
	v_fma_f32 v127, v12, v127, v219
	global_store_dwordx4 v[68:69], v[124:127], off offset:2048
	v_mul_f32_e32 v216, v8, v124
	v_mul_f32_e32 v217, v9, v125
	v_mul_f32_e32 v218, v14, v126
	v_mul_f32_e32 v219, v15, v127
	v_add_f32_e32 v43, 0, v216
	v_add_f32_e32 v43, v217, v43
	v_add_f32_e32 v43, v218, v43
	v_add_f32_e32 v43, v219, v43
	s_waitcnt vmcnt(31)
; __device__ __forceinline__ float shfl_idx_f(float v, int src) { return __int_as_float(__builtin_amdgcn_ds_bpermute(src << 2, __float_as_int(v))); }
; __device__ __forceinline__ void ssd_sample_item(const Params& p, int item, const int wv) {
;     ...
;   for (int r = 0; r < 32; ++r) {
;     const int pp = 2 * r + hf;
;     f32x4 hv = *(const f32x4*)(st + (size_t)pp * 128 + n4);
;     const float xp = shfl_idx_f(x, pp) * dt;
;     f32x4 hn;
;     float yp = 0.f;
; #pragma unroll
;     for (int e = 0; e < 4; ++e) { hn[e] = dA * hv[e] + xp * Bv[e]; yp += hn[e] * Cv[e]; }
	v_mul_f32_e32 v216, v6, v44
	v_mul_f32_e32 v217, v7, v44
	v_mul_f32_e32 v218, v10, v44
	v_mul_f32_e32 v219, v11, v44
	v_fma_f32 v128, v12, v128, v216
	v_fma_f32 v129, v12, v129, v217
	v_fma_f32 v130, v12, v130, v218
	v_fma_f32 v131, v12, v131, v219
	global_store_dwordx4 v[68:69], v[128:131], off offset:3072
	v_mul_f32_e32 v216, v8, v128
	v_mul_f32_e32 v217, v9, v129
	v_mul_f32_e32 v218, v14, v130
	v_mul_f32_e32 v219, v15, v131
	v_add_f32_e32 v44, 0, v216
	v_add_f32_e32 v44, v217, v44
	v_add_f32_e32 v44, v218, v44
	v_add_f32_e32 v44, v219, v44
	s_mov_b64 s[12:13], 0x4ee7000
	v_lshl_add_u64 v[68:69], v[20:21], 0, s[12:13]
	s_waitcnt vmcnt(31)
	v_mul_f32_e32 v216, v6, v45
	v_mul_f32_e32 v217, v7, v45
	v_mul_f32_e32 v218, v10, v45
	v_mul_f32_e32 v219, v11, v45
	v_fma_f32 v132, v12, v132, v216
	v_fma_f32 v133, v12, v133, v217
	v_fma_f32 v134, v12, v134, v218
	v_fma_f32 v135, v12, v135, v219
	global_store_dwordx4 v[68:69], v[132:135], off
	v_mul_f32_e32 v216, v8, v132
	v_mul_f32_e32 v217, v9, v133
	v_mul_f32_e32 v218, v14, v134
	v_mul_f32_e32 v219, v15, v135
	v_add_f32_e32 v45, 0, v216
	v_add_f32_e32 v45, v217, v45
	v_add_f32_e32 v45, v218, v45
	v_add_f32_e32 v45, v219, v45
	s_waitcnt vmcnt(31)
	v_mul_f32_e32 v216, v6, v46
	v_mul_f32_e32 v217, v7, v46
	v_mul_f32_e32 v218, v10, v46
	v_mul_f32_e32 v219, v11, v46
	v_fma_f32 v136, v12, v136, v216
	v_fma_f32 v137, v12, v137, v217
	v_fma_f32 v138, v12, v138, v218
	v_fma_f32 v139, v12, v139, v219
	global_store_dwordx4 v[68:69], v[136:139], off offset:1024
	v_mul_f32_e32 v216, v8, v136
	v_mul_f32_e32 v217, v9, v137
	v_mul_f32_e32 v218, v14, v138
	v_mul_f32_e32 v219, v15, v139
	v_add_f32_e32 v46, 0, v216
	v_add_f32_e32 v46, v217, v46
	v_add_f32_e32 v46, v218, v46
	v_add_f32_e32 v46, v219, v46
	s_waitcnt vmcnt(31)
	v_mul_f32_e32 v216, v6, v47
	v_mul_f32_e32 v217, v7, v47
	v_mul_f32_e32 v218, v10, v47
	v_mul_f32_e32 v219, v11, v47
	v_fma_f32 v140, v12, v140, v216
	v_fma_f32 v141, v12, v141, v217
	v_fma_f32 v142, v12, v142, v218
	v_fma_f32 v143, v12, v143, v219
	global_store_dwordx4 v[68:69], v[140:143], off offset:2048
	v_mul_f32_e32 v216, v8, v140
	v_mul_f32_e32 v217, v9, v141
	v_mul_f32_e32 v218, v14, v142
	v_mul_f32_e32 v219, v15, v143
	v_add_f32_e32 v47, 0, v216
	v_add_f32_e32 v47, v217, v47
	v_add_f32_e32 v47, v218, v47
	v_add_f32_e32 v47, v219, v47
	s_waitcnt vmcnt(31)
	v_mul_f32_e32 v216, v6, v48
	v_mul_f32_e32 v217, v7, v48
	v_mul_f32_e32 v218, v10, v48
	v_mul_f32_e32 v219, v11, v48
	v_fma_f32 v144, v12, v144, v216
	v_fma_f32 v145, v12, v145, v217
	v_fma_f32 v146, v12, v146, v218
	v_fma_f32 v147, v12, v147, v219
	global_store_dwordx4 v[68:69], v[144:147], off offset:3072
	v_mul_f32_e32 v216, v8, v144
	v_mul_f32_e32 v217, v9, v145
	v_mul_f32_e32 v218, v14, v146
	v_mul_f32_e32 v219, v15, v147
	v_add_f32_e32 v48, 0, v216
	v_add_f32_e32 v48, v217, v48
	v_add_f32_e32 v48, v218, v48
	v_add_f32_e32 v48, v219, v48
	s_mov_b64 s[12:13], 0x4ee8000
	v_lshl_add_u64 v[68:69], v[20:21], 0, s[12:13]
	s_waitcnt vmcnt(31)
	v_mul_f32_e32 v216, v6, v49
	v_mul_f32_e32 v217, v7, v49
	v_mul_f32_e32 v218, v10, v49
	v_mul_f32_e32 v219, v11, v49
	v_fma_f32 v148, v12, v148, v216
	v_fma_f32 v149, v12, v149, v217
	v_fma_f32 v150, v12, v150, v218
	v_fma_f32 v151, v12, v151, v219
	global_store_dwordx4 v[68:69], v[148:151], off
	v_mul_f32_e32 v216, v8, v148
	v_mul_f32_e32 v217, v9, v149
	v_mul_f32_e32 v218, v14, v150
	v_mul_f32_e32 v219, v15, v151
	v_add_f32_e32 v49, 0, v216
	v_add_f32_e32 v49, v217, v49
	v_add_f32_e32 v49, v218, v49
	v_add_f32_e32 v49, v219, v49
	s_waitcnt vmcnt(31)
	v_mul_f32_e32 v216, v6, v50
	v_mul_f32_e32 v217, v7, v50
	v_mul_f32_e32 v218, v10, v50
	v_mul_f32_e32 v219, v11, v50
	v_fma_f32 v152, v12, v152, v216
	v_fma_f32 v153, v12, v153, v217
	v_fma_f32 v154, v12, v154, v218
	v_fma_f32 v155, v12, v155, v219
	global_store_dwordx4 v[68:69], v[152:155], off offset:1024
	v_mul_f32_e32 v216, v8, v152
	v_mul_f32_e32 v217, v9, v153
	v_mul_f32_e32 v218, v14, v154
	v_mul_f32_e32 v219, v15, v155
	v_add_f32_e32 v50, 0, v216
	v_add_f32_e32 v50, v217, v50
	v_add_f32_e32 v50, v218, v50
	v_add_f32_e32 v50, v219, v50
	s_waitcnt vmcnt(31)
	v_mul_f32_e32 v216, v6, v51
	v_mul_f32_e32 v217, v7, v51
	v_mul_f32_e32 v218, v10, v51
	v_mul_f32_e32 v219, v11, v51
	v_fma_f32 v156, v12, v156, v216
	v_fma_f32 v157, v12, v157, v217
	v_fma_f32 v158, v12, v158, v218
	v_fma_f32 v159, v12, v159, v219
	global_store_dwordx4 v[68:69], v[156:159], off offset:2048
	v_mul_f32_e32 v216, v8, v156
	v_mul_f32_e32 v217, v9, v157
	v_mul_f32_e32 v218, v14, v158
	v_mul_f32_e32 v219, v15, v159
	v_add_f32_e32 v51, 0, v216
	v_add_f32_e32 v51, v217, v51
	v_add_f32_e32 v51, v218, v51
	v_add_f32_e32 v51, v219, v51
	s_waitcnt vmcnt(31)
	v_mul_f32_e32 v216, v6, v52
	v_mul_f32_e32 v217, v7, v52
	v_mul_f32_e32 v218, v10, v52
	v_mul_f32_e32 v219, v11, v52
	v_fma_f32 v164, v12, v164, v216
	v_fma_f32 v165, v12, v165, v217
	v_fma_f32 v166, v12, v166, v218
	v_fma_f32 v167, v12, v167, v219
	global_store_dwordx4 v[68:69], v[164:167], off offset:3072
	v_mul_f32_e32 v216, v8, v164
	v_mul_f32_e32 v217, v9, v165
	v_mul_f32_e32 v218, v14, v166
	v_mul_f32_e32 v219, v15, v167
	v_add_f32_e32 v52, 0, v216
	v_add_f32_e32 v52, v217, v52
	v_add_f32_e32 v52, v218, v52
	v_add_f32_e32 v52, v219, v52
	s_mov_b64 s[12:13], 0x4ee9000
	v_lshl_add_u64 v[68:69], v[20:21], 0, s[12:13]
	s_waitcnt vmcnt(31)
	v_mul_f32_e32 v216, v6, v53
	v_mul_f32_e32 v217, v7, v53
	v_mul_f32_e32 v218, v10, v53
	v_mul_f32_e32 v219, v11, v53
	v_fma_f32 v168, v12, v168, v216
	v_fma_f32 v169, v12, v169, v217
	v_fma_f32 v170, v12, v170, v218
	v_fma_f32 v171, v12, v171, v219
	global_store_dwordx4 v[68:69], v[168:171], off
	v_mul_f32_e32 v216, v8, v168
	v_mul_f32_e32 v217, v9, v169
	v_mul_f32_e32 v218, v14, v170
	v_mul_f32_e32 v219, v15, v171
	v_add_f32_e32 v53, 0, v216
	v_add_f32_e32 v53, v217, v53
	v_add_f32_e32 v53, v218, v53
	v_add_f32_e32 v53, v219, v53
	s_waitcnt vmcnt(31)
; __device__ __forceinline__ float shfl_idx_f(float v, int src) { return __int_as_float(__builtin_amdgcn_ds_bpermute(src << 2, __float_as_int(v))); }
; __device__ __forceinline__ void ssd_sample_item(const Params& p, int item, const int wv) {
;     ...
;   for (int r = 0; r < 32; ++r) {
;     const int pp = 2 * r + hf;
;     f32x4 hv = *(const f32x4*)(st + (size_t)pp * 128 + n4);
;     const float xp = shfl_idx_f(x, pp) * dt;
;     f32x4 hn;
;     float yp = 0.f;
; #pragma unroll
;     for (int e = 0; e < 4; ++e) { hn[e] = dA * hv[e] + xp * Bv[e]; yp += hn[e] * Cv[e]; }
	v_mul_f32_e32 v216, v6, v54
	v_mul_f32_e32 v217, v7, v54
	v_mul_f32_e32 v218, v10, v54
	v_mul_f32_e32 v219, v11, v54
	v_fma_f32 v172, v12, v172, v216
	v_fma_f32 v173, v12, v173, v217
	v_fma_f32 v174, v12, v174, v218
	v_fma_f32 v175, v12, v175, v219
	global_store_dwordx4 v[68:69], v[172:175], off offset:1024
	v_mul_f32_e32 v216, v8, v172
	v_mul_f32_e32 v217, v9, v173
	v_mul_f32_e32 v218, v14, v174
	v_mul_f32_e32 v219, v15, v175
	v_add_f32_e32 v54, 0, v216
	v_add_f32_e32 v54, v217, v54
	v_add_f32_e32 v54, v218, v54
	v_add_f32_e32 v54, v219, v54
	s_waitcnt vmcnt(31)
	v_mul_f32_e32 v216, v6, v55
	v_mul_f32_e32 v217, v7, v55
	v_mul_f32_e32 v218, v10, v55
	v_mul_f32_e32 v219, v11, v55
	v_fma_f32 v176, v12, v176, v216
	v_fma_f32 v177, v12, v177, v217
	v_fma_f32 v178, v12, v178, v218
	v_fma_f32 v179, v12, v179, v219
	global_store_dwordx4 v[68:69], v[176:179], off offset:2048
	v_mul_f32_e32 v216, v8, v176
	v_mul_f32_e32 v217, v9, v177
	v_mul_f32_e32 v218, v14, v178
	v_mul_f32_e32 v219, v15, v179
	v_add_f32_e32 v55, 0, v216
	v_add_f32_e32 v55, v217, v55
	v_add_f32_e32 v55, v218, v55
	v_add_f32_e32 v55, v219, v55
	s_waitcnt vmcnt(31)
	v_mul_f32_e32 v216, v6, v56
	v_mul_f32_e32 v217, v7, v56
	v_mul_f32_e32 v218, v10, v56
	v_mul_f32_e32 v219, v11, v56
	v_fma_f32 v180, v12, v180, v216
	v_fma_f32 v181, v12, v181, v217
	v_fma_f32 v182, v12, v182, v218
	v_fma_f32 v183, v12, v183, v219
	global_store_dwordx4 v[68:69], v[180:183], off offset:3072
	v_mul_f32_e32 v216, v8, v180
	v_mul_f32_e32 v217, v9, v181
	v_mul_f32_e32 v218, v14, v182
	v_mul_f32_e32 v219, v15, v183
	v_add_f32_e32 v56, 0, v216
	v_add_f32_e32 v56, v217, v56
	v_add_f32_e32 v56, v218, v56
	v_add_f32_e32 v56, v219, v56
	s_mov_b64 s[12:13], 0x4eea000
	v_lshl_add_u64 v[68:69], v[20:21], 0, s[12:13]
	s_waitcnt vmcnt(31)
	v_mul_f32_e32 v216, v6, v57
	v_mul_f32_e32 v217, v7, v57
	v_mul_f32_e32 v218, v10, v57
	v_mul_f32_e32 v219, v11, v57
	v_fma_f32 v184, v12, v184, v216
	v_fma_f32 v185, v12, v185, v217
	v_fma_f32 v186, v12, v186, v218
	v_fma_f32 v187, v12, v187, v219
	global_store_dwordx4 v[68:69], v[184:187], off
	v_mul_f32_e32 v216, v8, v184
	v_mul_f32_e32 v217, v9, v185
	v_mul_f32_e32 v218, v14, v186
	v_mul_f32_e32 v219, v15, v187
	v_add_f32_e32 v57, 0, v216
	v_add_f32_e32 v57, v217, v57
	v_add_f32_e32 v57, v218, v57
	v_add_f32_e32 v57, v219, v57
	s_waitcnt vmcnt(31)
	v_mul_f32_e32 v216, v6, v58
	v_mul_f32_e32 v217, v7, v58
	v_mul_f32_e32 v218, v10, v58
	v_mul_f32_e32 v219, v11, v58
	v_fma_f32 v188, v12, v188, v216
	v_fma_f32 v189, v12, v189, v217
	v_fma_f32 v190, v12, v190, v218
	v_fma_f32 v191, v12, v191, v219
	global_store_dwordx4 v[68:69], v[188:191], off offset:1024
	v_mul_f32_e32 v216, v8, v188
	v_mul_f32_e32 v217, v9, v189
	v_mul_f32_e32 v218, v14, v190
	v_mul_f32_e32 v219, v15, v191
	v_add_f32_e32 v58, 0, v216
	v_add_f32_e32 v58, v217, v58
	v_add_f32_e32 v58, v218, v58
	v_add_f32_e32 v58, v219, v58
	s_waitcnt vmcnt(31)
	v_mul_f32_e32 v216, v6, v59
	v_mul_f32_e32 v217, v7, v59
	v_mul_f32_e32 v218, v10, v59
	v_mul_f32_e32 v219, v11, v59
	v_fma_f32 v192, v12, v192, v216
	v_fma_f32 v193, v12, v193, v217
	v_fma_f32 v194, v12, v194, v218
	v_fma_f32 v195, v12, v195, v219
	global_store_dwordx4 v[68:69], v[192:195], off offset:2048
	v_mul_f32_e32 v216, v8, v192
	v_mul_f32_e32 v217, v9, v193
	v_mul_f32_e32 v218, v14, v194
	v_mul_f32_e32 v219, v15, v195
	v_add_f32_e32 v59, 0, v216
	v_add_f32_e32 v59, v217, v59
	v_add_f32_e32 v59, v218, v59
	v_add_f32_e32 v59, v219, v59
	s_waitcnt vmcnt(31)
	v_mul_f32_e32 v216, v6, v60
	v_mul_f32_e32 v217, v7, v60
	v_mul_f32_e32 v218, v10, v60
	v_mul_f32_e32 v219, v11, v60
	v_fma_f32 v196, v12, v196, v216
	v_fma_f32 v197, v12, v197, v217
	v_fma_f32 v198, v12, v198, v218
	v_fma_f32 v199, v12, v199, v219
	global_store_dwordx4 v[68:69], v[196:199], off offset:3072
	v_mul_f32_e32 v216, v8, v196
	v_mul_f32_e32 v217, v9, v197
	v_mul_f32_e32 v218, v14, v198
	v_mul_f32_e32 v219, v15, v199
	v_add_f32_e32 v60, 0, v216
	v_add_f32_e32 v60, v217, v60
	v_add_f32_e32 v60, v218, v60
	v_add_f32_e32 v60, v219, v60
	s_mov_b64 s[12:13], 0x4eeb000
	v_lshl_add_u64 v[68:69], v[20:21], 0, s[12:13]
	s_waitcnt vmcnt(31)
	v_mul_f32_e32 v216, v6, v61
	v_mul_f32_e32 v217, v7, v61
	v_mul_f32_e32 v218, v10, v61
	v_mul_f32_e32 v219, v11, v61
	v_fma_f32 v200, v12, v200, v216
	v_fma_f32 v201, v12, v201, v217
	v_fma_f32 v202, v12, v202, v218
	v_fma_f32 v203, v12, v203, v219
	global_store_dwordx4 v[68:69], v[200:203], off
	v_mul_f32_e32 v216, v8, v200
	v_mul_f32_e32 v217, v9, v201
	v_mul_f32_e32 v218, v14, v202
	v_mul_f32_e32 v219, v15, v203
	v_add_f32_e32 v61, 0, v216
	v_add_f32_e32 v61, v217, v61
	v_add_f32_e32 v61, v218, v61
	v_add_f32_e32 v61, v219, v61
	s_waitcnt vmcnt(31)
	v_mul_f32_e32 v216, v6, v62
	v_mul_f32_e32 v217, v7, v62
	v_mul_f32_e32 v218, v10, v62
	v_mul_f32_e32 v219, v11, v62
	v_fma_f32 v204, v12, v204, v216
	v_fma_f32 v205, v12, v205, v217
	v_fma_f32 v206, v12, v206, v218
	v_fma_f32 v207, v12, v207, v219
	global_store_dwordx4 v[68:69], v[204:207], off offset:1024
	v_mul_f32_e32 v216, v8, v204
	v_mul_f32_e32 v217, v9, v205
	v_mul_f32_e32 v218, v14, v206
	v_mul_f32_e32 v219, v15, v207
	v_add_f32_e32 v62, 0, v216
	v_add_f32_e32 v62, v217, v62
	v_add_f32_e32 v62, v218, v62
	v_add_f32_e32 v62, v219, v62
	s_waitcnt vmcnt(31)
	v_mul_f32_e32 v216, v6, v63
	v_mul_f32_e32 v217, v7, v63
	v_mul_f32_e32 v218, v10, v63
	v_mul_f32_e32 v219, v11, v63
	v_fma_f32 v208, v12, v208, v216
	v_fma_f32 v209, v12, v209, v217
	v_fma_f32 v210, v12, v210, v218
	v_fma_f32 v211, v12, v211, v219
	global_store_dwordx4 v[68:69], v[208:211], off offset:2048
	v_mul_f32_e32 v216, v8, v208
	v_mul_f32_e32 v217, v9, v209
	v_mul_f32_e32 v218, v14, v210
	v_mul_f32_e32 v219, v15, v211
	v_add_f32_e32 v63, 0, v216
	v_add_f32_e32 v63, v217, v63
	v_add_f32_e32 v63, v218, v63
	v_add_f32_e32 v63, v219, v63
	s_waitcnt vmcnt(31)
; __device__ __forceinline__ float shfl_xor_f(float v, int mask) { const int l = lane_fresh(); return __int_as_float(__builtin_amdgcn_ds_bpermute((l ^ mask) << 2, __float_as_int(v))); }
; __device__ __forceinline__ void ssd_sample_item(const Params& p, int item, const int wv) {
;     ...
;     for (int e = 0; e < 4; ++e) { hn[e] = dA * hv[e] + xp * Bv[e]; yp += hn[e] * Cv[e]; }
;     *(f32x4*)(so + (size_t)pp * 128 + n4) = hn;
; #pragma unroll
;     for (int o = 16; o >= 1; o >>= 1) yp += shfl_xor_f(yp, o);
	v_mul_f32_e32 v216, v6, v64
	v_mul_f32_e32 v217, v7, v64
	v_mul_f32_e32 v218, v10, v64
	v_mul_f32_e32 v219, v11, v64
	v_fma_f32 v212, v12, v212, v216
	v_fma_f32 v213, v12, v213, v217
	v_fma_f32 v214, v12, v214, v218
	v_fma_f32 v215, v12, v215, v219
	global_store_dwordx4 v[68:69], v[212:215], off offset:3072
	v_mul_f32_e32 v216, v8, v212
	v_mul_f32_e32 v217, v9, v213
	v_mul_f32_e32 v218, v14, v214
	v_mul_f32_e32 v219, v15, v215
	v_add_f32_e32 v64, 0, v216
	v_add_f32_e32 v64, v217, v64
	v_add_f32_e32 v64, v218, v64
	v_add_f32_e32 v64, v219, v64
	ds_bpermute_b32 v66, v22, v33
	ds_bpermute_b32 v67, v22, v34
	ds_bpermute_b32 v68, v22, v35
	ds_bpermute_b32 v69, v22, v36
	ds_bpermute_b32 v70, v22, v37
	ds_bpermute_b32 v71, v22, v38
	ds_bpermute_b32 v72, v22, v39
	ds_bpermute_b32 v73, v22, v40
	ds_bpermute_b32 v74, v22, v41
	ds_bpermute_b32 v75, v22, v42
	ds_bpermute_b32 v76, v22, v43
	ds_bpermute_b32 v77, v22, v44
	ds_bpermute_b32 v78, v22, v45
	ds_bpermute_b32 v0, v22, v46
	ds_bpermute_b32 v1, v22, v47
	ds_bpermute_b32 v2, v22, v48
	s_waitcnt lgkmcnt(15)
	v_add_f32_e32 v33, v33, v66
	s_waitcnt lgkmcnt(14)
	v_add_f32_e32 v34, v34, v67
	s_waitcnt lgkmcnt(13)
	v_add_f32_e32 v35, v35, v68
	s_waitcnt lgkmcnt(12)
	v_add_f32_e32 v36, v36, v69
	s_waitcnt lgkmcnt(11)
	v_add_f32_e32 v37, v37, v70
	s_waitcnt lgkmcnt(10)
	v_add_f32_e32 v38, v38, v71
	s_waitcnt lgkmcnt(9)
	v_add_f32_e32 v39, v39, v72
	s_waitcnt lgkmcnt(8)
	v_add_f32_e32 v40, v40, v73
	s_waitcnt lgkmcnt(7)
	v_add_f32_e32 v41, v41, v74
	s_waitcnt lgkmcnt(6)
	v_add_f32_e32 v42, v42, v75
	s_waitcnt lgkmcnt(5)
	v_add_f32_e32 v43, v43, v76
	s_waitcnt lgkmcnt(4)
	v_add_f32_e32 v44, v44, v77
	s_waitcnt lgkmcnt(3)
	v_add_f32_e32 v45, v45, v78
	s_waitcnt lgkmcnt(2)
	v_add_f32_e32 v46, v46, v0
	s_waitcnt lgkmcnt(1)
	v_add_f32_e32 v47, v47, v1
	s_waitcnt lgkmcnt(0)
	v_add_f32_e32 v48, v48, v2
	ds_bpermute_b32 v66, v23, v33
	ds_bpermute_b32 v67, v23, v34
	ds_bpermute_b32 v68, v23, v35
	ds_bpermute_b32 v69, v23, v36
	ds_bpermute_b32 v70, v23, v37
	ds_bpermute_b32 v71, v23, v38
	ds_bpermute_b32 v72, v23, v39
	ds_bpermute_b32 v73, v23, v40
	ds_bpermute_b32 v74, v23, v41
	ds_bpermute_b32 v75, v23, v42
	ds_bpermute_b32 v76, v23, v43
	ds_bpermute_b32 v77, v23, v44
	ds_bpermute_b32 v78, v23, v45
	ds_bpermute_b32 v0, v23, v46
	ds_bpermute_b32 v1, v23, v47
	ds_bpermute_b32 v2, v23, v48
	s_waitcnt lgkmcnt(15)
	v_add_f32_e32 v33, v33, v66
	s_waitcnt lgkmcnt(14)
	v_add_f32_e32 v34, v34, v67
	s_waitcnt lgkmcnt(13)
	v_add_f32_e32 v35, v35, v68
	s_waitcnt lgkmcnt(12)
	v_add_f32_e32 v36, v36, v69
	s_waitcnt lgkmcnt(11)
	v_add_f32_e32 v37, v37, v70
	s_waitcnt lgkmcnt(10)
	v_add_f32_e32 v38, v38, v71
	s_waitcnt lgkmcnt(9)
	v_add_f32_e32 v39, v39, v72
	s_waitcnt lgkmcnt(8)
	v_add_f32_e32 v40, v40, v73
	s_waitcnt lgkmcnt(7)
	v_add_f32_e32 v41, v41, v74
	s_waitcnt lgkmcnt(6)
	v_add_f32_e32 v42, v42, v75
	s_waitcnt lgkmcnt(5)
	v_add_f32_e32 v43, v43, v76
	s_waitcnt lgkmcnt(4)
	v_add_f32_e32 v44, v44, v77
	s_waitcnt lgkmcnt(3)
	v_add_f32_e32 v45, v45, v78
	s_waitcnt lgkmcnt(2)
	v_add_f32_e32 v46, v46, v0
	s_waitcnt lgkmcnt(1)
	v_add_f32_e32 v47, v47, v1
	s_waitcnt lgkmcnt(0)
	v_add_f32_e32 v48, v48, v2
	ds_bpermute_b32 v66, v24, v33
	ds_bpermute_b32 v67, v24, v34
	ds_bpermute_b32 v68, v24, v35
	ds_bpermute_b32 v69, v24, v36
	ds_bpermute_b32 v70, v24, v37
	ds_bpermute_b32 v71, v24, v38
	ds_bpermute_b32 v72, v24, v39
	ds_bpermute_b32 v73, v24, v40
	ds_bpermute_b32 v74, v24, v41
	ds_bpermute_b32 v75, v24, v42
	ds_bpermute_b32 v76, v24, v43
	ds_bpermute_b32 v77, v24, v44
	ds_bpermute_b32 v78, v24, v45
	ds_bpermute_b32 v0, v24, v46
	ds_bpermute_b32 v1, v24, v47
	ds_bpermute_b32 v2, v24, v48
	s_waitcnt lgkmcnt(15)
	v_add_f32_e32 v33, v33, v66
	s_waitcnt lgkmcnt(14)
	v_add_f32_e32 v34, v34, v67
	s_waitcnt lgkmcnt(13)
	v_add_f32_e32 v35, v35, v68
	s_waitcnt lgkmcnt(12)
	v_add_f32_e32 v36, v36, v69
	s_waitcnt lgkmcnt(11)
	v_add_f32_e32 v37, v37, v70
	s_waitcnt lgkmcnt(10)
	v_add_f32_e32 v38, v38, v71
	s_waitcnt lgkmcnt(9)
	v_add_f32_e32 v39, v39, v72
	s_waitcnt lgkmcnt(8)
	v_add_f32_e32 v40, v40, v73
	s_waitcnt lgkmcnt(7)
	v_add_f32_e32 v41, v41, v74
	s_waitcnt lgkmcnt(6)
	v_add_f32_e32 v42, v42, v75
	s_waitcnt lgkmcnt(5)
	v_add_f32_e32 v43, v43, v76
	s_waitcnt lgkmcnt(4)
	v_add_f32_e32 v44, v44, v77
	s_waitcnt lgkmcnt(3)
	v_add_f32_e32 v45, v45, v78
	s_waitcnt lgkmcnt(2)
	v_add_f32_e32 v46, v46, v0
	s_waitcnt lgkmcnt(1)
	v_add_f32_e32 v47, v47, v1
	s_waitcnt lgkmcnt(0)
	v_add_f32_e32 v48, v48, v2
	ds_bpermute_b32 v66, v25, v33
	ds_bpermute_b32 v67, v25, v34
	ds_bpermute_b32 v68, v25, v35
	ds_bpermute_b32 v69, v25, v36
	ds_bpermute_b32 v70, v25, v37
	ds_bpermute_b32 v71, v25, v38
	ds_bpermute_b32 v72, v25, v39
	ds_bpermute_b32 v73, v25, v40
	ds_bpermute_b32 v74, v25, v41
	ds_bpermute_b32 v75, v25, v42
	ds_bpermute_b32 v76, v25, v43
	ds_bpermute_b32 v77, v25, v44
	ds_bpermute_b32 v78, v25, v45
	ds_bpermute_b32 v0, v25, v46
	ds_bpermute_b32 v1, v25, v47
	ds_bpermute_b32 v2, v25, v48
	s_waitcnt lgkmcnt(15)
	v_add_f32_e32 v33, v33, v66
	s_waitcnt lgkmcnt(14)
	v_add_f32_e32 v34, v34, v67
	s_waitcnt lgkmcnt(13)
	v_add_f32_e32 v35, v35, v68
	s_waitcnt lgkmcnt(12)
	v_add_f32_e32 v36, v36, v69
	s_waitcnt lgkmcnt(11)
	v_add_f32_e32 v37, v37, v70
	s_waitcnt lgkmcnt(10)
	v_add_f32_e32 v38, v38, v71
	s_waitcnt lgkmcnt(9)
	v_add_f32_e32 v39, v39, v72
	s_waitcnt lgkmcnt(8)
	v_add_f32_e32 v40, v40, v73
	s_waitcnt lgkmcnt(7)
	v_add_f32_e32 v41, v41, v74
	s_waitcnt lgkmcnt(6)
	v_add_f32_e32 v42, v42, v75
	s_waitcnt lgkmcnt(5)
	v_add_f32_e32 v43, v43, v76
	s_waitcnt lgkmcnt(4)
	v_add_f32_e32 v44, v44, v77
	s_waitcnt lgkmcnt(3)
; __device__ __forceinline__ float shfl_xor_f(float v, int mask) { const int l = lane_fresh(); return __int_as_float(__builtin_amdgcn_ds_bpermute((l ^ mask) << 2, __float_as_int(v))); }
; __device__ __forceinline__ void ssd_sample_item(const Params& p, int item, const int wv) {
;     ...
;     for (int o = 16; o >= 1; o >>= 1) yp += shfl_xor_f(yp, o);
	v_add_f32_e32 v45, v45, v78
	s_waitcnt lgkmcnt(2)
	v_add_f32_e32 v46, v46, v0
	s_waitcnt lgkmcnt(1)
	v_add_f32_e32 v47, v47, v1
	s_waitcnt lgkmcnt(0)
	v_add_f32_e32 v48, v48, v2
	ds_bpermute_b32 v66, v26, v33
	ds_bpermute_b32 v67, v26, v34
	ds_bpermute_b32 v68, v26, v35
	ds_bpermute_b32 v69, v26, v36
	ds_bpermute_b32 v70, v26, v37
	ds_bpermute_b32 v71, v26, v38
	ds_bpermute_b32 v72, v26, v39
	ds_bpermute_b32 v73, v26, v40
	ds_bpermute_b32 v74, v26, v41
	ds_bpermute_b32 v75, v26, v42
	ds_bpermute_b32 v76, v26, v43
	ds_bpermute_b32 v77, v26, v44
	ds_bpermute_b32 v78, v26, v45
	ds_bpermute_b32 v0, v26, v46
	ds_bpermute_b32 v1, v26, v47
	ds_bpermute_b32 v2, v26, v48
	s_waitcnt lgkmcnt(15)
	v_add_f32_e32 v33, v33, v66
	s_waitcnt lgkmcnt(14)
	v_add_f32_e32 v34, v34, v67
	s_waitcnt lgkmcnt(13)
	v_add_f32_e32 v35, v35, v68
	s_waitcnt lgkmcnt(12)
	v_add_f32_e32 v36, v36, v69
	s_waitcnt lgkmcnt(11)
	v_add_f32_e32 v37, v37, v70
	s_waitcnt lgkmcnt(10)
	v_add_f32_e32 v38, v38, v71
	s_waitcnt lgkmcnt(9)
	v_add_f32_e32 v39, v39, v72
	s_waitcnt lgkmcnt(8)
	v_add_f32_e32 v40, v40, v73
	s_waitcnt lgkmcnt(7)
	v_add_f32_e32 v41, v41, v74
	s_waitcnt lgkmcnt(6)
	v_add_f32_e32 v42, v42, v75
	s_waitcnt lgkmcnt(5)
	v_add_f32_e32 v43, v43, v76
	s_waitcnt lgkmcnt(4)
	v_add_f32_e32 v44, v44, v77
	s_waitcnt lgkmcnt(3)
	v_add_f32_e32 v45, v45, v78
	s_waitcnt lgkmcnt(2)
	v_add_f32_e32 v46, v46, v0
	s_waitcnt lgkmcnt(1)
	v_add_f32_e32 v47, v47, v1
	s_waitcnt lgkmcnt(0)
	v_add_f32_e32 v48, v48, v2
	ds_bpermute_b32 v66, v22, v49
	ds_bpermute_b32 v67, v22, v50
	ds_bpermute_b32 v68, v22, v51
	ds_bpermute_b32 v69, v22, v52
	ds_bpermute_b32 v70, v22, v53
	ds_bpermute_b32 v71, v22, v54
	ds_bpermute_b32 v72, v22, v55
	ds_bpermute_b32 v73, v22, v56
	ds_bpermute_b32 v74, v22, v57
	ds_bpermute_b32 v75, v22, v58
	ds_bpermute_b32 v76, v22, v59
	ds_bpermute_b32 v77, v22, v60
	ds_bpermute_b32 v78, v22, v61
	ds_bpermute_b32 v0, v22, v62
	ds_bpermute_b32 v1, v22, v63
	ds_bpermute_b32 v2, v22, v64
	s_waitcnt lgkmcnt(15)
	v_add_f32_e32 v49, v49, v66
	s_waitcnt lgkmcnt(14)
	v_add_f32_e32 v50, v50, v67
	s_waitcnt lgkmcnt(13)
	v_add_f32_e32 v51, v51, v68
	s_waitcnt lgkmcnt(12)
	v_add_f32_e32 v52, v52, v69
	s_waitcnt lgkmcnt(11)
	v_add_f32_e32 v53, v53, v70
	s_waitcnt lgkmcnt(10)
	v_add_f32_e32 v54, v54, v71
	s_waitcnt lgkmcnt(9)
	v_add_f32_e32 v55, v55, v72
	s_waitcnt lgkmcnt(8)
	v_add_f32_e32 v56, v56, v73
	s_waitcnt lgkmcnt(7)
	v_add_f32_e32 v57, v57, v74
	s_waitcnt lgkmcnt(6)
	v_add_f32_e32 v58, v58, v75
	s_waitcnt lgkmcnt(5)
	v_add_f32_e32 v59, v59, v76
	s_waitcnt lgkmcnt(4)
	v_add_f32_e32 v60, v60, v77
	s_waitcnt lgkmcnt(3)
	v_add_f32_e32 v61, v61, v78
	s_waitcnt lgkmcnt(2)
	v_add_f32_e32 v62, v62, v0
	s_waitcnt lgkmcnt(1)
	v_add_f32_e32 v63, v63, v1
	s_waitcnt lgkmcnt(0)
	v_add_f32_e32 v64, v64, v2
	ds_bpermute_b32 v66, v23, v49
	ds_bpermute_b32 v67, v23, v50
	ds_bpermute_b32 v68, v23, v51
	ds_bpermute_b32 v69, v23, v52
	ds_bpermute_b32 v70, v23, v53
	ds_bpermute_b32 v71, v23, v54
	ds_bpermute_b32 v72, v23, v55
	ds_bpermute_b32 v73, v23, v56
	ds_bpermute_b32 v74, v23, v57
	ds_bpermute_b32 v75, v23, v58
	ds_bpermute_b32 v76, v23, v59
	ds_bpermute_b32 v77, v23, v60
	ds_bpermute_b32 v78, v23, v61
	ds_bpermute_b32 v0, v23, v62
	ds_bpermute_b32 v1, v23, v63
	ds_bpermute_b32 v2, v23, v64
	s_waitcnt lgkmcnt(15)
	v_add_f32_e32 v49, v49, v66
	s_waitcnt lgkmcnt(14)
	v_add_f32_e32 v50, v50, v67
	s_waitcnt lgkmcnt(13)
	v_add_f32_e32 v51, v51, v68
	s_waitcnt lgkmcnt(12)
	v_add_f32_e32 v52, v52, v69
	s_waitcnt lgkmcnt(11)
	v_add_f32_e32 v53, v53, v70
	s_waitcnt lgkmcnt(10)
	v_add_f32_e32 v54, v54, v71
	s_waitcnt lgkmcnt(9)
	v_add_f32_e32 v55, v55, v72
	s_waitcnt lgkmcnt(8)
	v_add_f32_e32 v56, v56, v73
	s_waitcnt lgkmcnt(7)
	v_add_f32_e32 v57, v57, v74
	s_waitcnt lgkmcnt(6)
	v_add_f32_e32 v58, v58, v75
	s_waitcnt lgkmcnt(5)
	v_add_f32_e32 v59, v59, v76
	s_waitcnt lgkmcnt(4)
	v_add_f32_e32 v60, v60, v77
	s_waitcnt lgkmcnt(3)
	v_add_f32_e32 v61, v61, v78
	s_waitcnt lgkmcnt(2)
	v_add_f32_e32 v62, v62, v0
	s_waitcnt lgkmcnt(1)
	v_add_f32_e32 v63, v63, v1
	s_waitcnt lgkmcnt(0)
	v_add_f32_e32 v64, v64, v2
	ds_bpermute_b32 v66, v24, v49
	ds_bpermute_b32 v67, v24, v50
	ds_bpermute_b32 v68, v24, v51
	ds_bpermute_b32 v69, v24, v52
	ds_bpermute_b32 v70, v24, v53
	ds_bpermute_b32 v71, v24, v54
	ds_bpermute_b32 v72, v24, v55
	ds_bpermute_b32 v73, v24, v56
	ds_bpermute_b32 v74, v24, v57
	ds_bpermute_b32 v75, v24, v58
	ds_bpermute_b32 v76, v24, v59
	ds_bpermute_b32 v77, v24, v60
	ds_bpermute_b32 v78, v24, v61
	ds_bpermute_b32 v0, v24, v62
	ds_bpermute_b32 v1, v24, v63
	ds_bpermute_b32 v2, v24, v64
	s_waitcnt lgkmcnt(15)
	v_add_f32_e32 v49, v49, v66
	s_waitcnt lgkmcnt(14)
	v_add_f32_e32 v50, v50, v67
	s_waitcnt lgkmcnt(13)
	v_add_f32_e32 v51, v51, v68
	s_waitcnt lgkmcnt(12)
	v_add_f32_e32 v52, v52, v69
	s_waitcnt lgkmcnt(11)
	v_add_f32_e32 v53, v53, v70
	s_waitcnt lgkmcnt(10)
	v_add_f32_e32 v54, v54, v71
	s_waitcnt lgkmcnt(9)
	v_add_f32_e32 v55, v55, v72
	s_waitcnt lgkmcnt(8)
	v_add_f32_e32 v56, v56, v73
	s_waitcnt lgkmcnt(7)
	v_add_f32_e32 v57, v57, v74
	s_waitcnt lgkmcnt(6)
	v_add_f32_e32 v58, v58, v75
	s_waitcnt lgkmcnt(5)
	v_add_f32_e32 v59, v59, v76
	s_waitcnt lgkmcnt(4)
	v_add_f32_e32 v60, v60, v77
	s_waitcnt lgkmcnt(3)
	v_add_f32_e32 v61, v61, v78
	s_waitcnt lgkmcnt(2)
	v_add_f32_e32 v62, v62, v0
	s_waitcnt lgkmcnt(1)
	v_add_f32_e32 v63, v63, v1
	s_waitcnt lgkmcnt(0)
; __device__ __forceinline__ float shfl_xor_f(float v, int mask) { const int l = lane_fresh(); return __int_as_float(__builtin_amdgcn_ds_bpermute((l ^ mask) << 2, __float_as_int(v))); }
; __device__ __forceinline__ void ssd_sample_item(const Params& p, int item, const int wv) {
;     ...
;     for (int o = 16; o >= 1; o >>= 1) yp += shfl_xor_f(yp, o);
	v_add_f32_e32 v64, v64, v2
	ds_bpermute_b32 v66, v25, v49
	ds_bpermute_b32 v67, v25, v50
	ds_bpermute_b32 v68, v25, v51
	ds_bpermute_b32 v69, v25, v52
	ds_bpermute_b32 v70, v25, v53
	ds_bpermute_b32 v71, v25, v54
	ds_bpermute_b32 v72, v25, v55
	ds_bpermute_b32 v73, v25, v56
	ds_bpermute_b32 v74, v25, v57
	ds_bpermute_b32 v75, v25, v58
	ds_bpermute_b32 v76, v25, v59
	ds_bpermute_b32 v77, v25, v60
	ds_bpermute_b32 v78, v25, v61
	ds_bpermute_b32 v0, v25, v62
	ds_bpermute_b32 v1, v25, v63
	ds_bpermute_b32 v2, v25, v64
	s_waitcnt lgkmcnt(15)
	v_add_f32_e32 v49, v49, v66
	s_waitcnt lgkmcnt(14)
	v_add_f32_e32 v50, v50, v67
	s_waitcnt lgkmcnt(13)
	v_add_f32_e32 v51, v51, v68
	s_waitcnt lgkmcnt(12)
	v_add_f32_e32 v52, v52, v69
	s_waitcnt lgkmcnt(11)
	v_add_f32_e32 v53, v53, v70
	s_waitcnt lgkmcnt(10)
	v_add_f32_e32 v54, v54, v71
	s_waitcnt lgkmcnt(9)
	v_add_f32_e32 v55, v55, v72
	s_waitcnt lgkmcnt(8)
	v_add_f32_e32 v56, v56, v73
	s_waitcnt lgkmcnt(7)
	v_add_f32_e32 v57, v57, v74
	s_waitcnt lgkmcnt(6)
	v_add_f32_e32 v58, v58, v75
	s_waitcnt lgkmcnt(5)
	v_add_f32_e32 v59, v59, v76
	s_waitcnt lgkmcnt(4)
	v_add_f32_e32 v60, v60, v77
	s_waitcnt lgkmcnt(3)
	v_add_f32_e32 v61, v61, v78
	s_waitcnt lgkmcnt(2)
	v_add_f32_e32 v62, v62, v0
	s_waitcnt lgkmcnt(1)
	v_add_f32_e32 v63, v63, v1
	s_waitcnt lgkmcnt(0)
	v_add_f32_e32 v64, v64, v2
	ds_bpermute_b32 v66, v26, v49
	ds_bpermute_b32 v67, v26, v50
	ds_bpermute_b32 v68, v26, v51
	ds_bpermute_b32 v69, v26, v52
	ds_bpermute_b32 v70, v26, v53
	ds_bpermute_b32 v71, v26, v54
	ds_bpermute_b32 v72, v26, v55
	ds_bpermute_b32 v73, v26, v56
	ds_bpermute_b32 v74, v26, v57
	ds_bpermute_b32 v75, v26, v58
	ds_bpermute_b32 v76, v26, v59
	ds_bpermute_b32 v77, v26, v60
	ds_bpermute_b32 v78, v26, v61
	ds_bpermute_b32 v0, v26, v62
	ds_bpermute_b32 v1, v26, v63
	ds_bpermute_b32 v2, v26, v64
	s_waitcnt lgkmcnt(15)
	v_add_f32_e32 v49, v49, v66
	s_waitcnt lgkmcnt(14)
	v_add_f32_e32 v50, v50, v67
	s_waitcnt lgkmcnt(13)
	v_add_f32_e32 v51, v51, v68
	s_waitcnt lgkmcnt(12)
	v_add_f32_e32 v52, v52, v69
	s_waitcnt lgkmcnt(11)
	v_add_f32_e32 v53, v53, v70
	s_waitcnt lgkmcnt(10)
	v_add_f32_e32 v54, v54, v71
	s_waitcnt lgkmcnt(9)
	v_add_f32_e32 v55, v55, v72
	s_waitcnt lgkmcnt(8)
	v_add_f32_e32 v56, v56, v73
	s_waitcnt lgkmcnt(7)
	v_add_f32_e32 v57, v57, v74
	s_waitcnt lgkmcnt(6)
	v_add_f32_e32 v58, v58, v75
	s_waitcnt lgkmcnt(5)
	v_add_f32_e32 v59, v59, v76
	s_waitcnt lgkmcnt(4)
	v_add_f32_e32 v60, v60, v77
	s_waitcnt lgkmcnt(3)
	v_add_f32_e32 v61, v61, v78
	s_waitcnt lgkmcnt(2)
	v_add_f32_e32 v62, v62, v0
	s_waitcnt lgkmcnt(1)
	v_add_f32_e32 v63, v63, v1
	s_waitcnt lgkmcnt(0)
; __device__ __forceinline__ u16 f2bf(float f) { return (u16)(cvt_pk(f, 0.f) & 0xffffu); }
; __device__ __forceinline__ float bf2f(u16 h) { return __uint_as_float(((unsigned)h) << 16); }
; __device__ __forceinline__ float shfl_xor_f(float v, int mask) { const int l = lane_fresh(); return __int_as_float(__builtin_amdgcn_ds_bpermute((l ^ mask) << 2, __float_as_int(v))); }
; __device__ __forceinline__ float shfl_idx_f(float v, int src) { return __int_as_float(__builtin_amdgcn_ds_bpermute(src << 2, __float_as_int(v))); }
; __device__ __forceinline__ float wave_sum(float v) {
; #pragma unroll
;   for (int o = 32; o >= 1; o >>= 1) v += shfl_xor_f(v, o);
;   return v;
; }
; __device__ __forceinline__ void ssd_sample_item(const Params& p, int item, const int wv) {
;     ...
;     if ((lane & 31) == r) ymine = yp;
;   }
;   const int pm = 2 * (lane & 31) + hf;
;   const float xm = shfl_idx_f(x, pm);
;   const float zs = bf2f(ZS[(size_t)tok * 1024 + h * 64 + pm]);
;   const float yg = (ymine + xm * p.in[17][h]) * zs;
;   float ss = wave_sum(yg * yg);
;   Y[(size_t)tok * 1024 + h * 64 + pm] = f2bf(yg);
;   if (lane == 0) { YPS[(size_t)tok * 32 + g * 16 + (h & 7) * 2] = ss; YPS[(size_t)tok * 32 + g * 16 + (h & 7) * 2 + 1] = 0.f; }
	v_add_f32_e32 v64, v64, v2
	v_cmp_eq_u32_e64 s[36:37], 0, v29
	v_cmp_eq_u32_e64 s[38:39], 1, v29
	v_cmp_eq_u32_e64 s[40:41], 2, v29
	v_cndmask_b32_e64 v17, v17, v33, s[36:37]
	v_cmp_eq_u32_e64 s[36:37], 3, v29
	v_cndmask_b32_e64 v17, v17, v34, s[38:39]
	v_cmp_eq_u32_e64 s[38:39], 4, v29
	v_cndmask_b32_e64 v17, v17, v35, s[40:41]
	v_cmp_eq_u32_e64 s[40:41], 5, v29
	v_cndmask_b32_e64 v17, v17, v36, s[36:37]
	v_cmp_eq_u32_e64 s[36:37], 6, v29
	v_cndmask_b32_e64 v17, v17, v37, s[38:39]
	v_cmp_eq_u32_e64 s[38:39], 7, v29
	v_cndmask_b32_e64 v17, v17, v38, s[40:41]
	v_cmp_eq_u32_e64 s[40:41], 8, v29
	v_cndmask_b32_e64 v17, v17, v39, s[36:37]
	v_cmp_eq_u32_e64 s[36:37], 9, v29
	v_cndmask_b32_e64 v17, v17, v40, s[38:39]
	v_cmp_eq_u32_e64 s[38:39], 10, v29
	v_cndmask_b32_e64 v17, v17, v41, s[40:41]
	v_cmp_eq_u32_e64 s[40:41], 11, v29
	v_cndmask_b32_e64 v17, v17, v42, s[36:37]
	v_cmp_eq_u32_e64 s[36:37], 12, v29
	v_cndmask_b32_e64 v17, v17, v43, s[38:39]
	v_cmp_eq_u32_e64 s[38:39], 13, v29
	v_cndmask_b32_e64 v17, v17, v44, s[40:41]
	v_cmp_eq_u32_e64 s[40:41], 14, v29
	v_cndmask_b32_e64 v17, v17, v45, s[36:37]
	v_cmp_eq_u32_e64 s[36:37], 15, v29
	v_cndmask_b32_e64 v17, v17, v46, s[38:39]
	v_cmp_eq_u32_e64 s[38:39], 16, v29
	v_cndmask_b32_e64 v17, v17, v47, s[40:41]
	v_cmp_eq_u32_e64 s[40:41], 17, v29
	v_cndmask_b32_e64 v17, v17, v48, s[36:37]
	v_cmp_eq_u32_e64 s[36:37], 18, v29
	v_cndmask_b32_e64 v17, v17, v49, s[38:39]
	v_cmp_eq_u32_e64 s[38:39], 19, v29
	v_cndmask_b32_e64 v17, v17, v50, s[40:41]
	v_cmp_eq_u32_e64 s[40:41], 20, v29
	v_cndmask_b32_e64 v17, v17, v51, s[36:37]
	v_cmp_eq_u32_e64 s[36:37], 21, v29
	v_cndmask_b32_e64 v17, v17, v52, s[38:39]
	v_cmp_eq_u32_e64 s[38:39], 22, v29
	v_cndmask_b32_e64 v17, v17, v53, s[40:41]
	v_cmp_eq_u32_e64 s[40:41], 23, v29
	v_cndmask_b32_e64 v17, v17, v54, s[36:37]
	v_cmp_eq_u32_e64 s[36:37], 24, v29
	v_cndmask_b32_e64 v17, v17, v55, s[38:39]
	v_cmp_eq_u32_e64 s[38:39], 25, v29
	v_cndmask_b32_e64 v17, v17, v56, s[40:41]
	v_cmp_eq_u32_e64 s[40:41], 26, v29
	v_cndmask_b32_e64 v17, v17, v57, s[36:37]
	v_cmp_eq_u32_e64 s[36:37], 27, v29
	v_cndmask_b32_e64 v17, v17, v58, s[38:39]
	v_cmp_eq_u32_e64 s[38:39], 28, v29
	v_cndmask_b32_e64 v17, v17, v59, s[40:41]
	v_cmp_eq_u32_e64 s[40:41], 29, v29
	v_cndmask_b32_e64 v17, v17, v60, s[36:37]
	v_cmp_eq_u32_e64 s[36:37], 30, v29
	v_cndmask_b32_e64 v17, v17, v61, s[38:39]
	v_cmp_eq_u32_e64 s[38:39], 31, v29
	v_cndmask_b32_e64 v17, v17, v62, s[40:41]
	s_nop 1
	v_cndmask_b32_e64 v17, v17, v63, s[36:37]
	v_cndmask_b32_e64 v17, v17, v64, s[38:39]
	v_add_u32_e32 v32, 0x100, v32
	s_mov_b32 s10, 32
	s_mov_b64 s[12:13], 0x8000
	s_lshl_b32 s10, s31, 11
	s_add_u32 s0, s17, s10
	v_lshl_add_u32 v0, v29, 1, v16
	s_addc_u32 s1, s18, 0
	s_lshl_b32 s12, s34, 1
	v_ashrrev_i32_e32 v1, 31, v0
	s_add_u32 s0, s0, s12
	s_addc_u32 s1, s1, 0
	v_lshlrev_b64 v[2:3], 1, v[0:1]
	v_lshl_add_u64 v[6:7], s[0:1], 0, v[2:3]
	s_lshl_b32 s0, s33, 2
	v_readlane_b32 s60, v251, 22
	v_mov_b32_e32 v4, s0
	v_readlane_b32 s62, v251, 24
	v_readlane_b32 s63, v251, 25
	global_load_ushort v1, v[6:7], off
	v_lshlrev_b32_e32 v0, 2, v0
	ds_bpermute_b32 v0, v0, v31
	s_add_u32 s0, s48, s10
	s_addc_u32 s1, s49, 0
	global_load_dword v4, v4, s[62:63]
	v_mbcnt_lo_u32_b32 v6, -1, 0
	v_mbcnt_hi_u32_b32 v6, -1, v6
	v_cmp_eq_u32_e32 vcc, 0, v28
	v_lshlrev_b32_e32 v6, 2, v6
	v_xor_b32_e32 v6, 0x80, v6
	v_readlane_b32 s61, v251, 23
	v_readlane_b32 s64, v251, 26
	v_readlane_b32 s65, v251, 27
	v_readlane_b32 s66, v251, 28
	v_readlane_b32 s67, v251, 29
	v_readlane_b32 s68, v251, 30
	v_readlane_b32 s69, v251, 31
	v_readlane_b32 s70, v251, 32
	v_readlane_b32 s71, v251, 33
	v_readlane_b32 s72, v251, 34
	v_readlane_b32 s73, v251, 35
	v_readlane_b32 s74, v251, 36
	v_readlane_b32 s75, v251, 37
	s_waitcnt vmcnt(1)
	v_lshlrev_b32_e32 v1, 16, v1
	s_waitcnt vmcnt(0) lgkmcnt(0)
	v_fmac_f32_e32 v17, v4, v0
	v_mul_f32_e32 v0, v17, v1
	v_mul_f32_e32 v1, v0, v0
	ds_bpermute_b32 v1, v6, v1
	v_mbcnt_lo_u32_b32 v4, -1, 0
	v_mbcnt_hi_u32_b32 v4, -1, v4
	v_mbcnt_lo_u32_b32 v6, -1, 0
	v_mbcnt_hi_u32_b32 v6, -1, v6
	s_waitcnt lgkmcnt(0)
	v_fmac_f32_e32 v1, v0, v0
	v_lshlrev_b32_e32 v4, 2, v4
	v_xor_b32_e32 v4, 64, v4
	ds_bpermute_b32 v4, v4, v1
	v_lshlrev_b32_e32 v6, 2, v6
	v_xor_b32_e32 v6, 32, v6
	s_waitcnt lgkmcnt(0)
	v_add_f32_e32 v1, v1, v4
	s_nop 1
	v_mov_b32_dpp v4, v1 row_ror:8 row_mask:0xf bank_mask:0xf
	v_mbcnt_lo_u32_b32 v6, -1, 0
	v_mbcnt_hi_u32_b32 v6, -1, v6
	s_waitcnt lgkmcnt(0)
	v_add_f32_e32 v1, v1, v4
	v_lshlrev_b32_e32 v6, 2, v6
	v_xor_b32_e32 v6, 16, v6
	s_nop 1
	v_mov_b32_dpp v4, v1 row_shl:4 row_mask:0xf bank_mask:0x5
	v_mov_b32_dpp v4, v1 row_shr:4 row_mask:0xf bank_mask:0xa
	v_mbcnt_lo_u32_b32 v6, -1, 0
	v_mbcnt_hi_u32_b32 v6, -1, v6
	v_mbcnt_lo_u32_b32 v7, -1, 0
	v_mbcnt_hi_u32_b32 v7, -1, v7
	s_waitcnt lgkmcnt(0)
	v_add_f32_e32 v1, v1, v4
	v_lshlrev_b32_e32 v6, 2, v6
	v_xor_b32_e32 v6, 8, v6
	s_nop 1
	v_mov_b32_dpp v4, v1 quad_perm:[2,3,0,1] row_mask:0xf bank_mask:0xf
	v_lshlrev_b32_e32 v6, 2, v7
	v_xor_b32_e32 v6, 4, v6
	v_cvt_pk_bf16_f32 v7, v0, s0
	s_add_u32 s0, s0, s12
	s_waitcnt lgkmcnt(0)
	v_add_f32_e32 v0, v1, v4
	s_nop 1
	v_mov_b32_dpp v1, v0 quad_perm:[1,0,3,2] row_mask:0xf bank_mask:0xf
	s_addc_u32 s1, s1, 0
	v_lshl_add_u64 v[2:3], s[0:1], 0, v[2:3]
	global_store_short v[2:3], v7, off
	s_and_saveexec_b64 s[0:1], vcc
	s_cbranch_execz .LBB0_455
	s_lshl_b32 s10, s31, 7
	s_add_u32 s10, s19, s10
	s_addc_u32 s13, s20, 0
	s_lshl_b32 s12, s30, 6
	s_add_u32 s12, s10, s12
	s_addc_u32 s13, s13, 0
	s_lshl_b32 s10, s29, 3
	s_and_b32 s10, s10, 56
	s_waitcnt lgkmcnt(0)
	v_add_f32_e32 v4, v0, v1
	v_mov_b32_e32 v0, s10
	global_store_dwordx2 v0, v[4:5], s[12:13]
	s_branch .LBB0_455

; __device__ __forceinline__ float bflo(unsigned w) { return __uint_as_float(w << 16); }
; __device__ __forceinline__ float bfhi(unsigned w) { return __uint_as_float(w & 0xffff0000u); }
; __device__ __forceinline__ void attn_sample_item(const Params& p, int item, const int wv) {
;     ...
;   const float* Kc = p.in[3] + ((size_t)b * 256 * 4 + h) * 128;
;   const float* Vc = p.in[4] + ((size_t)b * 256 * 4 + h) * 128;
;   const int vdch = tid & 31, vmg = tid >> 5;
;   f32x4 vreg[16];
; #pragma unroll
;   for (int i = 0; i < 16; ++i) vreg[i] = *(const f32x4*)(Vc + (size_t)(vmg * 16 + i) * 512 + vdch * 4);
;   __syncthreads();
;   {
;     const int dch = lane & 15, ksub = lane >> 4;
;     u32x4 qw = *(const u32x4*)(Q + (size_t)tok * 512 + h * 128 + dch * 8);
;     float q[8] = {bflo(qw.x), bfhi(qw.x), bflo(qw.y), bfhi(qw.y), bflo(qw.z), bfhi(qw.z), bflo(qw.w), bfhi(qw.w)};
; #pragma unroll
;     for (int it = 0; it < 8; ++it) {
;       const int mm = wid * 32 + it * 4 + ksub;
;       f32x4 k0 = *(const f32x4*)(Kc + (size_t)mm * 512 + dch * 8), k1 = *(const f32x4*)(Kc + (size_t)mm * 512 + dch * 8 + 4);
;       float d = q[0] * k0[0] + q[1] * k0[1] + q[2] * k0[2] + q[3] * k0[3] + q[4] * k1[0] + q[5] * k1[1] + q[6] * k1[2] + q[7] * k1[3];
.LBB0_464:
	s_ashr_i32 s0, s19, 2
	s_ashr_i32 s1, s0, 31
	s_and_b32 s22, s15, 0x180
	v_readlane_b32 s64, v251, 6
	s_lshl_b64 s[10:11], s[0:1], 19
	s_lshl_b32 s1, s22, 2
	v_readlane_b32 s72, v251, 14
	v_readlane_b32 s73, v251, 15
	s_or_b32 s1, s10, s1
	s_mov_b64 s[44:45], s[72:73]
	v_readlane_b32 s70, v251, 12
	v_readlane_b32 s71, v251, 13
	s_add_u32 s20, s44, s1
	v_mbcnt_lo_u32_b32 v72, -1, 0
	v_mbcnt_hi_u32_b32 v72, -1, v72
	s_mov_b64 s[42:43], s[70:71]
	v_add_u32_e32 v66, s82, v72
	s_addc_u32 s21, s45, s11
	s_addk_i32 s0, 0x4000
	v_and_b32_e32 v0, 31, v72
	v_ashrrev_i32_e32 v67, 5, v66
	s_add_u32 s10, s42, s1
	v_lshlrev_b32_e32 v56, 4, v67
	v_lshlrev_b32_e32 v64, 4, v0
	s_addc_u32 s11, s43, s11
	s_ashr_i32 s1, s0, 31
	v_lshl_add_u64 v[58:59], s[20:21], 0, v[64:65]
	v_ashrrev_i32_e32 v57, 31, v56
	s_lshl_b64 s[20:21], s[0:1], 10
	s_waitcnt lgkmcnt(0)
	v_lshlrev_b64 v[0:1], 11, v[56:57]
	v_or_b32_e32 v2, 1, v56
	v_or_b32_e32 v8, 2, v56
	v_or_b32_e32 v10, 3, v56
	v_or_b32_e32 v16, 4, v56
	v_or_b32_e32 v18, 5, v56
	v_or_b32_e32 v24, 6, v56
	v_or_b32_e32 v26, 7, v56
	v_or_b32_e32 v32, 8, v56
	v_or_b32_e32 v34, 9, v56
	v_or_b32_e32 v40, 10, v56
	v_or_b32_e32 v42, 11, v56
	v_or_b32_e32 v48, 12, v56
	v_or_b32_e32 v50, 13, v56
	v_or_b32_e32 v60, 14, v56
	v_or_b32_e32 v56, 15, v56
	s_add_u32 s23, s7, s20
	v_ashrrev_i32_e32 v3, 31, v2
	v_ashrrev_i32_e32 v9, 31, v8
	v_ashrrev_i32_e32 v11, 31, v10
	v_ashrrev_i32_e32 v17, 31, v16
	v_ashrrev_i32_e32 v19, 31, v18
	v_ashrrev_i32_e32 v25, 31, v24
	v_ashrrev_i32_e32 v27, 31, v26
	v_ashrrev_i32_e32 v33, 31, v32
	v_ashrrev_i32_e32 v35, 31, v34
	v_ashrrev_i32_e32 v41, 31, v40
	v_ashrrev_i32_e32 v43, 31, v42
	v_ashrrev_i32_e32 v49, 31, v48
	v_ashrrev_i32_e32 v51, 31, v50
	v_ashrrev_i32_e32 v61, 31, v60
	v_ashrrev_i32_e32 v57, 31, v56
	s_addc_u32 s21, s12, s21
	s_lshl_b32 s20, s22, 1
	v_lshlrev_b64 v[2:3], 11, v[2:3]
	v_lshlrev_b64 v[8:9], 11, v[8:9]
	v_lshlrev_b64 v[10:11], 11, v[10:11]
	v_lshlrev_b64 v[16:17], 11, v[16:17]
	v_lshlrev_b64 v[18:19], 11, v[18:19]
	v_lshlrev_b64 v[24:25], 11, v[24:25]
	v_lshlrev_b64 v[26:27], 11, v[26:27]
	v_lshlrev_b64 v[32:33], 11, v[32:33]
	v_lshlrev_b64 v[34:35], 11, v[34:35]
	v_lshlrev_b64 v[40:41], 11, v[40:41]
	v_lshlrev_b64 v[42:43], 11, v[42:43]
	v_lshlrev_b64 v[48:49], 11, v[48:49]
	v_lshlrev_b64 v[50:51], 11, v[50:51]
	v_lshlrev_b64 v[60:61], 11, v[60:61]
	v_lshlrev_b64 v[56:57], 11, v[56:57]
	v_and_b32_e32 v92, 15, v72
	v_ashrrev_i32_e32 v68, 4, v72
	s_add_u32 s22, s23, s20
	v_lshl_add_u64 v[0:1], v[58:59], 0, v[0:1]
	v_lshl_add_u64 v[2:3], v[58:59], 0, v[2:3]
	v_lshl_add_u64 v[8:9], v[58:59], 0, v[8:9]
	v_lshl_add_u64 v[10:11], v[58:59], 0, v[10:11]
	v_lshl_add_u64 v[16:17], v[58:59], 0, v[16:17]
	v_lshl_add_u64 v[18:19], v[58:59], 0, v[18:19]
	v_lshl_add_u64 v[24:25], v[58:59], 0, v[24:25]
	v_lshl_add_u64 v[26:27], v[58:59], 0, v[26:27]
	v_lshl_add_u64 v[32:33], v[58:59], 0, v[32:33]
	v_lshl_add_u64 v[34:35], v[58:59], 0, v[34:35]
	v_lshl_add_u64 v[40:41], v[58:59], 0, v[40:41]
	v_lshl_add_u64 v[42:43], v[58:59], 0, v[42:43]
	v_lshl_add_u64 v[48:49], v[58:59], 0, v[48:49]
	v_lshl_add_u64 v[50:51], v[58:59], 0, v[50:51]
	v_lshl_add_u64 v[60:61], v[58:59], 0, v[60:61]
	v_lshl_add_u64 v[56:57], v[58:59], 0, v[56:57]
	s_addc_u32 s23, s21, 0
	v_lshlrev_b32_e32 v69, 4, v92
	v_add_u32_e32 v70, s5, v68
	global_load_dwordx4 v[4:7], v[0:1], off
	s_nop 0
	global_load_dwordx4 v[0:3], v[2:3], off
	s_nop 0
	global_load_dwordx4 v[12:15], v[8:9], off
	s_nop 0
	global_load_dwordx4 v[8:11], v[10:11], off
	s_nop 0
	global_load_dwordx4 v[20:23], v[16:17], off
	s_nop 0
	global_load_dwordx4 v[16:19], v[18:19], off
	s_nop 0
	global_load_dwordx4 v[28:31], v[24:25], off
	s_nop 0
	global_load_dwordx4 v[24:27], v[26:27], off
	s_nop 0
	global_load_dwordx4 v[36:39], v[32:33], off
	s_nop 0
	global_load_dwordx4 v[32:35], v[34:35], off
	s_nop 0
	global_load_dwordx4 v[44:47], v[40:41], off
	s_nop 0
	global_load_dwordx4 v[40:43], v[42:43], off
	s_nop 0
	global_load_dwordx4 v[52:55], v[48:49], off
	s_nop 0
	global_load_dwordx4 v[48:51], v[50:51], off
	s_nop 0
	global_load_dwordx4 v[60:63], v[60:61], off
	s_nop 0
	global_load_dwordx4 v[56:59], v[56:57], off
	s_barrier
	global_load_dwordx4 v[80:83], v69, s[22:23]
	v_lshlrev_b32_e32 v68, 5, v92
	v_mov_b32_e32 v69, v65
	v_ashrrev_i32_e32 v71, 31, v70
	v_lshl_add_u64 v[68:69], s[10:11], 0, v[68:69]
	v_lshlrev_b64 v[74:75], 11, v[70:71]
	v_lshl_add_u64 v[74:75], v[68:69], 0, v[74:75]
	global_load_dwordx4 v[84:87], v[74:75], off
	global_load_dwordx4 v[88:91], v[74:75], off offset:16
	v_mov_b32_e32 v221, 0
	v_mov_b32_e32 v220, 0x2000
	v_lshl_add_u64 v[222:223], v[220:221], 0, v[74:75]
	global_load_dwordx4 v[164:167], v[222:223], off
	global_load_dwordx4 v[168:171], v[222:223], off offset:16
	v_mov_b32_e32 v220, 0x4000
	v_lshl_add_u64 v[222:223], v[220:221], 0, v[74:75]
	global_load_dwordx4 v[172:175], v[222:223], off
	global_load_dwordx4 v[176:179], v[222:223], off offset:16
	v_mov_b32_e32 v220, 0x6000
	v_lshl_add_u64 v[222:223], v[220:221], 0, v[74:75]
	global_load_dwordx4 v[180:183], v[222:223], off
	global_load_dwordx4 v[184:187], v[222:223], off offset:16
	v_mov_b32_e32 v220, 0x8000
	v_lshl_add_u64 v[222:223], v[220:221], 0, v[74:75]
	global_load_dwordx4 v[188:191], v[222:223], off
	global_load_dwordx4 v[192:195], v[222:223], off offset:16
	v_mov_b32_e32 v220, 0xa000
	v_lshl_add_u64 v[222:223], v[220:221], 0, v[74:75]
	global_load_dwordx4 v[196:199], v[222:223], off
	global_load_dwordx4 v[200:203], v[222:223], off offset:16
	v_mov_b32_e32 v220, 0xc000
	v_lshl_add_u64 v[222:223], v[220:221], 0, v[74:75]
	global_load_dwordx4 v[204:207], v[222:223], off
	global_load_dwordx4 v[208:211], v[222:223], off offset:16
	v_mov_b32_e32 v220, 0xe000
	v_lshl_add_u64 v[222:223], v[220:221], 0, v[74:75]
	global_load_dwordx4 v[212:215], v[222:223], off
	global_load_dwordx4 v[216:219], v[222:223], off offset:16
	v_cmp_eq_u32_e32 vcc, 0, v92
	v_readlane_b32 s65, v251, 7
	v_readlane_b32 s66, v251, 8
	v_readlane_b32 s67, v251, 9
	v_readlane_b32 s68, v251, 10
	v_readlane_b32 s69, v251, 11
	v_readlane_b32 s74, v251, 16
	v_readlane_b32 s75, v251, 17
	v_readlane_b32 s76, v251, 18
	v_readlane_b32 s77, v251, 19
	v_readlane_b32 s78, v251, 20
	v_readlane_b32 s79, v251, 21
	s_waitcnt vmcnt(16)
; __device__ __forceinline__ float shfl_xor_f(float v, int mask) { const int l = lane_fresh(); return __int_as_float(__builtin_amdgcn_ds_bpermute((l ^ mask) << 2, __float_as_int(v))); }
; __device__ __forceinline__ void attn_sample_item(const Params& p, int item, const int wv) {
;     ...
;     for (int it = 0; it < 8; ++it) {
;       const int mm = wid * 32 + it * 4 + ksub;
;       f32x4 k0 = *(const f32x4*)(Kc + (size_t)mm * 512 + dch * 8), k1 = *(const f32x4*)(Kc + (size_t)mm * 512 + dch * 8 + 4);
;       float d = q[0] * k0[0] + q[1] * k0[1] + q[2] * k0[2] + q[3] * k0[3] + q[4] * k1[0] + q[5] * k1[1] + q[6] * k1[2] + q[7] * k1[3];
;       d += shfl_xor_f(d, 1); d += shfl_xor_f(d, 2); d += shfl_xor_f(d, 4); d += shfl_xor_f(d, 8);
;       if (dch == 0) sc_l[mm] = d * 0.08838834764831845f;
;     }
	v_and_b32_e32 v79, 0xffff0000, v80
	v_lshlrev_b32_e32 v71, 16, v80
	v_lshlrev_b32_e32 v73, 16, v81
	v_and_b32_e32 v74, 0xffff0000, v81
	v_lshlrev_b32_e32 v75, 16, v82
	v_and_b32_e32 v76, 0xffff0000, v82
	s_waitcnt vmcnt(15)
	v_mul_f32_e32 v80, v85, v79
	v_fmac_f32_e32 v80, v84, v71
	v_fmac_f32_e32 v80, v86, v73
	v_fmac_f32_e32 v80, v87, v74
	s_waitcnt vmcnt(14)
	v_fmac_f32_e32 v80, v88, v75
	v_lshlrev_b32_e32 v77, 16, v83
	v_fmac_f32_e32 v80, v89, v76
	v_mbcnt_lo_u32_b32 v81, -1, 0
	v_mbcnt_hi_u32_b32 v81, -1, v81
	v_and_b32_e32 v78, 0xffff0000, v83
	v_fmac_f32_e32 v80, v90, v77
	v_lshlrev_b32_e32 v81, 2, v81
	v_fmac_f32_e32 v80, v91, v78
	v_xor_b32_e32 v81, 4, v81
	s_nop 1
	v_mov_b32_dpp v81, v80 quad_perm:[1,0,3,2] row_mask:0xf bank_mask:0xf
	s_waitcnt lgkmcnt(0)
	v_add_f32_e32 v80, v80, v81
	v_mbcnt_lo_u32_b32 v81, -1, 0
	v_mbcnt_hi_u32_b32 v81, -1, v81
	s_nop 0
	v_lshlrev_b32_e32 v81, 2, v81
	v_xor_b32_e32 v81, 8, v81
	s_nop 1
	v_mov_b32_dpp v81, v80 quad_perm:[2,3,0,1] row_mask:0xf bank_mask:0xf
	s_waitcnt lgkmcnt(0)
	v_add_f32_e32 v80, v80, v81
	v_mbcnt_lo_u32_b32 v81, -1, 0
	v_mbcnt_hi_u32_b32 v81, -1, v81
	s_nop 0
	v_lshlrev_b32_e32 v81, 2, v81
	v_xor_b32_e32 v81, 16, v81
	s_nop 1
	v_mov_b32_dpp v81, v80 row_shl:4 row_mask:0xf bank_mask:0x5
	v_mov_b32_dpp v81, v80 row_shr:4 row_mask:0xf bank_mask:0xa
	s_waitcnt lgkmcnt(0)
	v_add_f32_e32 v81, v80, v81
	v_mbcnt_lo_u32_b32 v80, -1, 0
	v_mbcnt_hi_u32_b32 v80, -1, v80
	s_nop 0
	v_lshlrev_b32_e32 v80, 2, v80
	v_xor_b32_e32 v80, 32, v80
	s_nop 1
	v_mov_b32_dpp v82, v81 row_ror:8 row_mask:0xf bank_mask:0xf
	v_lshl_add_u32 v80, v70, 2, 16
	s_and_saveexec_b64 s[10:11], vcc
	s_cbranch_execz .LBB0_466
	s_waitcnt lgkmcnt(0)
	v_add_f32_e32 v81, v81, v82
	v_mul_f32_e32 v81, 0x3db504f3, v81
	ds_write_b32 v80, v81
.LBB0_466:
	s_or_b64 exec, exec, s[10:11]
	s_waitcnt lgkmcnt(0)
	v_add_u32_e32 v82, 4, v70
	v_ashrrev_i32_e32 v83, 31, v82
	v_lshlrev_b64 v[82:83], 11, v[82:83]
	v_lshl_add_u64 v[86:87], v[68:69], 0, v[82:83]
	s_nop 0
	v_mbcnt_lo_u32_b32 v81, -1, 0
	v_mbcnt_hi_u32_b32 v81, -1, v81
	s_waitcnt vmcnt(12)
	v_mul_f32_e32 v83, v165, v79
	v_fmac_f32_e32 v83, v164, v71
	v_fmac_f32_e32 v83, v166, v73
	v_fmac_f32_e32 v83, v167, v74
	v_fmac_f32_e32 v83, v168, v75
	v_fmac_f32_e32 v83, v169, v76
	v_lshlrev_b32_e32 v81, 2, v81
	v_fmac_f32_e32 v83, v170, v77
	v_xor_b32_e32 v81, 4, v81
	v_fmac_f32_e32 v83, v171, v78
	s_nop 1
	v_mov_b32_dpp v81, v83 quad_perm:[1,0,3,2] row_mask:0xf bank_mask:0xf
	v_mbcnt_lo_u32_b32 v82, -1, 0
	v_mbcnt_hi_u32_b32 v82, -1, v82
	s_waitcnt lgkmcnt(0)
	v_add_f32_e32 v81, v83, v81
	v_lshlrev_b32_e32 v82, 2, v82
	v_xor_b32_e32 v82, 8, v82
	s_nop 1
	v_mov_b32_dpp v82, v81 quad_perm:[2,3,0,1] row_mask:0xf bank_mask:0xf
	v_mbcnt_lo_u32_b32 v83, -1, 0
	v_mbcnt_hi_u32_b32 v83, -1, v83
	s_waitcnt lgkmcnt(0)
	v_add_f32_e32 v81, v81, v82
	v_lshlrev_b32_e32 v83, 2, v83
	v_xor_b32_e32 v83, 16, v83
	s_nop 1
	v_mov_b32_dpp v82, v81 row_shl:4 row_mask:0xf bank_mask:0x5
	v_mov_b32_dpp v82, v81 row_shr:4 row_mask:0xf bank_mask:0xa
	v_mbcnt_lo_u32_b32 v83, -1, 0
	v_mbcnt_hi_u32_b32 v83, -1, v83
	s_waitcnt lgkmcnt(0)
	v_add_f32_e32 v81, v81, v82
	v_lshlrev_b32_e32 v83, 2, v83
	v_xor_b32_e32 v82, 32, v83
	s_nop 1
	v_mov_b32_dpp v82, v81 row_ror:8 row_mask:0xf bank_mask:0xf
	s_and_saveexec_b64 s[10:11], vcc
	s_cbranch_execz .LBB0_468
	s_waitcnt lgkmcnt(0)
	v_add_f32_e32 v81, v81, v82
	v_mul_f32_e32 v81, 0x3db504f3, v81
	ds_write_b32 v80, v81 offset:16
.LBB0_468:
	s_or_b64 exec, exec, s[10:11]
	s_waitcnt lgkmcnt(0)
	v_add_u32_e32 v82, 8, v70
	v_ashrrev_i32_e32 v83, 31, v82
	v_lshlrev_b64 v[82:83], 11, v[82:83]
	v_lshl_add_u64 v[86:87], v[68:69], 0, v[82:83]
	s_nop 0
	v_mbcnt_lo_u32_b32 v81, -1, 0
	v_mbcnt_hi_u32_b32 v81, -1, v81
	s_waitcnt vmcnt(10)
	v_mul_f32_e32 v83, v173, v79
	v_fmac_f32_e32 v83, v172, v71
	v_fmac_f32_e32 v83, v174, v73
	v_fmac_f32_e32 v83, v175, v74
	v_fmac_f32_e32 v83, v176, v75
	v_fmac_f32_e32 v83, v177, v76
	v_lshlrev_b32_e32 v81, 2, v81
	v_fmac_f32_e32 v83, v178, v77
	v_xor_b32_e32 v81, 4, v81
	v_fmac_f32_e32 v83, v179, v78
	s_nop 1
	v_mov_b32_dpp v81, v83 quad_perm:[1,0,3,2] row_mask:0xf bank_mask:0xf
	v_mbcnt_lo_u32_b32 v82, -1, 0
	v_mbcnt_hi_u32_b32 v82, -1, v82
	s_waitcnt lgkmcnt(0)
	v_add_f32_e32 v81, v83, v81
	v_lshlrev_b32_e32 v82, 2, v82
	v_xor_b32_e32 v82, 8, v82
	s_nop 1
	v_mov_b32_dpp v82, v81 quad_perm:[2,3,0,1] row_mask:0xf bank_mask:0xf
	v_mbcnt_lo_u32_b32 v83, -1, 0
	v_mbcnt_hi_u32_b32 v83, -1, v83
	s_waitcnt lgkmcnt(0)
	v_add_f32_e32 v81, v81, v82
	v_lshlrev_b32_e32 v83, 2, v83
	v_xor_b32_e32 v83, 16, v83
	s_nop 1
	v_mov_b32_dpp v82, v81 row_shl:4 row_mask:0xf bank_mask:0x5
	v_mov_b32_dpp v82, v81 row_shr:4 row_mask:0xf bank_mask:0xa
	v_mbcnt_lo_u32_b32 v83, -1, 0
	v_mbcnt_hi_u32_b32 v83, -1, v83
	s_waitcnt lgkmcnt(0)
	v_add_f32_e32 v81, v81, v82
	v_lshlrev_b32_e32 v83, 2, v83
	v_xor_b32_e32 v82, 32, v83
	s_nop 1
	v_mov_b32_dpp v82, v81 row_ror:8 row_mask:0xf bank_mask:0xf
	s_and_saveexec_b64 s[10:11], vcc
	s_cbranch_execz .LBB0_470
	s_waitcnt lgkmcnt(0)
	v_add_f32_e32 v81, v81, v82
	v_mul_f32_e32 v81, 0x3db504f3, v81
	ds_write_b32 v80, v81 offset:32
; __device__ __forceinline__ float shfl_xor_f(float v, int mask) { const int l = lane_fresh(); return __int_as_float(__builtin_amdgcn_ds_bpermute((l ^ mask) << 2, __float_as_int(v))); }
; __device__ __forceinline__ void attn_sample_item(const Params& p, int item, const int wv) {
;     ...
;     for (int it = 0; it < 8; ++it) {
;       const int mm = wid * 32 + it * 4 + ksub;
;       f32x4 k0 = *(const f32x4*)(Kc + (size_t)mm * 512 + dch * 8), k1 = *(const f32x4*)(Kc + (size_t)mm * 512 + dch * 8 + 4);
;       float d = q[0] * k0[0] + q[1] * k0[1] + q[2] * k0[2] + q[3] * k0[3] + q[4] * k1[0] + q[5] * k1[1] + q[6] * k1[2] + q[7] * k1[3];
;       d += shfl_xor_f(d, 1); d += shfl_xor_f(d, 2); d += shfl_xor_f(d, 4); d += shfl_xor_f(d, 8);
;       if (dch == 0) sc_l[mm] = d * 0.08838834764831845f;
;     }
.LBB0_470:
	s_or_b64 exec, exec, s[10:11]
	s_waitcnt lgkmcnt(0)
	v_add_u32_e32 v82, 12, v70
	v_ashrrev_i32_e32 v83, 31, v82
	v_lshlrev_b64 v[82:83], 11, v[82:83]
	v_lshl_add_u64 v[86:87], v[68:69], 0, v[82:83]
	s_nop 0
	v_mbcnt_lo_u32_b32 v81, -1, 0
	v_mbcnt_hi_u32_b32 v81, -1, v81
	s_waitcnt vmcnt(8)
	v_mul_f32_e32 v83, v181, v79
	v_fmac_f32_e32 v83, v180, v71
	v_fmac_f32_e32 v83, v182, v73
	v_fmac_f32_e32 v83, v183, v74
	v_fmac_f32_e32 v83, v184, v75
	v_fmac_f32_e32 v83, v185, v76
	v_lshlrev_b32_e32 v81, 2, v81
	v_fmac_f32_e32 v83, v186, v77
	v_xor_b32_e32 v81, 4, v81
	v_fmac_f32_e32 v83, v187, v78
	s_nop 1
	v_mov_b32_dpp v81, v83 quad_perm:[1,0,3,2] row_mask:0xf bank_mask:0xf
	v_mbcnt_lo_u32_b32 v82, -1, 0
	v_mbcnt_hi_u32_b32 v82, -1, v82
	s_waitcnt lgkmcnt(0)
	v_add_f32_e32 v81, v83, v81
	v_lshlrev_b32_e32 v82, 2, v82
	v_xor_b32_e32 v82, 8, v82
	s_nop 1
	v_mov_b32_dpp v82, v81 quad_perm:[2,3,0,1] row_mask:0xf bank_mask:0xf
	v_mbcnt_lo_u32_b32 v83, -1, 0
	v_mbcnt_hi_u32_b32 v83, -1, v83
	s_waitcnt lgkmcnt(0)
	v_add_f32_e32 v81, v81, v82
	v_lshlrev_b32_e32 v83, 2, v83
	v_xor_b32_e32 v83, 16, v83
	s_nop 1
	v_mov_b32_dpp v82, v81 row_shl:4 row_mask:0xf bank_mask:0x5
	v_mov_b32_dpp v82, v81 row_shr:4 row_mask:0xf bank_mask:0xa
	v_mbcnt_lo_u32_b32 v83, -1, 0
	v_mbcnt_hi_u32_b32 v83, -1, v83
	s_waitcnt lgkmcnt(0)
	v_add_f32_e32 v81, v81, v82
	v_lshlrev_b32_e32 v83, 2, v83
	v_xor_b32_e32 v82, 32, v83
	s_nop 1
	v_mov_b32_dpp v82, v81 row_ror:8 row_mask:0xf bank_mask:0xf
	s_and_saveexec_b64 s[10:11], vcc
	s_cbranch_execz .LBB0_472
	s_waitcnt lgkmcnt(0)
	v_add_f32_e32 v81, v81, v82
	v_mul_f32_e32 v81, 0x3db504f3, v81
	ds_write_b32 v80, v81 offset:48
.LBB0_472:
	s_or_b64 exec, exec, s[10:11]
	s_waitcnt lgkmcnt(0)
	v_add_u32_e32 v82, 16, v70
	v_ashrrev_i32_e32 v83, 31, v82
	v_lshlrev_b64 v[82:83], 11, v[82:83]
	v_lshl_add_u64 v[86:87], v[68:69], 0, v[82:83]
	s_nop 0
	v_mbcnt_lo_u32_b32 v81, -1, 0
	v_mbcnt_hi_u32_b32 v81, -1, v81
	s_waitcnt vmcnt(6)
	v_mul_f32_e32 v83, v189, v79
	v_fmac_f32_e32 v83, v188, v71
	v_fmac_f32_e32 v83, v190, v73
	v_fmac_f32_e32 v83, v191, v74
	v_fmac_f32_e32 v83, v192, v75
	v_fmac_f32_e32 v83, v193, v76
	v_lshlrev_b32_e32 v81, 2, v81
	v_fmac_f32_e32 v83, v194, v77
	v_xor_b32_e32 v81, 4, v81
	v_fmac_f32_e32 v83, v195, v78
	s_nop 1
	v_mov_b32_dpp v81, v83 quad_perm:[1,0,3,2] row_mask:0xf bank_mask:0xf
	v_mbcnt_lo_u32_b32 v82, -1, 0
	v_mbcnt_hi_u32_b32 v82, -1, v82
	s_waitcnt lgkmcnt(0)
	v_add_f32_e32 v81, v83, v81
	v_lshlrev_b32_e32 v82, 2, v82
	v_xor_b32_e32 v82, 8, v82
	s_nop 1
	v_mov_b32_dpp v82, v81 quad_perm:[2,3,0,1] row_mask:0xf bank_mask:0xf
	v_mbcnt_lo_u32_b32 v83, -1, 0
	v_mbcnt_hi_u32_b32 v83, -1, v83
	s_waitcnt lgkmcnt(0)
	v_add_f32_e32 v81, v81, v82
	v_lshlrev_b32_e32 v83, 2, v83
	v_xor_b32_e32 v83, 16, v83
	s_nop 1
	v_mov_b32_dpp v82, v81 row_shl:4 row_mask:0xf bank_mask:0x5
	v_mov_b32_dpp v82, v81 row_shr:4 row_mask:0xf bank_mask:0xa
	v_mbcnt_lo_u32_b32 v83, -1, 0
	v_mbcnt_hi_u32_b32 v83, -1, v83
	s_waitcnt lgkmcnt(0)
	v_add_f32_e32 v81, v81, v82
	v_lshlrev_b32_e32 v83, 2, v83
	v_xor_b32_e32 v82, 32, v83
	s_nop 1
	v_mov_b32_dpp v82, v81 row_ror:8 row_mask:0xf bank_mask:0xf
	s_and_saveexec_b64 s[10:11], vcc
	s_cbranch_execz .LBB0_474
	s_waitcnt lgkmcnt(0)
	v_add_f32_e32 v81, v81, v82
	v_mul_f32_e32 v81, 0x3db504f3, v81
	ds_write_b32 v80, v81 offset:64
.LBB0_474:
	s_or_b64 exec, exec, s[10:11]
	s_waitcnt lgkmcnt(0)
	v_add_u32_e32 v82, 20, v70
	v_ashrrev_i32_e32 v83, 31, v82
	v_lshlrev_b64 v[82:83], 11, v[82:83]
	v_lshl_add_u64 v[86:87], v[68:69], 0, v[82:83]
	s_nop 0
	v_mbcnt_lo_u32_b32 v81, -1, 0
	v_mbcnt_hi_u32_b32 v81, -1, v81
	s_waitcnt vmcnt(4)
	v_mul_f32_e32 v83, v197, v79
	v_fmac_f32_e32 v83, v196, v71
	v_fmac_f32_e32 v83, v198, v73
	v_fmac_f32_e32 v83, v199, v74
	v_fmac_f32_e32 v83, v200, v75
	v_fmac_f32_e32 v83, v201, v76
	v_lshlrev_b32_e32 v81, 2, v81
	v_fmac_f32_e32 v83, v202, v77
	v_xor_b32_e32 v81, 4, v81
	v_fmac_f32_e32 v83, v203, v78
	s_nop 1
	v_mov_b32_dpp v81, v83 quad_perm:[1,0,3,2] row_mask:0xf bank_mask:0xf
	v_mbcnt_lo_u32_b32 v82, -1, 0
	v_mbcnt_hi_u32_b32 v82, -1, v82
	s_waitcnt lgkmcnt(0)
	v_add_f32_e32 v81, v83, v81
	v_lshlrev_b32_e32 v82, 2, v82
	v_xor_b32_e32 v82, 8, v82
	s_nop 1
	v_mov_b32_dpp v82, v81 quad_perm:[2,3,0,1] row_mask:0xf bank_mask:0xf
	v_mbcnt_lo_u32_b32 v83, -1, 0
	v_mbcnt_hi_u32_b32 v83, -1, v83
	s_waitcnt lgkmcnt(0)
	v_add_f32_e32 v81, v81, v82
	v_lshlrev_b32_e32 v83, 2, v83
	v_xor_b32_e32 v83, 16, v83
	s_nop 1
	v_mov_b32_dpp v82, v81 row_shl:4 row_mask:0xf bank_mask:0x5
	v_mov_b32_dpp v82, v81 row_shr:4 row_mask:0xf bank_mask:0xa
	v_mbcnt_lo_u32_b32 v83, -1, 0
	v_mbcnt_hi_u32_b32 v83, -1, v83
	s_waitcnt lgkmcnt(0)
	v_add_f32_e32 v81, v81, v82
	v_lshlrev_b32_e32 v83, 2, v83
	v_xor_b32_e32 v82, 32, v83
	s_nop 1
	v_mov_b32_dpp v82, v81 row_ror:8 row_mask:0xf bank_mask:0xf
	s_and_saveexec_b64 s[10:11], vcc
	s_cbranch_execz .LBB0_476
	s_waitcnt lgkmcnt(0)
	v_add_f32_e32 v81, v81, v82
	v_mul_f32_e32 v81, 0x3db504f3, v81
	ds_write_b32 v80, v81 offset:80
; __device__ __forceinline__ float shfl_xor_f(float v, int mask) { const int l = lane_fresh(); return __int_as_float(__builtin_amdgcn_ds_bpermute((l ^ mask) << 2, __float_as_int(v))); }
; __device__ __forceinline__ void attn_sample_item(const Params& p, int item, const int wv) {
;     ...
;     for (int it = 0; it < 8; ++it) {
;       const int mm = wid * 32 + it * 4 + ksub;
;       f32x4 k0 = *(const f32x4*)(Kc + (size_t)mm * 512 + dch * 8), k1 = *(const f32x4*)(Kc + (size_t)mm * 512 + dch * 8 + 4);
;       float d = q[0] * k0[0] + q[1] * k0[1] + q[2] * k0[2] + q[3] * k0[3] + q[4] * k1[0] + q[5] * k1[1] + q[6] * k1[2] + q[7] * k1[3];
;       d += shfl_xor_f(d, 1); d += shfl_xor_f(d, 2); d += shfl_xor_f(d, 4); d += shfl_xor_f(d, 8);
;       if (dch == 0) sc_l[mm] = d * 0.08838834764831845f;
;     }
.LBB0_476:
	s_or_b64 exec, exec, s[10:11]
	s_waitcnt lgkmcnt(0)
	v_add_u32_e32 v82, 24, v70
	v_ashrrev_i32_e32 v83, 31, v82
	v_lshlrev_b64 v[82:83], 11, v[82:83]
	v_lshl_add_u64 v[86:87], v[68:69], 0, v[82:83]
	s_nop 0
	v_mbcnt_lo_u32_b32 v81, -1, 0
	v_mbcnt_hi_u32_b32 v81, -1, v81
	s_waitcnt vmcnt(2)
	v_mul_f32_e32 v83, v205, v79
	v_fmac_f32_e32 v83, v204, v71
	v_fmac_f32_e32 v83, v206, v73
	v_fmac_f32_e32 v83, v207, v74
	v_fmac_f32_e32 v83, v208, v75
	v_fmac_f32_e32 v83, v209, v76
	v_lshlrev_b32_e32 v81, 2, v81
	v_fmac_f32_e32 v83, v210, v77
	v_xor_b32_e32 v81, 4, v81
	v_fmac_f32_e32 v83, v211, v78
	s_nop 1
	v_mov_b32_dpp v81, v83 quad_perm:[1,0,3,2] row_mask:0xf bank_mask:0xf
	v_mbcnt_lo_u32_b32 v82, -1, 0
	v_mbcnt_hi_u32_b32 v82, -1, v82
	s_waitcnt lgkmcnt(0)
	v_add_f32_e32 v81, v83, v81
	v_lshlrev_b32_e32 v82, 2, v82
	v_xor_b32_e32 v82, 8, v82
	s_nop 1
	v_mov_b32_dpp v82, v81 quad_perm:[2,3,0,1] row_mask:0xf bank_mask:0xf
	v_mbcnt_lo_u32_b32 v83, -1, 0
	v_mbcnt_hi_u32_b32 v83, -1, v83
	s_waitcnt lgkmcnt(0)
	v_add_f32_e32 v81, v81, v82
	v_lshlrev_b32_e32 v83, 2, v83
	v_xor_b32_e32 v83, 16, v83
	s_nop 1
	v_mov_b32_dpp v82, v81 row_shl:4 row_mask:0xf bank_mask:0x5
	v_mov_b32_dpp v82, v81 row_shr:4 row_mask:0xf bank_mask:0xa
	v_mbcnt_lo_u32_b32 v83, -1, 0
	v_mbcnt_hi_u32_b32 v83, -1, v83
	s_waitcnt lgkmcnt(0)
	v_add_f32_e32 v81, v81, v82
	v_lshlrev_b32_e32 v83, 2, v83
	v_xor_b32_e32 v82, 32, v83
	s_nop 1
	v_mov_b32_dpp v82, v81 row_ror:8 row_mask:0xf bank_mask:0xf
	s_and_saveexec_b64 s[10:11], vcc
	s_cbranch_execz .LBB0_478
	s_waitcnt lgkmcnt(0)
	v_add_f32_e32 v81, v81, v82
	v_mul_f32_e32 v81, 0x3db504f3, v81
	ds_write_b32 v80, v81 offset:96
.LBB0_478:
	s_or_b64 exec, exec, s[10:11]
	s_waitcnt lgkmcnt(0)
	v_add_u32_e32 v82, 28, v70
	v_ashrrev_i32_e32 v83, 31, v82
	v_lshlrev_b64 v[82:83], 11, v[82:83]
	v_lshl_add_u64 v[68:69], v[68:69], 0, v[82:83]
	v_mbcnt_lo_u32_b32 v68, -1, 0
	v_mbcnt_hi_u32_b32 v68, -1, v68
	v_mbcnt_lo_u32_b32 v70, -1, 0
	v_mbcnt_hi_u32_b32 v70, -1, v70
	s_waitcnt vmcnt(0)
	v_mul_f32_e32 v69, v213, v79
	v_fmac_f32_e32 v69, v212, v71
	v_fmac_f32_e32 v69, v214, v73
	v_fmac_f32_e32 v69, v215, v74
	v_fmac_f32_e32 v69, v216, v75
	v_fmac_f32_e32 v69, v217, v76
	v_lshlrev_b32_e32 v68, 2, v68
	v_fmac_f32_e32 v69, v218, v77
	v_xor_b32_e32 v68, 4, v68
	v_fmac_f32_e32 v69, v219, v78
	s_nop 1
	v_mov_b32_dpp v68, v69 quad_perm:[1,0,3,2] row_mask:0xf bank_mask:0xf
	v_lshlrev_b32_e32 v70, 2, v70
	v_xor_b32_e32 v70, 8, v70
	s_waitcnt lgkmcnt(0)
	v_add_f32_e32 v68, v69, v68
	s_nop 1
	v_mov_b32_dpp v69, v68 quad_perm:[2,3,0,1] row_mask:0xf bank_mask:0xf
	v_mbcnt_lo_u32_b32 v70, -1, 0
	v_mbcnt_hi_u32_b32 v70, -1, v70
	s_waitcnt lgkmcnt(0)
	v_add_f32_e32 v68, v68, v69
	v_lshlrev_b32_e32 v70, 2, v70
	v_xor_b32_e32 v70, 16, v70
	s_nop 1
	v_mov_b32_dpp v69, v68 row_shl:4 row_mask:0xf bank_mask:0x5
	v_mov_b32_dpp v69, v68 row_shr:4 row_mask:0xf bank_mask:0xa
	v_mbcnt_lo_u32_b32 v70, -1, 0
	v_mbcnt_hi_u32_b32 v70, -1, v70
	s_waitcnt lgkmcnt(0)
	v_add_f32_e32 v68, v68, v69
	v_lshlrev_b32_e32 v70, 2, v70
	v_xor_b32_e32 v69, 32, v70
	s_nop 1
	v_mov_b32_dpp v69, v68 row_ror:8 row_mask:0xf bank_mask:0xf
	s_and_saveexec_b64 s[10:11], vcc
	s_cbranch_execz .LBB0_480
	s_waitcnt lgkmcnt(0)
	v_add_f32_e32 v68, v68, v69
	v_mul_f32_e32 v68, 0x3db504f3, v68
	ds_write_b32 v80, v68 offset:112
; __device__ __forceinline__ void attn_sample_item(const Params& p, int item, const int wv) {
;     ...
;   __syncthreads();
;   float pv[4];
;   {
;     float mx = -1e30f;
; #pragma unroll
;     for (int i = 0; i < 4; ++i) { pv[i] = sc_l[lane + 64 * i]; mx = fmaxf(mx, pv[i]); }
;     mx = wave_max(mx);
;     float sum = 0.f;
; #pragma unroll
;     for (int i = 0; i < 4; ++i) { pv[i] = __expf(pv[i] - mx); sum += pv[i]; }
;     sum = wave_sum(sum);
;     const float inv = 1.f / sum;
; #pragma unroll
;     for (int i = 0; i < 4; ++i) pv[i] *= inv;
;   }
;   __syncthreads();
;   if (wid == 0) {
; #pragma unroll
;     for (int i = 0; i < 4; ++i) sc_l[lane + 64 * i] = pv[i];
;   }
.LBB0_480:
	s_or_b64 exec, exec, s[10:11]
	v_lshl_add_u32 v68, v72, 2, 16
	s_waitcnt lgkmcnt(0)
	s_barrier
	ds_read2st64_b32 v[70:71], v68 offset1:1
	ds_read2st64_b32 v[72:73], v68 offset0:2 offset1:3
	v_mbcnt_lo_u32_b32 v74, -1, 0
	v_mbcnt_hi_u32_b32 v74, -1, v74
	v_mbcnt_lo_u32_b32 v75, -1, 0
	v_mbcnt_hi_u32_b32 v75, -1, v75
	v_readlane_b32 s10, v251, 58
	s_waitcnt lgkmcnt(1)
	v_max3_f32 v69, v70, s17, v71
	v_lshlrev_b32_e32 v74, 2, v74
	s_waitcnt lgkmcnt(0)
	v_max3_f32 v69, v69, v72, v73
	v_xor_b32_e32 v74, 0x80, v74
	ds_bpermute_b32 v74, v74, v69
	v_readlane_b32 s11, v251, 59
	s_and_b64 vcc, exec, s[10:11]
	s_waitcnt lgkmcnt(0)
	v_max_f32_e32 v74, v74, v74
	v_max_f32_e32 v69, v69, v74
	v_lshlrev_b32_e32 v74, 2, v75
	v_xor_b32_e32 v74, 64, v74
	ds_bpermute_b32 v74, v74, v69
	v_mbcnt_lo_u32_b32 v75, -1, 0
	v_mbcnt_hi_u32_b32 v75, -1, v75
	s_waitcnt lgkmcnt(0)
	v_max_f32_e32 v74, v74, v74
	v_lshlrev_b32_e32 v75, 2, v75
	v_max_f32_e32 v69, v69, v74
	v_xor_b32_e32 v74, 32, v75
	s_nop 1
	v_mov_b32_dpp v74, v69 row_ror:8 row_mask:0xf bank_mask:0xf
	v_mbcnt_lo_u32_b32 v75, -1, 0
	v_mbcnt_hi_u32_b32 v75, -1, v75
	s_waitcnt lgkmcnt(0)
	v_max_f32_e32 v74, v74, v74
	v_lshlrev_b32_e32 v75, 2, v75
	v_xor_b32_e32 v75, 16, v75
	v_max_f32_e32 v69, v69, v74
	s_nop 1
	v_mov_b32_dpp v74, v69 row_shl:4 row_mask:0xf bank_mask:0x5
	v_mov_b32_dpp v74, v69 row_shr:4 row_mask:0xf bank_mask:0xa
	v_mbcnt_lo_u32_b32 v75, -1, 0
	v_mbcnt_hi_u32_b32 v75, -1, v75
	s_waitcnt lgkmcnt(0)
	v_max_f32_e32 v74, v74, v74
	v_lshlrev_b32_e32 v75, 2, v75
	v_xor_b32_e32 v75, 8, v75
	v_max_f32_e32 v69, v69, v74
	s_nop 1
	v_mov_b32_dpp v74, v69 quad_perm:[2,3,0,1] row_mask:0xf bank_mask:0xf
	v_mbcnt_lo_u32_b32 v75, -1, 0
	v_mbcnt_hi_u32_b32 v75, -1, v75
	s_waitcnt lgkmcnt(0)
	v_max_f32_e32 v74, v74, v74
	v_lshlrev_b32_e32 v75, 2, v75
	v_xor_b32_e32 v75, 4, v75
	v_max_f32_e32 v69, v69, v74
	s_nop 1
	v_mov_b32_dpp v74, v69 quad_perm:[1,0,3,2] row_mask:0xf bank_mask:0xf
	s_waitcnt lgkmcnt(0)
	v_max_f32_e32 v74, v74, v74
	v_max_f32_e32 v69, v69, v74
	v_sub_f32_e32 v70, v70, v69
	v_sub_f32_e32 v71, v71, v69
	v_sub_f32_e32 v72, v72, v69
	v_sub_f32_e32 v69, v73, v69
	v_mul_f32_e32 v70, 0x3fb8aa3b, v70
	v_mul_f32_e32 v71, 0x3fb8aa3b, v71
	v_mul_f32_e32 v73, 0x3fb8aa3b, v69
	v_exp_f32_e32 v69, v70
	v_mul_f32_e32 v72, 0x3fb8aa3b, v72
	v_exp_f32_e32 v70, v71
	v_exp_f32_e32 v71, v72
	v_exp_f32_e32 v72, v73
	v_add_f32_e32 v73, 0, v69
	v_add_f32_e32 v73, v70, v73
	v_mbcnt_lo_u32_b32 v74, -1, 0
	v_mbcnt_hi_u32_b32 v74, -1, v74
	v_add_f32_e32 v73, v71, v73
	v_lshlrev_b32_e32 v74, 2, v74
	v_add_f32_e32 v73, v72, v73
	v_xor_b32_e32 v74, 0x80, v74
	ds_bpermute_b32 v74, v74, v73
	v_mbcnt_lo_u32_b32 v75, -1, 0
	v_mbcnt_hi_u32_b32 v75, -1, v75
	s_waitcnt lgkmcnt(0)
	v_add_f32_e32 v73, v73, v74
	v_lshlrev_b32_e32 v74, 2, v75
	v_xor_b32_e32 v74, 64, v74
	ds_bpermute_b32 v74, v74, v73
	v_mbcnt_lo_u32_b32 v75, -1, 0
	v_mbcnt_hi_u32_b32 v75, -1, v75
	s_waitcnt lgkmcnt(0)
	v_add_f32_e32 v73, v73, v74
	v_lshlrev_b32_e32 v75, 2, v75
	v_xor_b32_e32 v74, 32, v75
	s_nop 1
	v_mov_b32_dpp v74, v73 row_ror:8 row_mask:0xf bank_mask:0xf
	v_mbcnt_lo_u32_b32 v75, -1, 0
	v_mbcnt_hi_u32_b32 v75, -1, v75
	s_waitcnt lgkmcnt(0)
	v_add_f32_e32 v73, v73, v74
	v_lshlrev_b32_e32 v75, 2, v75
	v_xor_b32_e32 v75, 16, v75
	s_nop 1
	v_mov_b32_dpp v74, v73 row_shl:4 row_mask:0xf bank_mask:0x5
	v_mov_b32_dpp v74, v73 row_shr:4 row_mask:0xf bank_mask:0xa
	v_mbcnt_lo_u32_b32 v75, -1, 0
	v_mbcnt_hi_u32_b32 v75, -1, v75
	s_waitcnt lgkmcnt(0)
	v_add_f32_e32 v73, v73, v74
	v_lshlrev_b32_e32 v75, 2, v75
	v_xor_b32_e32 v75, 8, v75
	s_nop 1
	v_mov_b32_dpp v74, v73 quad_perm:[2,3,0,1] row_mask:0xf bank_mask:0xf
	v_mbcnt_lo_u32_b32 v75, -1, 0
	v_mbcnt_hi_u32_b32 v75, -1, v75
	s_waitcnt lgkmcnt(0)
	v_lshlrev_b32_e32 v75, 2, v75
	s_barrier
	v_add_f32_e32 v73, v73, v74
	v_xor_b32_e32 v74, 4, v75
	s_nop 1
	v_mov_b32_dpp v74, v73 quad_perm:[1,0,3,2] row_mask:0xf bank_mask:0xf
	s_waitcnt lgkmcnt(0)
	s_cbranch_vccnz .LBB0_482
	v_add_f32_e32 v73, v73, v74
	v_div_scale_f32 v74, s[10:11], v73, v73, 1.0
	v_rcp_f32_e32 v75, v74
	v_div_scale_f32 v76, vcc, 1.0, v73, 1.0
	v_fma_f32 v77, -v74, v75, 1.0
	v_fmac_f32_e32 v75, v77, v75
	v_mul_f32_e32 v77, v76, v75
	v_fma_f32 v78, -v74, v77, v76
	v_fmac_f32_e32 v77, v78, v75
	v_fma_f32 v74, -v74, v77, v76
	v_div_fmas_f32 v74, v74, v75, v77
	v_div_fixup_f32 v73, v74, v73, 1.0
	v_mul_f32_e32 v70, v70, v73
	v_mul_f32_e32 v69, v69, v73
	v_mul_f32_e32 v72, v72, v73
	v_mul_f32_e32 v71, v71, v73
	ds_write2st64_b32 v68, v69, v70 offset1:1
	ds_write2st64_b32 v68, v71, v72 offset0:2 offset1:3

; __device__ __forceinline__ float bflo(unsigned w) { return __uint_as_float(w << 16); }
; __device__ __forceinline__ float bfhi(unsigned w) { return __uint_as_float(w & 0xffff0000u); }
; __device__ __forceinline__ void attn_sample_item(const Params& p, int item, const int wv) {
;     ...
;   const int vdch = tid & 31, vmg = tid >> 5;
;   f32x4 vreg[16];
; #pragma unroll
;   for (int i = 0; i < 16; ++i) vreg[i] = *(const f32x4*)(Vc + (size_t)(vmg * 16 + i) * 512 + vdch * 4);
;   __syncthreads();
;   {
;     const int dch = lane & 15, ksub = lane >> 4;
;     u32x4 qw = *(const u32x4*)(Q + (size_t)tok * 512 + h * 128 + dch * 8);
;     float q[8] = {bflo(qw.x), bfhi(qw.x), bflo(qw.y), bfhi(qw.y), bflo(qw.z), bfhi(qw.z), bflo(qw.w), bfhi(qw.w)};
; #pragma unroll
;     for (int it = 0; it < 8; ++it) {
;       const int mm = wid * 32 + it * 4 + ksub;
;       f32x4 k0 = *(const f32x4*)(Kc + (size_t)mm * 512 + dch * 8), k1 = *(const f32x4*)(Kc + (size_t)mm * 512 + dch * 8 + 4);
;       float d = q[0] * k0[0] + q[1] * k0[1] + q[2] * k0[2] + q[3] * k0[3] + q[4] * k1[0] + q[5] * k1[1] + q[6] * k1[2] + q[7] * k1[3];
.LBB0_490:
	s_lshr_b32 s0, s18, 2
	s_and_b32 s19, s14, 0x180
	v_readlane_b32 s64, v251, 6
	s_lshl_b32 s20, s19, 2
	s_lshl_b64 s[8:9], s[0:1], 19
	v_readlane_b32 s72, v251, 14
	v_readlane_b32 s73, v251, 15
	s_or_b32 s8, s8, s20
	s_mov_b64 s[44:45], s[72:73]
	v_mbcnt_lo_u32_b32 v72, -1, 0
	v_mbcnt_hi_u32_b32 v72, -1, v72
	v_readlane_b32 s70, v251, 12
	v_add_u32_e32 v66, s82, v72
	v_readlane_b32 s71, v251, 13
	s_add_u32 s20, s44, s8
	s_mov_b64 s[42:43], s[70:71]
	s_addc_u32 s21, s45, s9
	v_and_b32_e32 v0, 31, v72
	v_ashrrev_i32_e32 v67, 5, v66
	s_addk_i32 s0, 0x4000
	v_lshlrev_b32_e32 v56, 4, v67
	v_lshlrev_b32_e32 v64, 4, v0
	s_add_u32 s8, s42, s8
	v_lshl_add_u64 v[58:59], s[20:21], 0, v[64:65]
	v_ashrrev_i32_e32 v57, 31, v56
	s_addc_u32 s9, s43, s9
	s_lshl_b64 s[20:21], s[0:1], 10
	s_waitcnt lgkmcnt(0)
	v_lshlrev_b64 v[0:1], 11, v[56:57]
	v_or_b32_e32 v2, 1, v56
	v_or_b32_e32 v8, 2, v56
	v_or_b32_e32 v10, 3, v56
	v_or_b32_e32 v16, 4, v56
	v_or_b32_e32 v18, 5, v56
	v_or_b32_e32 v24, 6, v56
	v_or_b32_e32 v26, 7, v56
	v_or_b32_e32 v32, 8, v56
	v_or_b32_e32 v34, 9, v56
	v_or_b32_e32 v40, 10, v56
	v_or_b32_e32 v42, 11, v56
	v_or_b32_e32 v48, 12, v56
	v_or_b32_e32 v50, 13, v56
	v_or_b32_e32 v60, 14, v56
	v_or_b32_e32 v56, 15, v56
	s_add_u32 s20, s10, s20
	v_ashrrev_i32_e32 v3, 31, v2
	v_ashrrev_i32_e32 v9, 31, v8
	v_ashrrev_i32_e32 v11, 31, v10
	v_ashrrev_i32_e32 v17, 31, v16
	v_ashrrev_i32_e32 v19, 31, v18
	v_ashrrev_i32_e32 v25, 31, v24
	v_ashrrev_i32_e32 v27, 31, v26
	v_ashrrev_i32_e32 v33, 31, v32
	v_ashrrev_i32_e32 v35, 31, v34
	v_ashrrev_i32_e32 v41, 31, v40
	v_ashrrev_i32_e32 v43, 31, v42
	v_ashrrev_i32_e32 v49, 31, v48
	v_ashrrev_i32_e32 v51, 31, v50
	v_ashrrev_i32_e32 v61, 31, v60
	v_ashrrev_i32_e32 v57, 31, v56
	s_addc_u32 s21, s11, s21
	s_lshl_b32 s19, s19, 1
	v_lshlrev_b64 v[2:3], 11, v[2:3]
	v_lshlrev_b64 v[8:9], 11, v[8:9]
	v_lshlrev_b64 v[10:11], 11, v[10:11]
	v_lshlrev_b64 v[16:17], 11, v[16:17]
	v_lshlrev_b64 v[18:19], 11, v[18:19]
	v_lshlrev_b64 v[24:25], 11, v[24:25]
	v_lshlrev_b64 v[26:27], 11, v[26:27]
	v_lshlrev_b64 v[32:33], 11, v[32:33]
	v_lshlrev_b64 v[34:35], 11, v[34:35]
	v_lshlrev_b64 v[40:41], 11, v[40:41]
	v_lshlrev_b64 v[42:43], 11, v[42:43]
	v_lshlrev_b64 v[48:49], 11, v[48:49]
	v_lshlrev_b64 v[50:51], 11, v[50:51]
	v_lshlrev_b64 v[60:61], 11, v[60:61]
	v_lshlrev_b64 v[56:57], 11, v[56:57]
	v_and_b32_e32 v92, 15, v72
	v_ashrrev_i32_e32 v68, 4, v72
	s_add_u32 s20, s20, s19
	v_lshl_add_u64 v[0:1], v[58:59], 0, v[0:1]
	v_lshl_add_u64 v[2:3], v[58:59], 0, v[2:3]
	v_lshl_add_u64 v[8:9], v[58:59], 0, v[8:9]
	v_lshl_add_u64 v[10:11], v[58:59], 0, v[10:11]
	v_lshl_add_u64 v[16:17], v[58:59], 0, v[16:17]
	v_lshl_add_u64 v[18:19], v[58:59], 0, v[18:19]
	v_lshl_add_u64 v[24:25], v[58:59], 0, v[24:25]
	v_lshl_add_u64 v[26:27], v[58:59], 0, v[26:27]
	v_lshl_add_u64 v[32:33], v[58:59], 0, v[32:33]
	v_lshl_add_u64 v[34:35], v[58:59], 0, v[34:35]
	v_lshl_add_u64 v[40:41], v[58:59], 0, v[40:41]
	v_lshl_add_u64 v[42:43], v[58:59], 0, v[42:43]
	v_lshl_add_u64 v[48:49], v[58:59], 0, v[48:49]
	v_lshl_add_u64 v[50:51], v[58:59], 0, v[50:51]
	v_lshl_add_u64 v[60:61], v[58:59], 0, v[60:61]
	v_lshl_add_u64 v[56:57], v[58:59], 0, v[56:57]
	s_addc_u32 s21, s21, 0
	v_lshlrev_b32_e32 v69, 4, v92
	v_add_u32_e32 v70, s5, v68
	global_load_dwordx4 v[4:7], v[0:1], off
	s_nop 0
	global_load_dwordx4 v[0:3], v[2:3], off
	s_nop 0
	global_load_dwordx4 v[12:15], v[8:9], off
	s_nop 0
	global_load_dwordx4 v[8:11], v[10:11], off
	s_nop 0
	global_load_dwordx4 v[20:23], v[16:17], off
	s_nop 0
	global_load_dwordx4 v[16:19], v[18:19], off
	s_nop 0
	global_load_dwordx4 v[28:31], v[24:25], off
	s_nop 0
	global_load_dwordx4 v[24:27], v[26:27], off
	s_nop 0
	global_load_dwordx4 v[36:39], v[32:33], off
	s_nop 0
	global_load_dwordx4 v[32:35], v[34:35], off
	s_nop 0
	global_load_dwordx4 v[44:47], v[40:41], off
	s_nop 0
	global_load_dwordx4 v[40:43], v[42:43], off
	s_nop 0
	global_load_dwordx4 v[52:55], v[48:49], off
	s_nop 0
	global_load_dwordx4 v[48:51], v[50:51], off
	s_nop 0
	global_load_dwordx4 v[60:63], v[60:61], off
	s_nop 0
	global_load_dwordx4 v[56:59], v[56:57], off
	s_barrier
	global_load_dwordx4 v[80:83], v69, s[20:21]
	v_lshlrev_b32_e32 v68, 5, v92
	v_mov_b32_e32 v69, v65
	v_ashrrev_i32_e32 v71, 31, v70
	v_lshl_add_u64 v[68:69], s[8:9], 0, v[68:69]
	v_lshlrev_b64 v[74:75], 11, v[70:71]
	v_lshl_add_u64 v[74:75], v[68:69], 0, v[74:75]
	global_load_dwordx4 v[84:87], v[74:75], off
	global_load_dwordx4 v[88:91], v[74:75], off offset:16
	v_mov_b32_e32 v221, 0
	v_mov_b32_e32 v220, 0x2000
	v_lshl_add_u64 v[222:223], v[220:221], 0, v[74:75]
	global_load_dwordx4 v[164:167], v[222:223], off
	global_load_dwordx4 v[168:171], v[222:223], off offset:16
	v_mov_b32_e32 v220, 0x4000
	v_lshl_add_u64 v[222:223], v[220:221], 0, v[74:75]
	global_load_dwordx4 v[172:175], v[222:223], off
	global_load_dwordx4 v[176:179], v[222:223], off offset:16
	v_mov_b32_e32 v220, 0x6000
	v_lshl_add_u64 v[222:223], v[220:221], 0, v[74:75]
	global_load_dwordx4 v[180:183], v[222:223], off
	global_load_dwordx4 v[184:187], v[222:223], off offset:16
	v_mov_b32_e32 v220, 0x8000
	v_lshl_add_u64 v[222:223], v[220:221], 0, v[74:75]
	global_load_dwordx4 v[188:191], v[222:223], off
	global_load_dwordx4 v[192:195], v[222:223], off offset:16
	v_mov_b32_e32 v220, 0xa000
	v_lshl_add_u64 v[222:223], v[220:221], 0, v[74:75]
	global_load_dwordx4 v[196:199], v[222:223], off
	global_load_dwordx4 v[200:203], v[222:223], off offset:16
	v_mov_b32_e32 v220, 0xc000
	v_lshl_add_u64 v[222:223], v[220:221], 0, v[74:75]
	global_load_dwordx4 v[204:207], v[222:223], off
	global_load_dwordx4 v[208:211], v[222:223], off offset:16
	v_mov_b32_e32 v220, 0xe000
	v_lshl_add_u64 v[222:223], v[220:221], 0, v[74:75]
	global_load_dwordx4 v[212:215], v[222:223], off
	global_load_dwordx4 v[216:219], v[222:223], off offset:16
	v_cmp_eq_u32_e32 vcc, 0, v92
	v_readlane_b32 s65, v251, 7
	v_readlane_b32 s66, v251, 8
	v_readlane_b32 s67, v251, 9
	v_readlane_b32 s68, v251, 10
	v_readlane_b32 s69, v251, 11
	v_readlane_b32 s74, v251, 16
	v_readlane_b32 s75, v251, 17
	v_readlane_b32 s76, v251, 18
	v_readlane_b32 s77, v251, 19
	v_readlane_b32 s78, v251, 20
	v_readlane_b32 s79, v251, 21
	s_waitcnt vmcnt(16)
; __device__ __forceinline__ float shfl_xor_f(float v, int mask) { const int l = lane_fresh(); return __int_as_float(__builtin_amdgcn_ds_bpermute((l ^ mask) << 2, __float_as_int(v))); }
; __device__ __forceinline__ void attn_sample_item(const Params& p, int item, const int wv) {
;     ...
;     for (int it = 0; it < 8; ++it) {
;       const int mm = wid * 32 + it * 4 + ksub;
;       f32x4 k0 = *(const f32x4*)(Kc + (size_t)mm * 512 + dch * 8), k1 = *(const f32x4*)(Kc + (size_t)mm * 512 + dch * 8 + 4);
;       float d = q[0] * k0[0] + q[1] * k0[1] + q[2] * k0[2] + q[3] * k0[3] + q[4] * k1[0] + q[5] * k1[1] + q[6] * k1[2] + q[7] * k1[3];
;       d += shfl_xor_f(d, 1); d += shfl_xor_f(d, 2); d += shfl_xor_f(d, 4); d += shfl_xor_f(d, 8);
;       if (dch == 0) sc_l[mm] = d * 0.08838834764831845f;
;     }
	v_and_b32_e32 v79, 0xffff0000, v80
	v_lshlrev_b32_e32 v71, 16, v80
	v_lshlrev_b32_e32 v73, 16, v81
	v_and_b32_e32 v74, 0xffff0000, v81
	v_lshlrev_b32_e32 v75, 16, v82
	v_and_b32_e32 v76, 0xffff0000, v82
	s_waitcnt vmcnt(15)
	v_mul_f32_e32 v80, v85, v79
	v_fmac_f32_e32 v80, v84, v71
	v_fmac_f32_e32 v80, v86, v73
	v_fmac_f32_e32 v80, v87, v74
	s_waitcnt vmcnt(14)
	v_fmac_f32_e32 v80, v88, v75
	v_lshlrev_b32_e32 v77, 16, v83
	v_fmac_f32_e32 v80, v89, v76
	v_mbcnt_lo_u32_b32 v81, -1, 0
	v_mbcnt_hi_u32_b32 v81, -1, v81
	v_and_b32_e32 v78, 0xffff0000, v83
	v_fmac_f32_e32 v80, v90, v77
	v_lshlrev_b32_e32 v81, 2, v81
	v_fmac_f32_e32 v80, v91, v78
	v_xor_b32_e32 v81, 4, v81
	s_nop 1
	v_mov_b32_dpp v81, v80 quad_perm:[1,0,3,2] row_mask:0xf bank_mask:0xf
	s_waitcnt lgkmcnt(0)
	v_add_f32_e32 v80, v80, v81
	v_mbcnt_lo_u32_b32 v81, -1, 0
	v_mbcnt_hi_u32_b32 v81, -1, v81
	s_nop 0
	v_lshlrev_b32_e32 v81, 2, v81
	v_xor_b32_e32 v81, 8, v81
	s_nop 1
	v_mov_b32_dpp v81, v80 quad_perm:[2,3,0,1] row_mask:0xf bank_mask:0xf
	s_waitcnt lgkmcnt(0)
	v_add_f32_e32 v80, v80, v81
	v_mbcnt_lo_u32_b32 v81, -1, 0
	v_mbcnt_hi_u32_b32 v81, -1, v81
	s_nop 0
	v_lshlrev_b32_e32 v81, 2, v81
	v_xor_b32_e32 v81, 16, v81
	s_nop 1
	v_mov_b32_dpp v81, v80 row_shl:4 row_mask:0xf bank_mask:0x5
	v_mov_b32_dpp v81, v80 row_shr:4 row_mask:0xf bank_mask:0xa
	s_waitcnt lgkmcnt(0)
	v_add_f32_e32 v81, v80, v81
	v_mbcnt_lo_u32_b32 v80, -1, 0
	v_mbcnt_hi_u32_b32 v80, -1, v80
	s_nop 0
	v_lshlrev_b32_e32 v80, 2, v80
	v_xor_b32_e32 v80, 32, v80
	s_nop 1
	v_mov_b32_dpp v82, v81 row_ror:8 row_mask:0xf bank_mask:0xf
	v_lshl_add_u32 v80, v70, 2, 16
	s_and_saveexec_b64 s[8:9], vcc
	s_cbranch_execz .LBB0_492
	s_waitcnt lgkmcnt(0)
	v_add_f32_e32 v81, v81, v82
	v_mul_f32_e32 v81, 0x3db504f3, v81
	ds_write_b32 v80, v81
.LBB0_492:
	s_or_b64 exec, exec, s[8:9]
	s_waitcnt lgkmcnt(0)
	v_add_u32_e32 v82, 4, v70
	v_ashrrev_i32_e32 v83, 31, v82
	v_lshlrev_b64 v[82:83], 11, v[82:83]
	v_lshl_add_u64 v[86:87], v[68:69], 0, v[82:83]
	s_nop 0
	v_mbcnt_lo_u32_b32 v81, -1, 0
	v_mbcnt_hi_u32_b32 v81, -1, v81
	s_waitcnt vmcnt(12)
	v_mul_f32_e32 v83, v165, v79
	v_fmac_f32_e32 v83, v164, v71
	v_fmac_f32_e32 v83, v166, v73
	v_fmac_f32_e32 v83, v167, v74
	v_fmac_f32_e32 v83, v168, v75
	v_fmac_f32_e32 v83, v169, v76
	v_lshlrev_b32_e32 v81, 2, v81
	v_fmac_f32_e32 v83, v170, v77
	v_xor_b32_e32 v81, 4, v81
	v_fmac_f32_e32 v83, v171, v78
	s_nop 1
	v_mov_b32_dpp v81, v83 quad_perm:[1,0,3,2] row_mask:0xf bank_mask:0xf
	v_mbcnt_lo_u32_b32 v82, -1, 0
	v_mbcnt_hi_u32_b32 v82, -1, v82
	s_waitcnt lgkmcnt(0)
	v_add_f32_e32 v81, v83, v81
	v_lshlrev_b32_e32 v82, 2, v82
	v_xor_b32_e32 v82, 8, v82
	s_nop 1
	v_mov_b32_dpp v82, v81 quad_perm:[2,3,0,1] row_mask:0xf bank_mask:0xf
	v_mbcnt_lo_u32_b32 v83, -1, 0
	v_mbcnt_hi_u32_b32 v83, -1, v83
	s_waitcnt lgkmcnt(0)
	v_add_f32_e32 v81, v81, v82
	v_lshlrev_b32_e32 v83, 2, v83
	v_xor_b32_e32 v83, 16, v83
	s_nop 1
	v_mov_b32_dpp v82, v81 row_shl:4 row_mask:0xf bank_mask:0x5
	v_mov_b32_dpp v82, v81 row_shr:4 row_mask:0xf bank_mask:0xa
	v_mbcnt_lo_u32_b32 v83, -1, 0
	v_mbcnt_hi_u32_b32 v83, -1, v83
	s_waitcnt lgkmcnt(0)
	v_add_f32_e32 v81, v81, v82
	v_lshlrev_b32_e32 v83, 2, v83
	v_xor_b32_e32 v82, 32, v83
	s_nop 1
	v_mov_b32_dpp v82, v81 row_ror:8 row_mask:0xf bank_mask:0xf
	s_and_saveexec_b64 s[8:9], vcc
	s_cbranch_execz .LBB0_494
	s_waitcnt lgkmcnt(0)
	v_add_f32_e32 v81, v81, v82
	v_mul_f32_e32 v81, 0x3db504f3, v81
	ds_write_b32 v80, v81 offset:16
.LBB0_494:
	s_or_b64 exec, exec, s[8:9]
	s_waitcnt lgkmcnt(0)
	v_add_u32_e32 v82, 8, v70
	v_ashrrev_i32_e32 v83, 31, v82
	v_lshlrev_b64 v[82:83], 11, v[82:83]
	v_lshl_add_u64 v[86:87], v[68:69], 0, v[82:83]
	s_nop 0
	v_mbcnt_lo_u32_b32 v81, -1, 0
	v_mbcnt_hi_u32_b32 v81, -1, v81
	s_waitcnt vmcnt(10)
	v_mul_f32_e32 v83, v173, v79
	v_fmac_f32_e32 v83, v172, v71
	v_fmac_f32_e32 v83, v174, v73
	v_fmac_f32_e32 v83, v175, v74
	v_fmac_f32_e32 v83, v176, v75
	v_fmac_f32_e32 v83, v177, v76
	v_lshlrev_b32_e32 v81, 2, v81
	v_fmac_f32_e32 v83, v178, v77
	v_xor_b32_e32 v81, 4, v81
	v_fmac_f32_e32 v83, v179, v78
	s_nop 1
	v_mov_b32_dpp v81, v83 quad_perm:[1,0,3,2] row_mask:0xf bank_mask:0xf
	v_mbcnt_lo_u32_b32 v82, -1, 0
	v_mbcnt_hi_u32_b32 v82, -1, v82
	s_waitcnt lgkmcnt(0)
	v_add_f32_e32 v81, v83, v81
	v_lshlrev_b32_e32 v82, 2, v82
	v_xor_b32_e32 v82, 8, v82
	s_nop 1
	v_mov_b32_dpp v82, v81 quad_perm:[2,3,0,1] row_mask:0xf bank_mask:0xf
	v_mbcnt_lo_u32_b32 v83, -1, 0
	v_mbcnt_hi_u32_b32 v83, -1, v83
	s_waitcnt lgkmcnt(0)
	v_add_f32_e32 v81, v81, v82
	v_lshlrev_b32_e32 v83, 2, v83
	v_xor_b32_e32 v83, 16, v83
	s_nop 1
	v_mov_b32_dpp v82, v81 row_shl:4 row_mask:0xf bank_mask:0x5
	v_mov_b32_dpp v82, v81 row_shr:4 row_mask:0xf bank_mask:0xa
	v_mbcnt_lo_u32_b32 v83, -1, 0
	v_mbcnt_hi_u32_b32 v83, -1, v83
	s_waitcnt lgkmcnt(0)
	v_add_f32_e32 v81, v81, v82
	v_lshlrev_b32_e32 v83, 2, v83
	v_xor_b32_e32 v82, 32, v83
	s_nop 1
	v_mov_b32_dpp v82, v81 row_ror:8 row_mask:0xf bank_mask:0xf
	s_and_saveexec_b64 s[8:9], vcc
	s_cbranch_execz .LBB0_496
	s_waitcnt lgkmcnt(0)
	v_add_f32_e32 v81, v81, v82
	v_mul_f32_e32 v81, 0x3db504f3, v81
	ds_write_b32 v80, v81 offset:32
; __device__ __forceinline__ float shfl_xor_f(float v, int mask) { const int l = lane_fresh(); return __int_as_float(__builtin_amdgcn_ds_bpermute((l ^ mask) << 2, __float_as_int(v))); }
; __device__ __forceinline__ void attn_sample_item(const Params& p, int item, const int wv) {
;     ...
;     for (int it = 0; it < 8; ++it) {
;       const int mm = wid * 32 + it * 4 + ksub;
;       f32x4 k0 = *(const f32x4*)(Kc + (size_t)mm * 512 + dch * 8), k1 = *(const f32x4*)(Kc + (size_t)mm * 512 + dch * 8 + 4);
;       float d = q[0] * k0[0] + q[1] * k0[1] + q[2] * k0[2] + q[3] * k0[3] + q[4] * k1[0] + q[5] * k1[1] + q[6] * k1[2] + q[7] * k1[3];
;       d += shfl_xor_f(d, 1); d += shfl_xor_f(d, 2); d += shfl_xor_f(d, 4); d += shfl_xor_f(d, 8);
;       if (dch == 0) sc_l[mm] = d * 0.08838834764831845f;
;     }
.LBB0_496:
	s_or_b64 exec, exec, s[8:9]
	s_waitcnt lgkmcnt(0)
	v_add_u32_e32 v82, 12, v70
	v_ashrrev_i32_e32 v83, 31, v82
	v_lshlrev_b64 v[82:83], 11, v[82:83]
	v_lshl_add_u64 v[86:87], v[68:69], 0, v[82:83]
	s_nop 0
	v_mbcnt_lo_u32_b32 v81, -1, 0
	v_mbcnt_hi_u32_b32 v81, -1, v81
	s_waitcnt vmcnt(8)
	v_mul_f32_e32 v83, v181, v79
	v_fmac_f32_e32 v83, v180, v71
	v_fmac_f32_e32 v83, v182, v73
	v_fmac_f32_e32 v83, v183, v74
	v_fmac_f32_e32 v83, v184, v75
	v_fmac_f32_e32 v83, v185, v76
	v_lshlrev_b32_e32 v81, 2, v81
	v_fmac_f32_e32 v83, v186, v77
	v_xor_b32_e32 v81, 4, v81
	v_fmac_f32_e32 v83, v187, v78
	s_nop 1
	v_mov_b32_dpp v81, v83 quad_perm:[1,0,3,2] row_mask:0xf bank_mask:0xf
	v_mbcnt_lo_u32_b32 v82, -1, 0
	v_mbcnt_hi_u32_b32 v82, -1, v82
	s_waitcnt lgkmcnt(0)
	v_add_f32_e32 v81, v83, v81
	v_lshlrev_b32_e32 v82, 2, v82
	v_xor_b32_e32 v82, 8, v82
	s_nop 1
	v_mov_b32_dpp v82, v81 quad_perm:[2,3,0,1] row_mask:0xf bank_mask:0xf
	v_mbcnt_lo_u32_b32 v83, -1, 0
	v_mbcnt_hi_u32_b32 v83, -1, v83
	s_waitcnt lgkmcnt(0)
	v_add_f32_e32 v81, v81, v82
	v_lshlrev_b32_e32 v83, 2, v83
	v_xor_b32_e32 v83, 16, v83
	s_nop 1
	v_mov_b32_dpp v82, v81 row_shl:4 row_mask:0xf bank_mask:0x5
	v_mov_b32_dpp v82, v81 row_shr:4 row_mask:0xf bank_mask:0xa
	v_mbcnt_lo_u32_b32 v83, -1, 0
	v_mbcnt_hi_u32_b32 v83, -1, v83
	s_waitcnt lgkmcnt(0)
	v_add_f32_e32 v81, v81, v82
	v_lshlrev_b32_e32 v83, 2, v83
	v_xor_b32_e32 v82, 32, v83
	s_nop 1
	v_mov_b32_dpp v82, v81 row_ror:8 row_mask:0xf bank_mask:0xf
	s_and_saveexec_b64 s[8:9], vcc
	s_cbranch_execz .LBB0_498
	s_waitcnt lgkmcnt(0)
	v_add_f32_e32 v81, v81, v82
	v_mul_f32_e32 v81, 0x3db504f3, v81
	ds_write_b32 v80, v81 offset:48
.LBB0_498:
	s_or_b64 exec, exec, s[8:9]
	s_waitcnt lgkmcnt(0)
	v_add_u32_e32 v82, 16, v70
	v_ashrrev_i32_e32 v83, 31, v82
	v_lshlrev_b64 v[82:83], 11, v[82:83]
	v_lshl_add_u64 v[86:87], v[68:69], 0, v[82:83]
	s_nop 0
	v_mbcnt_lo_u32_b32 v81, -1, 0
	v_mbcnt_hi_u32_b32 v81, -1, v81
	s_waitcnt vmcnt(6)
	v_mul_f32_e32 v83, v189, v79
	v_fmac_f32_e32 v83, v188, v71
	v_fmac_f32_e32 v83, v190, v73
	v_fmac_f32_e32 v83, v191, v74
	v_fmac_f32_e32 v83, v192, v75
	v_fmac_f32_e32 v83, v193, v76
	v_lshlrev_b32_e32 v81, 2, v81
	v_fmac_f32_e32 v83, v194, v77
	v_xor_b32_e32 v81, 4, v81
	v_fmac_f32_e32 v83, v195, v78
	s_nop 1
	v_mov_b32_dpp v81, v83 quad_perm:[1,0,3,2] row_mask:0xf bank_mask:0xf
	v_mbcnt_lo_u32_b32 v82, -1, 0
	v_mbcnt_hi_u32_b32 v82, -1, v82
	s_waitcnt lgkmcnt(0)
	v_add_f32_e32 v81, v83, v81
	v_lshlrev_b32_e32 v82, 2, v82
	v_xor_b32_e32 v82, 8, v82
	s_nop 1
	v_mov_b32_dpp v82, v81 quad_perm:[2,3,0,1] row_mask:0xf bank_mask:0xf
	v_mbcnt_lo_u32_b32 v83, -1, 0
	v_mbcnt_hi_u32_b32 v83, -1, v83
	s_waitcnt lgkmcnt(0)
	v_add_f32_e32 v81, v81, v82
	v_lshlrev_b32_e32 v83, 2, v83
	v_xor_b32_e32 v83, 16, v83
	s_nop 1
	v_mov_b32_dpp v82, v81 row_shl:4 row_mask:0xf bank_mask:0x5
	v_mov_b32_dpp v82, v81 row_shr:4 row_mask:0xf bank_mask:0xa
	v_mbcnt_lo_u32_b32 v83, -1, 0
	v_mbcnt_hi_u32_b32 v83, -1, v83
	s_waitcnt lgkmcnt(0)
	v_add_f32_e32 v81, v81, v82
	v_lshlrev_b32_e32 v83, 2, v83
	v_xor_b32_e32 v82, 32, v83
	s_nop 1
	v_mov_b32_dpp v82, v81 row_ror:8 row_mask:0xf bank_mask:0xf
	s_and_saveexec_b64 s[8:9], vcc
	s_cbranch_execz .LBB0_500
	s_waitcnt lgkmcnt(0)
	v_add_f32_e32 v81, v81, v82
	v_mul_f32_e32 v81, 0x3db504f3, v81
	ds_write_b32 v80, v81 offset:64
.LBB0_500:
	s_or_b64 exec, exec, s[8:9]
	s_waitcnt lgkmcnt(0)
	v_add_u32_e32 v82, 20, v70
	v_ashrrev_i32_e32 v83, 31, v82
	v_lshlrev_b64 v[82:83], 11, v[82:83]
	v_lshl_add_u64 v[86:87], v[68:69], 0, v[82:83]
	s_nop 0
	v_mbcnt_lo_u32_b32 v81, -1, 0
	v_mbcnt_hi_u32_b32 v81, -1, v81
	s_waitcnt vmcnt(4)
	v_mul_f32_e32 v83, v197, v79
	v_fmac_f32_e32 v83, v196, v71
	v_fmac_f32_e32 v83, v198, v73
	v_fmac_f32_e32 v83, v199, v74
	v_fmac_f32_e32 v83, v200, v75
	v_fmac_f32_e32 v83, v201, v76
	v_lshlrev_b32_e32 v81, 2, v81
	v_fmac_f32_e32 v83, v202, v77
	v_xor_b32_e32 v81, 4, v81
	v_fmac_f32_e32 v83, v203, v78
	s_nop 1
	v_mov_b32_dpp v81, v83 quad_perm:[1,0,3,2] row_mask:0xf bank_mask:0xf
	v_mbcnt_lo_u32_b32 v82, -1, 0
	v_mbcnt_hi_u32_b32 v82, -1, v82
	s_waitcnt lgkmcnt(0)
	v_add_f32_e32 v81, v83, v81
	v_lshlrev_b32_e32 v82, 2, v82
	v_xor_b32_e32 v82, 8, v82
	s_nop 1
	v_mov_b32_dpp v82, v81 quad_perm:[2,3,0,1] row_mask:0xf bank_mask:0xf
	v_mbcnt_lo_u32_b32 v83, -1, 0
	v_mbcnt_hi_u32_b32 v83, -1, v83
	s_waitcnt lgkmcnt(0)
	v_add_f32_e32 v81, v81, v82
	v_lshlrev_b32_e32 v83, 2, v83
	v_xor_b32_e32 v83, 16, v83
	s_nop 1
	v_mov_b32_dpp v82, v81 row_shl:4 row_mask:0xf bank_mask:0x5
	v_mov_b32_dpp v82, v81 row_shr:4 row_mask:0xf bank_mask:0xa
	v_mbcnt_lo_u32_b32 v83, -1, 0
	v_mbcnt_hi_u32_b32 v83, -1, v83
	s_waitcnt lgkmcnt(0)
	v_add_f32_e32 v81, v81, v82
	v_lshlrev_b32_e32 v83, 2, v83
	v_xor_b32_e32 v82, 32, v83
	s_nop 1
	v_mov_b32_dpp v82, v81 row_ror:8 row_mask:0xf bank_mask:0xf
	s_and_saveexec_b64 s[8:9], vcc
	s_cbranch_execz .LBB0_502
	s_waitcnt lgkmcnt(0)
	v_add_f32_e32 v81, v81, v82
	v_mul_f32_e32 v81, 0x3db504f3, v81
	ds_write_b32 v80, v81 offset:80
; __device__ __forceinline__ float shfl_xor_f(float v, int mask) { const int l = lane_fresh(); return __int_as_float(__builtin_amdgcn_ds_bpermute((l ^ mask) << 2, __float_as_int(v))); }
; __device__ __forceinline__ void attn_sample_item(const Params& p, int item, const int wv) {
;     ...
;     for (int it = 0; it < 8; ++it) {
;       const int mm = wid * 32 + it * 4 + ksub;
;       f32x4 k0 = *(const f32x4*)(Kc + (size_t)mm * 512 + dch * 8), k1 = *(const f32x4*)(Kc + (size_t)mm * 512 + dch * 8 + 4);
;       float d = q[0] * k0[0] + q[1] * k0[1] + q[2] * k0[2] + q[3] * k0[3] + q[4] * k1[0] + q[5] * k1[1] + q[6] * k1[2] + q[7] * k1[3];
;       d += shfl_xor_f(d, 1); d += shfl_xor_f(d, 2); d += shfl_xor_f(d, 4); d += shfl_xor_f(d, 8);
;       if (dch == 0) sc_l[mm] = d * 0.08838834764831845f;
;     }
.LBB0_502:
	s_or_b64 exec, exec, s[8:9]
	s_waitcnt lgkmcnt(0)
	v_add_u32_e32 v82, 24, v70
	v_ashrrev_i32_e32 v83, 31, v82
	v_lshlrev_b64 v[82:83], 11, v[82:83]
	v_lshl_add_u64 v[86:87], v[68:69], 0, v[82:83]
	s_nop 0
	v_mbcnt_lo_u32_b32 v81, -1, 0
	v_mbcnt_hi_u32_b32 v81, -1, v81
	s_waitcnt vmcnt(2)
	v_mul_f32_e32 v83, v205, v79
	v_fmac_f32_e32 v83, v204, v71
	v_fmac_f32_e32 v83, v206, v73
	v_fmac_f32_e32 v83, v207, v74
	v_fmac_f32_e32 v83, v208, v75
	v_fmac_f32_e32 v83, v209, v76
	v_lshlrev_b32_e32 v81, 2, v81
	v_fmac_f32_e32 v83, v210, v77
	v_xor_b32_e32 v81, 4, v81
	v_fmac_f32_e32 v83, v211, v78
	s_nop 1
	v_mov_b32_dpp v81, v83 quad_perm:[1,0,3,2] row_mask:0xf bank_mask:0xf
	v_mbcnt_lo_u32_b32 v82, -1, 0
	v_mbcnt_hi_u32_b32 v82, -1, v82
	s_waitcnt lgkmcnt(0)
	v_add_f32_e32 v81, v83, v81
	v_lshlrev_b32_e32 v82, 2, v82
	v_xor_b32_e32 v82, 8, v82
	s_nop 1
	v_mov_b32_dpp v82, v81 quad_perm:[2,3,0,1] row_mask:0xf bank_mask:0xf
	v_mbcnt_lo_u32_b32 v83, -1, 0
	v_mbcnt_hi_u32_b32 v83, -1, v83
	s_waitcnt lgkmcnt(0)
	v_add_f32_e32 v81, v81, v82
	v_lshlrev_b32_e32 v83, 2, v83
	v_xor_b32_e32 v83, 16, v83
	s_nop 1
	v_mov_b32_dpp v82, v81 row_shl:4 row_mask:0xf bank_mask:0x5
	v_mov_b32_dpp v82, v81 row_shr:4 row_mask:0xf bank_mask:0xa
	v_mbcnt_lo_u32_b32 v83, -1, 0
	v_mbcnt_hi_u32_b32 v83, -1, v83
	s_waitcnt lgkmcnt(0)
	v_add_f32_e32 v81, v81, v82
	v_lshlrev_b32_e32 v83, 2, v83
	v_xor_b32_e32 v82, 32, v83
	s_nop 1
	v_mov_b32_dpp v82, v81 row_ror:8 row_mask:0xf bank_mask:0xf
	s_and_saveexec_b64 s[8:9], vcc
	s_cbranch_execz .LBB0_504
	s_waitcnt lgkmcnt(0)
	v_add_f32_e32 v81, v81, v82
	v_mul_f32_e32 v81, 0x3db504f3, v81
	ds_write_b32 v80, v81 offset:96
.LBB0_504:
	s_or_b64 exec, exec, s[8:9]
	s_waitcnt lgkmcnt(0)
	v_add_u32_e32 v82, 28, v70
	v_ashrrev_i32_e32 v83, 31, v82
	v_lshlrev_b64 v[82:83], 11, v[82:83]
	v_lshl_add_u64 v[68:69], v[68:69], 0, v[82:83]
	v_mbcnt_lo_u32_b32 v68, -1, 0
	v_mbcnt_hi_u32_b32 v68, -1, v68
	v_mbcnt_lo_u32_b32 v70, -1, 0
	v_mbcnt_hi_u32_b32 v70, -1, v70
	s_waitcnt vmcnt(0)
	v_mul_f32_e32 v69, v213, v79
	v_fmac_f32_e32 v69, v212, v71
	v_fmac_f32_e32 v69, v214, v73
	v_fmac_f32_e32 v69, v215, v74
	v_fmac_f32_e32 v69, v216, v75
	v_fmac_f32_e32 v69, v217, v76
	v_lshlrev_b32_e32 v68, 2, v68
	v_fmac_f32_e32 v69, v218, v77
	v_xor_b32_e32 v68, 4, v68
	v_fmac_f32_e32 v69, v219, v78
	s_nop 1
	v_mov_b32_dpp v68, v69 quad_perm:[1,0,3,2] row_mask:0xf bank_mask:0xf
	v_lshlrev_b32_e32 v70, 2, v70
	v_xor_b32_e32 v70, 8, v70
	s_waitcnt lgkmcnt(0)
	v_add_f32_e32 v68, v69, v68
	s_nop 1
	v_mov_b32_dpp v69, v68 quad_perm:[2,3,0,1] row_mask:0xf bank_mask:0xf
	v_mbcnt_lo_u32_b32 v70, -1, 0
	v_mbcnt_hi_u32_b32 v70, -1, v70
	s_waitcnt lgkmcnt(0)
	v_add_f32_e32 v68, v68, v69
	v_lshlrev_b32_e32 v70, 2, v70
	v_xor_b32_e32 v70, 16, v70
	s_nop 1
	v_mov_b32_dpp v69, v68 row_shl:4 row_mask:0xf bank_mask:0x5
	v_mov_b32_dpp v69, v68 row_shr:4 row_mask:0xf bank_mask:0xa
	v_mbcnt_lo_u32_b32 v70, -1, 0
	v_mbcnt_hi_u32_b32 v70, -1, v70
	s_waitcnt lgkmcnt(0)
	v_add_f32_e32 v68, v68, v69
	v_lshlrev_b32_e32 v70, 2, v70
	v_xor_b32_e32 v69, 32, v70
	s_nop 1
	v_mov_b32_dpp v69, v68 row_ror:8 row_mask:0xf bank_mask:0xf
	s_and_saveexec_b64 s[8:9], vcc
	s_cbranch_execz .LBB0_506
	s_waitcnt lgkmcnt(0)
	v_add_f32_e32 v68, v68, v69
	v_mul_f32_e32 v68, 0x3db504f3, v68
	ds_write_b32 v80, v68 offset:112
; __device__ __forceinline__ void attn_sample_item(const Params& p, int item, const int wv) {
;     ...
;   __syncthreads();
;   float pv[4];
;   {
;     float mx = -1e30f;
; #pragma unroll
;     for (int i = 0; i < 4; ++i) { pv[i] = sc_l[lane + 64 * i]; mx = fmaxf(mx, pv[i]); }
;     mx = wave_max(mx);
;     float sum = 0.f;
; #pragma unroll
;     for (int i = 0; i < 4; ++i) { pv[i] = __expf(pv[i] - mx); sum += pv[i]; }
;     sum = wave_sum(sum);
;     const float inv = 1.f / sum;
; #pragma unroll
;     for (int i = 0; i < 4; ++i) pv[i] *= inv;
;   }
;   __syncthreads();
;   if (wid == 0) {
; #pragma unroll
;     for (int i = 0; i < 4; ++i) sc_l[lane + 64 * i] = pv[i];
;   }
.LBB0_506:
	s_or_b64 exec, exec, s[8:9]
	v_lshl_add_u32 v68, v72, 2, 16
	s_waitcnt lgkmcnt(0)
	s_barrier
	ds_read2st64_b32 v[70:71], v68 offset1:1
	ds_read2st64_b32 v[72:73], v68 offset0:2 offset1:3
	v_mbcnt_lo_u32_b32 v74, -1, 0
	v_mbcnt_hi_u32_b32 v74, -1, v74
	v_mbcnt_lo_u32_b32 v75, -1, 0
	v_mbcnt_hi_u32_b32 v75, -1, v75
	v_readlane_b32 s8, v251, 58
	s_waitcnt lgkmcnt(1)
	v_max3_f32 v69, v70, s16, v71
	v_lshlrev_b32_e32 v74, 2, v74
	s_waitcnt lgkmcnt(0)
	v_max3_f32 v69, v69, v72, v73
	v_xor_b32_e32 v74, 0x80, v74
	ds_bpermute_b32 v74, v74, v69
	v_readlane_b32 s9, v251, 59
	s_and_b64 vcc, exec, s[8:9]
	s_waitcnt lgkmcnt(0)
	v_max_f32_e32 v74, v74, v74
	v_max_f32_e32 v69, v69, v74
	v_lshlrev_b32_e32 v74, 2, v75
	v_xor_b32_e32 v74, 64, v74
	ds_bpermute_b32 v74, v74, v69
	v_mbcnt_lo_u32_b32 v75, -1, 0
	v_mbcnt_hi_u32_b32 v75, -1, v75
	s_waitcnt lgkmcnt(0)
	v_max_f32_e32 v74, v74, v74
	v_lshlrev_b32_e32 v75, 2, v75
	v_max_f32_e32 v69, v69, v74
	v_xor_b32_e32 v74, 32, v75
	s_nop 1
	v_mov_b32_dpp v74, v69 row_ror:8 row_mask:0xf bank_mask:0xf
	v_mbcnt_lo_u32_b32 v75, -1, 0
	v_mbcnt_hi_u32_b32 v75, -1, v75
	s_waitcnt lgkmcnt(0)
	v_max_f32_e32 v74, v74, v74
	v_lshlrev_b32_e32 v75, 2, v75
	v_xor_b32_e32 v75, 16, v75
	v_max_f32_e32 v69, v69, v74
	s_nop 1
	v_mov_b32_dpp v74, v69 row_shl:4 row_mask:0xf bank_mask:0x5
	v_mov_b32_dpp v74, v69 row_shr:4 row_mask:0xf bank_mask:0xa
	v_mbcnt_lo_u32_b32 v75, -1, 0
	v_mbcnt_hi_u32_b32 v75, -1, v75
	s_waitcnt lgkmcnt(0)
	v_max_f32_e32 v74, v74, v74
	v_lshlrev_b32_e32 v75, 2, v75
	v_xor_b32_e32 v75, 8, v75
	v_max_f32_e32 v69, v69, v74
	s_nop 1
	v_mov_b32_dpp v74, v69 quad_perm:[2,3,0,1] row_mask:0xf bank_mask:0xf
	v_mbcnt_lo_u32_b32 v75, -1, 0
	v_mbcnt_hi_u32_b32 v75, -1, v75
	s_waitcnt lgkmcnt(0)
	v_max_f32_e32 v74, v74, v74
	v_lshlrev_b32_e32 v75, 2, v75
	v_xor_b32_e32 v75, 4, v75
	v_max_f32_e32 v69, v69, v74
	s_nop 1
	v_mov_b32_dpp v74, v69 quad_perm:[1,0,3,2] row_mask:0xf bank_mask:0xf
	s_waitcnt lgkmcnt(0)
	v_max_f32_e32 v74, v74, v74
	v_max_f32_e32 v69, v69, v74
	v_sub_f32_e32 v70, v70, v69
	v_sub_f32_e32 v71, v71, v69
	v_sub_f32_e32 v72, v72, v69
	v_sub_f32_e32 v69, v73, v69
	v_mul_f32_e32 v70, 0x3fb8aa3b, v70
	v_mul_f32_e32 v71, 0x3fb8aa3b, v71
	v_mul_f32_e32 v73, 0x3fb8aa3b, v69
	v_exp_f32_e32 v69, v70
	v_mul_f32_e32 v72, 0x3fb8aa3b, v72
	v_exp_f32_e32 v70, v71
	v_exp_f32_e32 v71, v72
	v_exp_f32_e32 v72, v73
	v_add_f32_e32 v73, 0, v69
	v_add_f32_e32 v73, v70, v73
	v_mbcnt_lo_u32_b32 v74, -1, 0
	v_mbcnt_hi_u32_b32 v74, -1, v74
	v_add_f32_e32 v73, v71, v73
	v_lshlrev_b32_e32 v74, 2, v74
	v_add_f32_e32 v73, v72, v73
	v_xor_b32_e32 v74, 0x80, v74
	ds_bpermute_b32 v74, v74, v73
	v_mbcnt_lo_u32_b32 v75, -1, 0
	v_mbcnt_hi_u32_b32 v75, -1, v75
	s_waitcnt lgkmcnt(0)
	v_add_f32_e32 v73, v73, v74
	v_lshlrev_b32_e32 v74, 2, v75
	v_xor_b32_e32 v74, 64, v74
	ds_bpermute_b32 v74, v74, v73
	v_mbcnt_lo_u32_b32 v75, -1, 0
	v_mbcnt_hi_u32_b32 v75, -1, v75
	s_waitcnt lgkmcnt(0)
	v_add_f32_e32 v73, v73, v74
	v_lshlrev_b32_e32 v75, 2, v75
	v_xor_b32_e32 v74, 32, v75
	s_nop 1
	v_mov_b32_dpp v74, v73 row_ror:8 row_mask:0xf bank_mask:0xf
	v_mbcnt_lo_u32_b32 v75, -1, 0
	v_mbcnt_hi_u32_b32 v75, -1, v75
	s_waitcnt lgkmcnt(0)
	v_add_f32_e32 v73, v73, v74
	v_lshlrev_b32_e32 v75, 2, v75
	v_xor_b32_e32 v75, 16, v75
	s_nop 1
	v_mov_b32_dpp v74, v73 row_shl:4 row_mask:0xf bank_mask:0x5
	v_mov_b32_dpp v74, v73 row_shr:4 row_mask:0xf bank_mask:0xa
	v_mbcnt_lo_u32_b32 v75, -1, 0
	v_mbcnt_hi_u32_b32 v75, -1, v75
	s_waitcnt lgkmcnt(0)
	v_add_f32_e32 v73, v73, v74
	v_lshlrev_b32_e32 v75, 2, v75
	v_xor_b32_e32 v75, 8, v75
	s_nop 1
	v_mov_b32_dpp v74, v73 quad_perm:[2,3,0,1] row_mask:0xf bank_mask:0xf
	v_mbcnt_lo_u32_b32 v75, -1, 0
	v_mbcnt_hi_u32_b32 v75, -1, v75
	s_waitcnt lgkmcnt(0)
	v_lshlrev_b32_e32 v75, 2, v75
	s_barrier
	v_add_f32_e32 v73, v73, v74
	v_xor_b32_e32 v74, 4, v75
	s_nop 1
	v_mov_b32_dpp v74, v73 quad_perm:[1,0,3,2] row_mask:0xf bank_mask:0xf
	s_waitcnt lgkmcnt(0)
	s_cbranch_vccnz .LBB0_508
	v_add_f32_e32 v73, v73, v74
	v_div_scale_f32 v74, s[8:9], v73, v73, 1.0
	v_rcp_f32_e32 v75, v74
	v_div_scale_f32 v76, vcc, 1.0, v73, 1.0
	v_fma_f32 v77, -v74, v75, 1.0
	v_fmac_f32_e32 v75, v77, v75
	v_mul_f32_e32 v77, v76, v75
	v_fma_f32 v78, -v74, v77, v76
	v_fmac_f32_e32 v77, v78, v75
	v_fma_f32 v74, -v74, v77, v76
	v_div_fmas_f32 v74, v74, v75, v77
	v_div_fixup_f32 v73, v74, v73, 1.0
	v_mul_f32_e32 v70, v70, v73
	v_mul_f32_e32 v69, v69, v73
	v_mul_f32_e32 v72, v72, v73
	v_mul_f32_e32 v71, v71, v73
	ds_write2st64_b32 v68, v69, v70 offset1:1
	ds_write2st64_b32 v68, v71, v72 offset0:2 offset1:3

; __device__ __forceinline__ float shfl_xor_f(float v, int mask) { const int l = lane_fresh(); return __int_as_float(__builtin_amdgcn_ds_bpermute((l ^ mask) << 2, __float_as_int(v))); }
; __device__ __forceinline__ void attn_sample_item(const Params& p, int item, const int wv) {
;     ...
;     for (int it = 0; it < 8; ++it) {
;       const int mm = wid * 32 + it * 4 + ksub;
;       f32x4 k0 = *(const f32x4*)(Kc + (size_t)mm * 512 + dch * 8), k1 = *(const f32x4*)(Kc + (size_t)mm * 512 + dch * 8 + 4);
;       float d = q[0] * k0[0] + q[1] * k0[1] + q[2] * k0[2] + q[3] * k0[3] + q[4] * k1[0] + q[5] * k1[1] + q[6] * k1[2] + q[7] * k1[3];
;       d += shfl_xor_f(d, 1); d += shfl_xor_f(d, 2); d += shfl_xor_f(d, 4); d += shfl_xor_f(d, 8);
;       if (dch == 0) sc_l[mm] = d * 0.08838834764831845f;
;     }
.LBB0_514:
	s_or_b64 exec, exec, s[8:9]
	v_add_u32_e32 v80, 4, v70
	s_waitcnt lgkmcnt(0)
	v_ashrrev_i32_e32 v81, 31, v80
	v_lshlrev_b64 v[80:81], 11, v[80:81]
	v_lshl_add_u64 v[84:85], v[68:69], 0, v[80:81]
	s_nop 0
	v_mbcnt_lo_u32_b32 v88, -1, 0
	v_mbcnt_hi_u32_b32 v88, -1, v88
	s_waitcnt vmcnt(12)
	v_mul_f32_e32 v81, v165, v78
	v_fmac_f32_e32 v81, v164, v67
	v_fmac_f32_e32 v81, v166, v71
	v_fmac_f32_e32 v81, v167, v73
	v_fmac_f32_e32 v81, v168, v74
	v_fmac_f32_e32 v81, v169, v75
	v_lshlrev_b32_e32 v88, 2, v88
	v_fmac_f32_e32 v81, v170, v76
	v_xor_b32_e32 v88, 4, v88
	v_fmac_f32_e32 v81, v171, v77
	s_nop 1
	v_mov_b32_dpp v80, v81 quad_perm:[1,0,3,2] row_mask:0xf bank_mask:0xf
	v_mbcnt_lo_u32_b32 v82, -1, 0
	v_mbcnt_hi_u32_b32 v82, -1, v82
	s_waitcnt lgkmcnt(0)
	v_add_f32_e32 v80, v81, v80
	v_lshlrev_b32_e32 v82, 2, v82
	v_xor_b32_e32 v82, 8, v82
	s_nop 1
	v_mov_b32_dpp v81, v80 quad_perm:[2,3,0,1] row_mask:0xf bank_mask:0xf
	v_mbcnt_lo_u32_b32 v82, -1, 0
	v_mbcnt_hi_u32_b32 v82, -1, v82
	s_waitcnt lgkmcnt(0)
	v_add_f32_e32 v80, v80, v81
	v_lshlrev_b32_e32 v82, 2, v82
	v_xor_b32_e32 v82, 16, v82
	s_nop 1
	v_mov_b32_dpp v81, v80 row_shl:4 row_mask:0xf bank_mask:0x5
	v_mov_b32_dpp v81, v80 row_shr:4 row_mask:0xf bank_mask:0xa
	v_mbcnt_lo_u32_b32 v82, -1, 0
	v_mbcnt_hi_u32_b32 v82, -1, v82
	s_waitcnt lgkmcnt(0)
	v_add_f32_e32 v80, v80, v81
	v_lshlrev_b32_e32 v82, 2, v82
	v_xor_b32_e32 v81, 32, v82
	s_nop 1
	v_mov_b32_dpp v81, v80 row_ror:8 row_mask:0xf bank_mask:0xf
	s_and_saveexec_b64 s[8:9], vcc
	s_cbranch_execz .LBB0_516
	s_waitcnt lgkmcnt(0)
	v_add_f32_e32 v80, v80, v81
	v_mul_f32_e32 v80, 0x3db504f3, v80
	ds_write_b32 v79, v80 offset:16
.LBB0_516:
	s_or_b64 exec, exec, s[8:9]
	v_add_u32_e32 v80, 8, v70
	s_waitcnt lgkmcnt(0)
	v_ashrrev_i32_e32 v81, 31, v80
	v_lshlrev_b64 v[80:81], 11, v[80:81]
	v_lshl_add_u64 v[84:85], v[68:69], 0, v[80:81]
	s_nop 0
	v_mbcnt_lo_u32_b32 v88, -1, 0
	v_mbcnt_hi_u32_b32 v88, -1, v88
	s_waitcnt vmcnt(10)
	v_mul_f32_e32 v81, v173, v78
	v_fmac_f32_e32 v81, v172, v67
	v_fmac_f32_e32 v81, v174, v71
	v_fmac_f32_e32 v81, v175, v73
	v_fmac_f32_e32 v81, v176, v74
	v_fmac_f32_e32 v81, v177, v75
	v_lshlrev_b32_e32 v88, 2, v88
	v_fmac_f32_e32 v81, v178, v76
	v_xor_b32_e32 v88, 4, v88
	v_fmac_f32_e32 v81, v179, v77
	s_nop 1
	v_mov_b32_dpp v80, v81 quad_perm:[1,0,3,2] row_mask:0xf bank_mask:0xf
	v_mbcnt_lo_u32_b32 v82, -1, 0
	v_mbcnt_hi_u32_b32 v82, -1, v82
	s_waitcnt lgkmcnt(0)
	v_add_f32_e32 v80, v81, v80
	v_lshlrev_b32_e32 v82, 2, v82
	v_xor_b32_e32 v82, 8, v82
	s_nop 1
	v_mov_b32_dpp v81, v80 quad_perm:[2,3,0,1] row_mask:0xf bank_mask:0xf
	v_mbcnt_lo_u32_b32 v82, -1, 0
	v_mbcnt_hi_u32_b32 v82, -1, v82
	s_waitcnt lgkmcnt(0)
	v_add_f32_e32 v80, v80, v81
	v_lshlrev_b32_e32 v82, 2, v82
	v_xor_b32_e32 v82, 16, v82
	s_nop 1
	v_mov_b32_dpp v81, v80 row_shl:4 row_mask:0xf bank_mask:0x5
	v_mov_b32_dpp v81, v80 row_shr:4 row_mask:0xf bank_mask:0xa
	v_mbcnt_lo_u32_b32 v82, -1, 0
	v_mbcnt_hi_u32_b32 v82, -1, v82
	s_waitcnt lgkmcnt(0)
	v_add_f32_e32 v80, v80, v81
	v_lshlrev_b32_e32 v82, 2, v82
	v_xor_b32_e32 v81, 32, v82
	s_nop 1
	v_mov_b32_dpp v81, v80 row_ror:8 row_mask:0xf bank_mask:0xf
	s_and_saveexec_b64 s[8:9], vcc
	s_cbranch_execz .LBB0_518
	s_waitcnt lgkmcnt(0)
	v_add_f32_e32 v80, v80, v81
	v_mul_f32_e32 v80, 0x3db504f3, v80
	ds_write_b32 v79, v80 offset:32
.LBB0_518:
	s_or_b64 exec, exec, s[8:9]
	v_add_u32_e32 v80, 12, v70
	s_waitcnt lgkmcnt(0)
	v_ashrrev_i32_e32 v81, 31, v80
	v_lshlrev_b64 v[80:81], 11, v[80:81]
	v_lshl_add_u64 v[84:85], v[68:69], 0, v[80:81]
	s_nop 0
	v_mbcnt_lo_u32_b32 v88, -1, 0
	v_mbcnt_hi_u32_b32 v88, -1, v88
	s_waitcnt vmcnt(8)
	v_mul_f32_e32 v81, v181, v78
	v_fmac_f32_e32 v81, v180, v67
	v_fmac_f32_e32 v81, v182, v71
	v_fmac_f32_e32 v81, v183, v73
	v_fmac_f32_e32 v81, v184, v74
	v_fmac_f32_e32 v81, v185, v75
	v_lshlrev_b32_e32 v88, 2, v88
	v_fmac_f32_e32 v81, v186, v76
	v_xor_b32_e32 v88, 4, v88
	v_fmac_f32_e32 v81, v187, v77
	s_nop 1
	v_mov_b32_dpp v80, v81 quad_perm:[1,0,3,2] row_mask:0xf bank_mask:0xf
	v_mbcnt_lo_u32_b32 v82, -1, 0
	v_mbcnt_hi_u32_b32 v82, -1, v82
	s_waitcnt lgkmcnt(0)
	v_add_f32_e32 v80, v81, v80
	v_lshlrev_b32_e32 v82, 2, v82
	v_xor_b32_e32 v82, 8, v82
	s_nop 1
	v_mov_b32_dpp v81, v80 quad_perm:[2,3,0,1] row_mask:0xf bank_mask:0xf
	v_mbcnt_lo_u32_b32 v82, -1, 0
	v_mbcnt_hi_u32_b32 v82, -1, v82
	s_waitcnt lgkmcnt(0)
	v_add_f32_e32 v80, v80, v81
	v_lshlrev_b32_e32 v82, 2, v82
	v_xor_b32_e32 v82, 16, v82
	s_nop 1
	v_mov_b32_dpp v81, v80 row_shl:4 row_mask:0xf bank_mask:0x5
	v_mov_b32_dpp v81, v80 row_shr:4 row_mask:0xf bank_mask:0xa
	v_mbcnt_lo_u32_b32 v82, -1, 0
	v_mbcnt_hi_u32_b32 v82, -1, v82
	s_waitcnt lgkmcnt(0)
	v_add_f32_e32 v80, v80, v81
	v_lshlrev_b32_e32 v82, 2, v82
	v_xor_b32_e32 v81, 32, v82
	s_nop 1
	v_mov_b32_dpp v81, v80 row_ror:8 row_mask:0xf bank_mask:0xf
	s_and_saveexec_b64 s[8:9], vcc
	s_cbranch_execz .LBB0_520
	s_waitcnt lgkmcnt(0)
	v_add_f32_e32 v80, v80, v81
	v_mul_f32_e32 v80, 0x3db504f3, v80
	ds_write_b32 v79, v80 offset:48
; __device__ __forceinline__ float shfl_xor_f(float v, int mask) { const int l = lane_fresh(); return __int_as_float(__builtin_amdgcn_ds_bpermute((l ^ mask) << 2, __float_as_int(v))); }
; __device__ __forceinline__ void attn_sample_item(const Params& p, int item, const int wv) {
;     ...
;     for (int it = 0; it < 8; ++it) {
;       const int mm = wid * 32 + it * 4 + ksub;
;       f32x4 k0 = *(const f32x4*)(Kc + (size_t)mm * 512 + dch * 8), k1 = *(const f32x4*)(Kc + (size_t)mm * 512 + dch * 8 + 4);
;       float d = q[0] * k0[0] + q[1] * k0[1] + q[2] * k0[2] + q[3] * k0[3] + q[4] * k1[0] + q[5] * k1[1] + q[6] * k1[2] + q[7] * k1[3];
;       d += shfl_xor_f(d, 1); d += shfl_xor_f(d, 2); d += shfl_xor_f(d, 4); d += shfl_xor_f(d, 8);
;       if (dch == 0) sc_l[mm] = d * 0.08838834764831845f;
;     }
.LBB0_520:
	s_or_b64 exec, exec, s[8:9]
	v_add_u32_e32 v80, 16, v70
	s_waitcnt lgkmcnt(0)
	v_ashrrev_i32_e32 v81, 31, v80
	v_lshlrev_b64 v[80:81], 11, v[80:81]
	v_lshl_add_u64 v[84:85], v[68:69], 0, v[80:81]
	s_nop 0
	v_mbcnt_lo_u32_b32 v88, -1, 0
	v_mbcnt_hi_u32_b32 v88, -1, v88
	s_waitcnt vmcnt(6)
	v_mul_f32_e32 v81, v189, v78
	v_fmac_f32_e32 v81, v188, v67
	v_fmac_f32_e32 v81, v190, v71
	v_fmac_f32_e32 v81, v191, v73
	v_fmac_f32_e32 v81, v192, v74
	v_fmac_f32_e32 v81, v193, v75
	v_lshlrev_b32_e32 v88, 2, v88
	v_fmac_f32_e32 v81, v194, v76
	v_xor_b32_e32 v88, 4, v88
	v_fmac_f32_e32 v81, v195, v77
	s_nop 1
	v_mov_b32_dpp v80, v81 quad_perm:[1,0,3,2] row_mask:0xf bank_mask:0xf
	v_mbcnt_lo_u32_b32 v82, -1, 0
	v_mbcnt_hi_u32_b32 v82, -1, v82
	s_waitcnt lgkmcnt(0)
	v_add_f32_e32 v80, v81, v80
	v_lshlrev_b32_e32 v82, 2, v82
	v_xor_b32_e32 v82, 8, v82
	s_nop 1
	v_mov_b32_dpp v81, v80 quad_perm:[2,3,0,1] row_mask:0xf bank_mask:0xf
	v_mbcnt_lo_u32_b32 v82, -1, 0
	v_mbcnt_hi_u32_b32 v82, -1, v82
	s_waitcnt lgkmcnt(0)
	v_add_f32_e32 v80, v80, v81
	v_lshlrev_b32_e32 v82, 2, v82
	v_xor_b32_e32 v82, 16, v82
	s_nop 1
	v_mov_b32_dpp v81, v80 row_shl:4 row_mask:0xf bank_mask:0x5
	v_mov_b32_dpp v81, v80 row_shr:4 row_mask:0xf bank_mask:0xa
	v_mbcnt_lo_u32_b32 v82, -1, 0
	v_mbcnt_hi_u32_b32 v82, -1, v82
	s_waitcnt lgkmcnt(0)
	v_add_f32_e32 v80, v80, v81
	v_lshlrev_b32_e32 v82, 2, v82
	v_xor_b32_e32 v81, 32, v82
	s_nop 1
	v_mov_b32_dpp v81, v80 row_ror:8 row_mask:0xf bank_mask:0xf
	s_and_saveexec_b64 s[8:9], vcc
	s_cbranch_execz .LBB0_522
	s_waitcnt lgkmcnt(0)
	v_add_f32_e32 v80, v80, v81
	v_mul_f32_e32 v80, 0x3db504f3, v80
	ds_write_b32 v79, v80 offset:64
.LBB0_522:
	s_or_b64 exec, exec, s[8:9]
	v_add_u32_e32 v80, 20, v70
	s_waitcnt lgkmcnt(0)
	v_ashrrev_i32_e32 v81, 31, v80
	v_lshlrev_b64 v[80:81], 11, v[80:81]
	v_lshl_add_u64 v[84:85], v[68:69], 0, v[80:81]
	s_nop 0
	v_mbcnt_lo_u32_b32 v88, -1, 0
	v_mbcnt_hi_u32_b32 v88, -1, v88
	s_waitcnt vmcnt(4)
	v_mul_f32_e32 v81, v197, v78
	v_fmac_f32_e32 v81, v196, v67
	v_fmac_f32_e32 v81, v198, v71
	v_fmac_f32_e32 v81, v199, v73
	v_fmac_f32_e32 v81, v200, v74
	v_fmac_f32_e32 v81, v201, v75
	v_lshlrev_b32_e32 v88, 2, v88
	v_fmac_f32_e32 v81, v202, v76
	v_xor_b32_e32 v88, 4, v88
	v_fmac_f32_e32 v81, v203, v77
	s_nop 1
	v_mov_b32_dpp v80, v81 quad_perm:[1,0,3,2] row_mask:0xf bank_mask:0xf
	v_mbcnt_lo_u32_b32 v82, -1, 0
	v_mbcnt_hi_u32_b32 v82, -1, v82
	s_waitcnt lgkmcnt(0)
	v_add_f32_e32 v80, v81, v80
	v_lshlrev_b32_e32 v82, 2, v82
	v_xor_b32_e32 v82, 8, v82
	s_nop 1
	v_mov_b32_dpp v81, v80 quad_perm:[2,3,0,1] row_mask:0xf bank_mask:0xf
	v_mbcnt_lo_u32_b32 v82, -1, 0
	v_mbcnt_hi_u32_b32 v82, -1, v82
	s_waitcnt lgkmcnt(0)
	v_add_f32_e32 v80, v80, v81
	v_lshlrev_b32_e32 v82, 2, v82
	v_xor_b32_e32 v82, 16, v82
	s_nop 1
	v_mov_b32_dpp v81, v80 row_shl:4 row_mask:0xf bank_mask:0x5
	v_mov_b32_dpp v81, v80 row_shr:4 row_mask:0xf bank_mask:0xa
	v_mbcnt_lo_u32_b32 v82, -1, 0
	v_mbcnt_hi_u32_b32 v82, -1, v82
	s_waitcnt lgkmcnt(0)
	v_add_f32_e32 v80, v80, v81
	v_lshlrev_b32_e32 v82, 2, v82
	v_xor_b32_e32 v81, 32, v82
	s_nop 1
	v_mov_b32_dpp v81, v80 row_ror:8 row_mask:0xf bank_mask:0xf
	s_and_saveexec_b64 s[8:9], vcc
	s_cbranch_execz .LBB0_524
	s_waitcnt lgkmcnt(0)
	v_add_f32_e32 v80, v80, v81
	v_mul_f32_e32 v80, 0x3db504f3, v80
	ds_write_b32 v79, v80 offset:80
.LBB0_524:
	s_or_b64 exec, exec, s[8:9]
	v_add_u32_e32 v80, 24, v70
	s_waitcnt lgkmcnt(0)
	v_ashrrev_i32_e32 v81, 31, v80
	v_lshlrev_b64 v[80:81], 11, v[80:81]
	v_lshl_add_u64 v[84:85], v[68:69], 0, v[80:81]
	s_nop 0
	v_mbcnt_lo_u32_b32 v88, -1, 0
	v_mbcnt_hi_u32_b32 v88, -1, v88
	s_waitcnt vmcnt(2)
	v_mul_f32_e32 v81, v205, v78
	v_fmac_f32_e32 v81, v204, v67
	v_fmac_f32_e32 v81, v206, v71
	v_fmac_f32_e32 v81, v207, v73
	v_fmac_f32_e32 v81, v208, v74
	v_fmac_f32_e32 v81, v209, v75
	v_lshlrev_b32_e32 v88, 2, v88
	v_fmac_f32_e32 v81, v210, v76
	v_xor_b32_e32 v88, 4, v88
	v_fmac_f32_e32 v81, v211, v77
	s_nop 1
	v_mov_b32_dpp v80, v81 quad_perm:[1,0,3,2] row_mask:0xf bank_mask:0xf
	v_mbcnt_lo_u32_b32 v82, -1, 0
	v_mbcnt_hi_u32_b32 v82, -1, v82
	s_waitcnt lgkmcnt(0)
	v_add_f32_e32 v80, v81, v80
	v_lshlrev_b32_e32 v82, 2, v82
	v_xor_b32_e32 v82, 8, v82
	s_nop 1
	v_mov_b32_dpp v81, v80 quad_perm:[2,3,0,1] row_mask:0xf bank_mask:0xf
	v_mbcnt_lo_u32_b32 v82, -1, 0
	v_mbcnt_hi_u32_b32 v82, -1, v82
	s_waitcnt lgkmcnt(0)
	v_add_f32_e32 v80, v80, v81
	v_lshlrev_b32_e32 v82, 2, v82
	v_xor_b32_e32 v82, 16, v82
	s_nop 1
	v_mov_b32_dpp v81, v80 row_shl:4 row_mask:0xf bank_mask:0x5
	v_mov_b32_dpp v81, v80 row_shr:4 row_mask:0xf bank_mask:0xa
	v_mbcnt_lo_u32_b32 v82, -1, 0
	v_mbcnt_hi_u32_b32 v82, -1, v82
	s_waitcnt lgkmcnt(0)
	v_add_f32_e32 v80, v80, v81
	v_lshlrev_b32_e32 v82, 2, v82
	v_xor_b32_e32 v81, 32, v82
	s_nop 1
	v_mov_b32_dpp v81, v80 row_ror:8 row_mask:0xf bank_mask:0xf
	s_and_saveexec_b64 s[8:9], vcc
	s_cbranch_execz .LBB0_526
	s_waitcnt lgkmcnt(0)
	v_add_f32_e32 v80, v80, v81
	v_mul_f32_e32 v80, 0x3db504f3, v80
	ds_write_b32 v79, v80 offset:96
; __device__ __forceinline__ float shfl_xor_f(float v, int mask) { const int l = lane_fresh(); return __int_as_float(__builtin_amdgcn_ds_bpermute((l ^ mask) << 2, __float_as_int(v))); }
; __device__ __forceinline__ void attn_sample_item(const Params& p, int item, const int wv) {
;     ...
;     for (int it = 0; it < 8; ++it) {
;       const int mm = wid * 32 + it * 4 + ksub;
;       f32x4 k0 = *(const f32x4*)(Kc + (size_t)mm * 512 + dch * 8), k1 = *(const f32x4*)(Kc + (size_t)mm * 512 + dch * 8 + 4);
;       float d = q[0] * k0[0] + q[1] * k0[1] + q[2] * k0[2] + q[3] * k0[3] + q[4] * k1[0] + q[5] * k1[1] + q[6] * k1[2] + q[7] * k1[3];
;       d += shfl_xor_f(d, 1); d += shfl_xor_f(d, 2); d += shfl_xor_f(d, 4); d += shfl_xor_f(d, 8);
;       if (dch == 0) sc_l[mm] = d * 0.08838834764831845f;
;     }
;   }
;   __syncthreads();
;   float pv[4];
;   {
;     float mx = -1e30f;
; #pragma unroll
;     for (int i = 0; i < 4; ++i) { pv[i] = sc_l[lane + 64 * i]; mx = fmaxf(mx, pv[i]); }
;     mx = wave_max(mx);
;     float sum = 0.f;
; #pragma unroll
;     for (int i = 0; i < 4; ++i) { pv[i] = __expf(pv[i] - mx); sum += pv[i]; }
;     sum = wave_sum(sum);
;     const float inv = 1.f / sum;
; #pragma unroll
;     for (int i = 0; i < 4; ++i) pv[i] *= inv;
;   }
;   __syncthreads();
;   if (wid == 0) {
; #pragma unroll
;     for (int i = 0; i < 4; ++i) sc_l[lane + 64 * i] = pv[i];
;   }
.LBB0_526:
	s_or_b64 exec, exec, s[8:9]
	v_add_u32_e32 v80, 28, v70
	s_waitcnt lgkmcnt(0)
	v_ashrrev_i32_e32 v81, 31, v80
	v_lshlrev_b64 v[80:81], 11, v[80:81]
	v_lshl_add_u64 v[68:69], v[68:69], 0, v[80:81]
	v_mbcnt_lo_u32_b32 v68, -1, 0
	v_mbcnt_hi_u32_b32 v68, -1, v68
	s_waitcnt vmcnt(0)
	v_mul_f32_e32 v69, v213, v78
	v_fmac_f32_e32 v69, v212, v67
	v_fmac_f32_e32 v69, v214, v71
	v_fmac_f32_e32 v69, v215, v73
	v_fmac_f32_e32 v69, v216, v74
	v_fmac_f32_e32 v69, v217, v75
	v_lshlrev_b32_e32 v68, 2, v68
	v_fmac_f32_e32 v69, v218, v76
	v_xor_b32_e32 v68, 4, v68
	v_fmac_f32_e32 v69, v219, v77
	s_nop 1
	v_mov_b32_dpp v67, v69 quad_perm:[1,0,3,2] row_mask:0xf bank_mask:0xf
	v_mbcnt_lo_u32_b32 v68, -1, 0
	v_mbcnt_hi_u32_b32 v68, -1, v68
	s_waitcnt lgkmcnt(0)
	v_add_f32_e32 v67, v69, v67
	v_lshlrev_b32_e32 v68, 2, v68
	v_xor_b32_e32 v68, 8, v68
	s_nop 1
	v_mov_b32_dpp v68, v67 quad_perm:[2,3,0,1] row_mask:0xf bank_mask:0xf
	v_mbcnt_lo_u32_b32 v69, -1, 0
	v_mbcnt_hi_u32_b32 v69, -1, v69
	s_waitcnt lgkmcnt(0)
	v_add_f32_e32 v67, v67, v68
	v_lshlrev_b32_e32 v69, 2, v69
	v_xor_b32_e32 v69, 16, v69
	s_nop 1
	v_mov_b32_dpp v68, v67 row_shl:4 row_mask:0xf bank_mask:0x5
	v_mov_b32_dpp v68, v67 row_shr:4 row_mask:0xf bank_mask:0xa
	v_mbcnt_lo_u32_b32 v69, -1, 0
	v_mbcnt_hi_u32_b32 v69, -1, v69
	s_waitcnt lgkmcnt(0)
	v_add_f32_e32 v67, v67, v68
	v_lshlrev_b32_e32 v69, 2, v69
	v_xor_b32_e32 v68, 32, v69
	s_nop 1
	v_mov_b32_dpp v68, v67 row_ror:8 row_mask:0xf bank_mask:0xf
	s_and_saveexec_b64 s[8:9], vcc
	s_cbranch_execz .LBB0_528
	s_waitcnt lgkmcnt(0)
	v_add_f32_e32 v67, v67, v68
	v_mul_f32_e32 v67, 0x3db504f3, v67
	ds_write_b32 v79, v67 offset:112
.LBB0_528:
	s_or_b64 exec, exec, s[8:9]
	v_lshl_add_u32 v67, v72, 2, 16
	s_waitcnt lgkmcnt(0)
	s_barrier
	ds_read2st64_b32 v[68:69], v67 offset1:1
	ds_read2st64_b32 v[70:71], v67 offset0:2 offset1:3
	s_mov_b32 s7, 0xf149f2ca
	v_mbcnt_lo_u32_b32 v73, -1, 0
	v_mbcnt_hi_u32_b32 v73, -1, v73
	v_readlane_b32 s8, v251, 58
	s_waitcnt lgkmcnt(1)
	v_max3_f32 v72, v68, s7, v69
	v_lshlrev_b32_e32 v73, 2, v73
	s_waitcnt lgkmcnt(0)
	v_max3_f32 v72, v72, v70, v71
	v_xor_b32_e32 v73, 0x80, v73
	ds_bpermute_b32 v73, v73, v72
	v_readlane_b32 s9, v251, 59
	s_movk_i32 s7, 0x80
	s_and_b64 vcc, exec, s[8:9]
	s_waitcnt lgkmcnt(0)
	v_max_f32_e32 v73, v73, v73
	v_max_f32_e32 v72, v72, v73
	v_mbcnt_lo_u32_b32 v73, -1, 0
	v_mbcnt_hi_u32_b32 v73, -1, v73
	v_mbcnt_lo_u32_b32 v74, -1, 0
	v_mbcnt_hi_u32_b32 v74, -1, v74
	s_nop 0
	v_lshlrev_b32_e32 v73, 2, v73
	v_xor_b32_e32 v73, 64, v73
	ds_bpermute_b32 v73, v73, v72
	s_waitcnt lgkmcnt(0)
	v_max_f32_e32 v73, v73, v73
	v_max_f32_e32 v72, v72, v73
	v_lshlrev_b32_e32 v73, 2, v74
	v_xor_b32_e32 v73, 32, v73
	s_nop 1
	v_mov_b32_dpp v73, v72 row_ror:8 row_mask:0xf bank_mask:0xf
	v_mbcnt_lo_u32_b32 v74, -1, 0
	v_mbcnt_hi_u32_b32 v74, -1, v74
	s_waitcnt lgkmcnt(0)
	v_max_f32_e32 v73, v73, v73
	v_lshlrev_b32_e32 v74, 2, v74
	v_max_f32_e32 v72, v72, v73
	v_xor_b32_e32 v73, 16, v74
	s_nop 1
	v_mov_b32_dpp v73, v72 row_shl:4 row_mask:0xf bank_mask:0x5
	v_mov_b32_dpp v73, v72 row_shr:4 row_mask:0xf bank_mask:0xa
	v_mbcnt_lo_u32_b32 v74, -1, 0
	v_mbcnt_hi_u32_b32 v74, -1, v74
	s_waitcnt lgkmcnt(0)
	v_max_f32_e32 v73, v73, v73
	v_lshlrev_b32_e32 v74, 2, v74
	v_xor_b32_e32 v74, 8, v74
	v_max_f32_e32 v72, v72, v73
	s_nop 1
	v_mov_b32_dpp v73, v72 quad_perm:[2,3,0,1] row_mask:0xf bank_mask:0xf
	v_mbcnt_lo_u32_b32 v74, -1, 0
	v_mbcnt_hi_u32_b32 v74, -1, v74
	s_waitcnt lgkmcnt(0)
	v_max_f32_e32 v73, v73, v73
	v_lshlrev_b32_e32 v74, 2, v74
	v_xor_b32_e32 v74, 4, v74
	v_max_f32_e32 v72, v72, v73
	s_nop 1
	v_mov_b32_dpp v73, v72 quad_perm:[1,0,3,2] row_mask:0xf bank_mask:0xf
	s_waitcnt lgkmcnt(0)
	v_max_f32_e32 v73, v73, v73
	v_max_f32_e32 v72, v72, v73
	v_sub_f32_e32 v68, v68, v72
	v_sub_f32_e32 v69, v69, v72
	v_mul_f32_e32 v68, 0x3fb8aa3b, v68
	v_sub_f32_e32 v70, v70, v72
	v_mul_f32_e32 v69, 0x3fb8aa3b, v69
	v_exp_f32_e32 v68, v68
	v_mul_f32_e32 v70, 0x3fb8aa3b, v70
	v_exp_f32_e32 v69, v69
	v_sub_f32_e32 v71, v71, v72
	v_exp_f32_e32 v70, v70
	v_mul_f32_e32 v71, 0x3fb8aa3b, v71
	v_exp_f32_e32 v71, v71
	v_add_f32_e32 v72, 0, v68
	v_add_f32_e32 v72, v69, v72
	v_mbcnt_lo_u32_b32 v73, -1, 0
	v_mbcnt_hi_u32_b32 v73, -1, v73
	v_add_f32_e32 v72, v70, v72
	v_lshlrev_b32_e32 v73, 2, v73
	v_add_f32_e32 v72, v71, v72
	v_xor_b32_e32 v73, 0x80, v73
	ds_bpermute_b32 v73, v73, v72
	s_waitcnt lgkmcnt(0)
	v_add_f32_e32 v72, v72, v73
	v_mbcnt_lo_u32_b32 v73, -1, 0
	v_mbcnt_hi_u32_b32 v73, -1, v73
	v_mbcnt_lo_u32_b32 v74, -1, 0
	v_mbcnt_hi_u32_b32 v74, -1, v74
	s_nop 0
	v_lshlrev_b32_e32 v73, 2, v73
	v_xor_b32_e32 v73, 64, v73
	ds_bpermute_b32 v73, v73, v72
	s_waitcnt lgkmcnt(0)
	v_add_f32_e32 v72, v72, v73
	v_lshlrev_b32_e32 v73, 2, v74
	v_xor_b32_e32 v73, 32, v73
	s_nop 1
	v_mov_b32_dpp v73, v72 row_ror:8 row_mask:0xf bank_mask:0xf
	v_mbcnt_lo_u32_b32 v74, -1, 0
	v_mbcnt_hi_u32_b32 v74, -1, v74
	s_waitcnt lgkmcnt(0)
	v_add_f32_e32 v72, v72, v73
	v_lshlrev_b32_e32 v74, 2, v74
	v_xor_b32_e32 v73, 16, v74
	s_nop 1
	v_mov_b32_dpp v73, v72 row_shl:4 row_mask:0xf bank_mask:0x5
	v_mov_b32_dpp v73, v72 row_shr:4 row_mask:0xf bank_mask:0xa
	v_mbcnt_lo_u32_b32 v74, -1, 0
	v_mbcnt_hi_u32_b32 v74, -1, v74
	s_waitcnt lgkmcnt(0)
	v_add_f32_e32 v72, v72, v73
	v_lshlrev_b32_e32 v74, 2, v74
	v_xor_b32_e32 v74, 8, v74
	s_nop 1
	v_mov_b32_dpp v73, v72 quad_perm:[2,3,0,1] row_mask:0xf bank_mask:0xf
	v_mbcnt_lo_u32_b32 v74, -1, 0
	v_mbcnt_hi_u32_b32 v74, -1, v74
	s_waitcnt lgkmcnt(0)
	v_lshlrev_b32_e32 v74, 2, v74
	s_barrier
	v_add_f32_e32 v72, v72, v73
	v_xor_b32_e32 v73, 4, v74
	s_nop 1
	v_mov_b32_dpp v73, v72 quad_perm:[1,0,3,2] row_mask:0xf bank_mask:0xf
	s_waitcnt lgkmcnt(0)
	s_cbranch_vccnz .LBB0_530
	v_add_f32_e32 v72, v72, v73
	v_div_scale_f32 v73, s[8:9], v72, v72, 1.0
	v_rcp_f32_e32 v74, v73
	v_div_scale_f32 v75, vcc, 1.0, v72, 1.0
	v_fma_f32 v76, -v73, v74, 1.0
	v_fmac_f32_e32 v74, v76, v74
	v_mul_f32_e32 v76, v75, v74
	v_fma_f32 v77, -v73, v76, v75
	v_fmac_f32_e32 v76, v77, v74
	v_fma_f32 v73, -v73, v76, v75
	v_div_fmas_f32 v73, v73, v74, v76
	v_div_fixup_f32 v72, v73, v72, 1.0
	v_mul_f32_e32 v69, v69, v72
	v_mul_f32_e32 v68, v68, v72
	v_mul_f32_e32 v71, v71, v72
	v_mul_f32_e32 v70, v70, v72
	ds_write2st64_b32 v67, v68, v69 offset1:1
	ds_write2st64_b32 v67, v70, v71 offset0:2 offset1:3

; __device__ __forceinline__ float bflo(unsigned w) { return __uint_as_float(w << 16); }
; __device__ __forceinline__ float bfhi(unsigned w) { return __uint_as_float(w & 0xffff0000u); }
; __device__ __forceinline__ void gmlp_prompt_item(const Params& p, int item, const int wv) {
;     ...
;     const int row = tid >> 2, qq = tid & 3;
;     const u16* vrow = UV + (size_t)(t0 + row) * 1024 + 512;
;     float sm = 0.f, sq = 0.f;
; #pragma unroll
;     for (int i = 0; i < 16; ++i) {
;       u32x4 w = *(const u32x4*)(vrow + qq * 128 + i * 8);
;       float f[8] = {bflo(w.x), bfhi(w.x), bflo(w.y), bfhi(w.y), bflo(w.z), bfhi(w.z), bflo(w.w), bfhi(w.w)};
; #pragma unroll
;       for (int e = 0; e < 8; ++e) { sm += f[e]; sq += f[e] * f[e]; }
;     }
.LBB0_552:
	v_mbcnt_lo_u32_b32 v72, -1, 0
	v_mbcnt_hi_u32_b32 v72, -1, v72
	s_lshl_b32 s16, s57, 6
	v_add_u32_e32 v0, s82, v72
	s_and_b32 s16, s16, 0x3f80
	v_ashrrev_i32_e32 v13, 2, v0
	v_add_u32_e32 v0, s16, v13
	s_waitcnt lgkmcnt(0)
	v_ashrrev_i32_e32 v1, 31, v0
	v_and_b32_e32 v12, 3, v72
	v_lshlrev_b64 v[0:1], 11, v[0:1]
	v_lshl_add_u64 v[8:9], s[12:13], 0, v[0:1]
	v_lshlrev_b32_e32 v64, 8, v12
	v_lshl_add_u64 v[10:11], v[8:9], 0, v[64:65]
	s_barrier
	global_load_dwordx4 v[14:17], v[10:11], off offset:1024
	global_load_dwordx4 v[18:21], v[10:11], off offset:1040
	global_load_dwordx4 v[22:25], v[10:11], off offset:1056
	global_load_dwordx4 v[26:29], v[10:11], off offset:1072
	global_load_dwordx4 v[30:33], v[10:11], off offset:1088
	global_load_dwordx4 v[34:37], v[10:11], off offset:1104
	global_load_dwordx4 v[0:3], v[10:11], off offset:1136
	global_load_dwordx4 v[4:7], v[10:11], off offset:1120
	s_lshl_b32 s22, s57, 8
	s_and_b32 s22, s22, 0x100
	v_ashrrev_i32_e32 v70, 4, v72
	v_and_b32_e32 v71, 15, v72
	s_add_i32 s23, s22, s7
	s_waitcnt vmcnt(7)
	v_lshlrev_b32_e32 v38, 16, v14
	v_and_b32_e32 v39, 0xffff0000, v14
	v_add_f32_e32 v56, 0, v38
	v_lshlrev_b32_e32 v40, 16, v15
	v_mul_f32_e32 v14, v39, v39
	v_add_f32_e32 v39, v56, v39
	v_and_b32_e32 v15, 0xffff0000, v15
	v_fmac_f32_e32 v14, v38, v38
	v_add_f32_e32 v38, v39, v40
	v_lshlrev_b32_e32 v41, 16, v16
	v_fmac_f32_e32 v14, v40, v40
	v_add_f32_e32 v38, v38, v15
	v_and_b32_e32 v16, 0xffff0000, v16
	v_fmac_f32_e32 v14, v15, v15
	v_add_f32_e32 v15, v38, v41
	v_lshlrev_b32_e32 v42, 16, v17
	v_fmac_f32_e32 v14, v41, v41
	v_add_f32_e32 v15, v15, v16
	v_and_b32_e32 v17, 0xffff0000, v17
	v_fmac_f32_e32 v14, v16, v16
	v_add_f32_e32 v15, v15, v42
	s_waitcnt vmcnt(6)
	v_lshlrev_b32_e32 v43, 16, v18
	v_fmac_f32_e32 v14, v42, v42
	v_add_f32_e32 v15, v15, v17
	v_and_b32_e32 v18, 0xffff0000, v18
	v_fmac_f32_e32 v14, v17, v17
	v_add_f32_e32 v15, v15, v43
	v_lshlrev_b32_e32 v44, 16, v19
	v_fmac_f32_e32 v14, v43, v43
	v_add_f32_e32 v15, v15, v18
	v_and_b32_e32 v19, 0xffff0000, v19
	v_fmac_f32_e32 v14, v18, v18
	v_add_f32_e32 v15, v15, v44
	v_lshlrev_b32_e32 v45, 16, v20
	v_fmac_f32_e32 v14, v44, v44
	v_add_f32_e32 v15, v15, v19
	v_and_b32_e32 v20, 0xffff0000, v20
	v_fmac_f32_e32 v14, v19, v19
	v_add_f32_e32 v15, v15, v45
	v_lshlrev_b32_e32 v46, 16, v21
	v_fmac_f32_e32 v14, v45, v45
	v_add_f32_e32 v15, v15, v20
	v_and_b32_e32 v21, 0xffff0000, v21
	v_fmac_f32_e32 v14, v20, v20
	v_add_f32_e32 v15, v15, v46
	s_waitcnt vmcnt(5)
	v_lshlrev_b32_e32 v47, 16, v22
	v_fmac_f32_e32 v14, v46, v46
	v_add_f32_e32 v15, v15, v21
	v_and_b32_e32 v22, 0xffff0000, v22
	v_fmac_f32_e32 v14, v21, v21
	v_add_f32_e32 v15, v15, v47
	v_lshlrev_b32_e32 v48, 16, v23
	v_fmac_f32_e32 v14, v47, v47
	v_add_f32_e32 v15, v15, v22
	v_and_b32_e32 v23, 0xffff0000, v23
	v_fmac_f32_e32 v14, v22, v22
	v_add_f32_e32 v15, v15, v48
	v_lshlrev_b32_e32 v49, 16, v24
	v_fmac_f32_e32 v14, v48, v48
	v_add_f32_e32 v15, v15, v23
	v_and_b32_e32 v24, 0xffff0000, v24
	v_fmac_f32_e32 v14, v23, v23
	v_add_f32_e32 v15, v15, v49
	v_lshlrev_b32_e32 v50, 16, v25
	v_fmac_f32_e32 v14, v49, v49
	v_add_f32_e32 v15, v15, v24
	v_and_b32_e32 v25, 0xffff0000, v25
	v_fmac_f32_e32 v14, v24, v24
	v_add_f32_e32 v15, v15, v50
	s_waitcnt vmcnt(4)
	v_lshlrev_b32_e32 v51, 16, v26
	v_fmac_f32_e32 v14, v50, v50
	v_add_f32_e32 v15, v15, v25
	v_and_b32_e32 v26, 0xffff0000, v26
	v_fmac_f32_e32 v14, v25, v25
	v_add_f32_e32 v15, v15, v51
	v_lshlrev_b32_e32 v52, 16, v27
	v_fmac_f32_e32 v14, v51, v51
	v_add_f32_e32 v15, v15, v26
	v_and_b32_e32 v27, 0xffff0000, v27
	v_fmac_f32_e32 v14, v26, v26
	v_add_f32_e32 v15, v15, v52
	v_lshlrev_b32_e32 v53, 16, v28
	v_fmac_f32_e32 v14, v52, v52
	v_add_f32_e32 v15, v15, v27
	v_and_b32_e32 v28, 0xffff0000, v28
	v_fmac_f32_e32 v14, v27, v27
	v_add_f32_e32 v15, v15, v53
	v_lshlrev_b32_e32 v54, 16, v29
	v_fmac_f32_e32 v14, v53, v53
	v_add_f32_e32 v15, v15, v28
	v_and_b32_e32 v29, 0xffff0000, v29
	v_fmac_f32_e32 v14, v28, v28
	v_add_f32_e32 v15, v15, v54
	s_waitcnt vmcnt(3)
	v_lshlrev_b32_e32 v55, 16, v30
	v_fmac_f32_e32 v14, v54, v54
	v_add_f32_e32 v15, v15, v29
	v_and_b32_e32 v30, 0xffff0000, v30
	v_fmac_f32_e32 v14, v29, v29
	v_add_f32_e32 v15, v15, v55
	v_lshlrev_b32_e32 v16, 16, v31
	v_fmac_f32_e32 v14, v55, v55
	v_add_f32_e32 v15, v15, v30
	v_and_b32_e32 v17, 0xffff0000, v31
	v_fmac_f32_e32 v14, v30, v30
	v_add_f32_e32 v15, v15, v16
	v_lshlrev_b32_e32 v18, 16, v32
	v_fmac_f32_e32 v14, v16, v16
	v_add_f32_e32 v15, v15, v17
	v_and_b32_e32 v24, 0xffff0000, v32
	v_fmac_f32_e32 v14, v17, v17
	v_add_f32_e32 v15, v15, v18
	v_lshlrev_b32_e32 v25, 16, v33
	v_fmac_f32_e32 v14, v18, v18
	v_add_f32_e32 v15, v15, v24
	global_load_dwordx4 v[16:19], v[10:11], off offset:1168
	global_load_dwordx4 v[20:23], v[10:11], off offset:1152
	v_and_b32_e32 v26, 0xffff0000, v33
	v_fmac_f32_e32 v14, v24, v24
	v_add_f32_e32 v15, v15, v25
	v_fmac_f32_e32 v14, v25, v25
	v_add_f32_e32 v15, v15, v26
	s_waitcnt vmcnt(4)
	v_lshlrev_b32_e32 v24, 16, v34
	v_fmac_f32_e32 v14, v26, v26
	v_and_b32_e32 v25, 0xffff0000, v34
	v_add_f32_e32 v15, v15, v24
	v_lshlrev_b32_e32 v26, 16, v35
	v_fmac_f32_e32 v14, v24, v24
	v_add_f32_e32 v15, v15, v25
	v_and_b32_e32 v27, 0xffff0000, v35
	v_fmac_f32_e32 v14, v25, v25
	v_add_f32_e32 v15, v15, v26
	v_lshlrev_b32_e32 v28, 16, v36
	v_fmac_f32_e32 v14, v26, v26
	v_add_f32_e32 v15, v15, v27
	v_and_b32_e32 v29, 0xffff0000, v36
	v_fmac_f32_e32 v14, v27, v27
	v_add_f32_e32 v15, v15, v28
	v_lshlrev_b32_e32 v30, 16, v37
	v_fmac_f32_e32 v14, v28, v28
	v_add_f32_e32 v15, v15, v29
	v_and_b32_e32 v31, 0xffff0000, v37
	v_fmac_f32_e32 v14, v29, v29
	v_add_f32_e32 v15, v15, v30
	v_fmac_f32_e32 v14, v30, v30
	v_add_f32_e32 v15, v15, v31
	s_waitcnt vmcnt(2)
; __device__ __forceinline__ float bflo(unsigned w) { return __uint_as_float(w << 16); }
; __device__ __forceinline__ float bfhi(unsigned w) { return __uint_as_float(w & 0xffff0000u); }
; __device__ __forceinline__ void gmlp_prompt_item(const Params& p, int item, const int wv) {
;     ...
;     for (int i = 0; i < 16; ++i) {
;       u32x4 w = *(const u32x4*)(vrow + qq * 128 + i * 8);
;       float f[8] = {bflo(w.x), bfhi(w.x), bflo(w.y), bfhi(w.y), bflo(w.z), bfhi(w.z), bflo(w.w), bfhi(w.w)};
; #pragma unroll
;       for (int e = 0; e < 8; ++e) { sm += f[e]; sq += f[e] * f[e]; }
;     }
	v_lshlrev_b32_e32 v24, 16, v4
	v_fmac_f32_e32 v14, v31, v31
	v_and_b32_e32 v4, 0xffff0000, v4
	v_lshlrev_b32_e32 v26, 16, v6
	v_and_b32_e32 v28, 0xffff0000, v6
	v_add_f32_e32 v6, v15, v24
	v_lshlrev_b32_e32 v25, 16, v5
	v_fmac_f32_e32 v14, v24, v24
	v_add_f32_e32 v6, v6, v4
	v_and_b32_e32 v5, 0xffff0000, v5
	v_fmac_f32_e32 v14, v4, v4
	v_add_f32_e32 v4, v6, v25
	v_fmac_f32_e32 v14, v25, v25
	v_add_f32_e32 v4, v4, v5
	v_fmac_f32_e32 v14, v5, v5
	v_add_f32_e32 v4, v4, v26
	v_lshlrev_b32_e32 v29, 16, v7
	v_and_b32_e32 v30, 0xffff0000, v7
	v_fmac_f32_e32 v14, v26, v26
	v_add_f32_e32 v15, v4, v28
	global_load_dwordx4 v[4:7], v[10:11], off offset:1200
	global_load_dwordx4 v[24:27], v[10:11], off offset:1184
	v_fmac_f32_e32 v14, v28, v28
	v_add_f32_e32 v15, v15, v29
	v_fmac_f32_e32 v14, v29, v29
	v_add_f32_e32 v15, v15, v30
	v_fmac_f32_e32 v14, v30, v30
	v_lshlrev_b32_e32 v28, 16, v0
	v_and_b32_e32 v0, 0xffff0000, v0
	v_add_f32_e32 v15, v15, v28
	v_fmac_f32_e32 v14, v28, v28
	v_lshlrev_b32_e32 v29, 16, v1
	v_add_f32_e32 v15, v15, v0
	v_fmac_f32_e32 v14, v0, v0
	v_and_b32_e32 v1, 0xffff0000, v1
	v_add_f32_e32 v0, v15, v29
	v_fmac_f32_e32 v14, v29, v29
	v_lshlrev_b32_e32 v30, 16, v2
	v_add_f32_e32 v0, v0, v1
	v_fmac_f32_e32 v14, v1, v1
	v_and_b32_e32 v2, 0xffff0000, v2
	v_add_f32_e32 v0, v0, v30
	v_fmac_f32_e32 v14, v30, v30
	v_lshlrev_b32_e32 v31, 16, v3
	v_add_f32_e32 v0, v0, v2
	v_fmac_f32_e32 v14, v2, v2
	v_and_b32_e32 v3, 0xffff0000, v3
	v_add_f32_e32 v0, v0, v31
	v_fmac_f32_e32 v14, v31, v31
	v_add_f32_e32 v0, v0, v3
	v_fmac_f32_e32 v14, v3, v3
	s_waitcnt vmcnt(2)
	v_lshlrev_b32_e32 v1, 16, v20
	v_and_b32_e32 v2, 0xffff0000, v20
	v_add_f32_e32 v0, v0, v1
	v_fmac_f32_e32 v14, v1, v1
	v_lshlrev_b32_e32 v3, 16, v21
	v_add_f32_e32 v0, v0, v2
	v_fmac_f32_e32 v14, v2, v2
	v_and_b32_e32 v15, 0xffff0000, v21
	v_add_f32_e32 v0, v0, v3
	v_fmac_f32_e32 v14, v3, v3
	v_lshlrev_b32_e32 v20, 16, v22
	v_add_f32_e32 v0, v0, v15
	v_fmac_f32_e32 v14, v15, v15
	v_and_b32_e32 v32, 0xffff0000, v22
	v_lshlrev_b32_e32 v33, 16, v23
	v_and_b32_e32 v34, 0xffff0000, v23
	v_add_f32_e32 v0, v0, v20
	v_fmac_f32_e32 v14, v20, v20
	global_load_dwordx4 v[20:23], v[10:11], off offset:1232
	global_load_dwordx4 v[28:31], v[10:11], off offset:1216
	v_add_f32_e32 v0, v0, v32
	v_fmac_f32_e32 v14, v32, v32
	v_add_f32_e32 v0, v0, v33
	v_fmac_f32_e32 v14, v33, v33
	v_add_f32_e32 v0, v0, v34
	v_lshlrev_b32_e32 v1, 16, v16
	v_fmac_f32_e32 v14, v34, v34
	v_and_b32_e32 v2, 0xffff0000, v16
	v_add_f32_e32 v0, v0, v1
	v_lshlrev_b32_e32 v3, 16, v17
	v_fmac_f32_e32 v14, v1, v1
	v_add_f32_e32 v0, v0, v2
	v_and_b32_e32 v15, 0xffff0000, v17
	v_fmac_f32_e32 v14, v2, v2
	v_add_f32_e32 v0, v0, v3
	v_lshlrev_b32_e32 v16, 16, v18
	v_fmac_f32_e32 v14, v3, v3
	v_add_f32_e32 v0, v0, v15
	v_and_b32_e32 v17, 0xffff0000, v18
	v_fmac_f32_e32 v14, v15, v15
	v_add_f32_e32 v0, v0, v16
	v_lshlrev_b32_e32 v18, 16, v19
	v_fmac_f32_e32 v14, v16, v16
	v_add_f32_e32 v0, v0, v17
	v_and_b32_e32 v19, 0xffff0000, v19
	v_fmac_f32_e32 v14, v17, v17
	v_add_f32_e32 v0, v0, v18
	v_fmac_f32_e32 v14, v18, v18
	v_add_f32_e32 v0, v0, v19
	v_fmac_f32_e32 v14, v19, v19
	s_waitcnt vmcnt(2)
	v_lshlrev_b32_e32 v1, 16, v24
	v_and_b32_e32 v2, 0xffff0000, v24
	v_add_f32_e32 v0, v0, v1
	v_lshlrev_b32_e32 v3, 16, v25
	v_fmac_f32_e32 v14, v1, v1
	v_add_f32_e32 v0, v0, v2
	v_and_b32_e32 v15, 0xffff0000, v25
	v_fmac_f32_e32 v14, v2, v2
	v_add_f32_e32 v0, v0, v3
	v_lshlrev_b32_e32 v24, 16, v26
	v_fmac_f32_e32 v14, v3, v3
	v_add_f32_e32 v0, v0, v15
	v_fmac_f32_e32 v14, v15, v15
	v_add_f32_e32 v15, v0, v24
	global_load_dwordx4 v[0:3], v[10:11], off offset:1264
	global_load_dwordx4 v[16:19], v[10:11], off offset:1248
	v_and_b32_e32 v25, 0xffff0000, v26
	v_lshlrev_b32_e32 v26, 16, v27
	v_fmac_f32_e32 v14, v24, v24
	v_add_f32_e32 v10, v15, v25
	v_and_b32_e32 v27, 0xffff0000, v27
	v_fmac_f32_e32 v14, v25, v25
	v_add_f32_e32 v10, v10, v26
	v_fmac_f32_e32 v14, v26, v26
	v_add_f32_e32 v10, v10, v27
	v_lshlrev_b32_e32 v11, 16, v4
	v_fmac_f32_e32 v14, v27, v27
	v_and_b32_e32 v4, 0xffff0000, v4
	v_add_f32_e32 v10, v10, v11
	v_lshlrev_b32_e32 v15, 16, v5
	v_fmac_f32_e32 v14, v11, v11
	v_add_f32_e32 v10, v10, v4
	v_and_b32_e32 v5, 0xffff0000, v5
	v_fmac_f32_e32 v14, v4, v4
	v_add_f32_e32 v4, v10, v15
	v_lshlrev_b32_e32 v24, 16, v6
	v_fmac_f32_e32 v14, v15, v15
	v_add_f32_e32 v4, v4, v5
	v_and_b32_e32 v6, 0xffff0000, v6
	v_fmac_f32_e32 v14, v5, v5
	v_add_f32_e32 v4, v4, v24
	v_lshlrev_b32_e32 v25, 16, v7
	v_fmac_f32_e32 v14, v24, v24
	v_add_f32_e32 v4, v4, v6
	v_and_b32_e32 v7, 0xffff0000, v7
	v_fmac_f32_e32 v14, v6, v6
	v_add_f32_e32 v4, v4, v25
	v_fmac_f32_e32 v14, v25, v25
	v_add_f32_e32 v4, v4, v7
	s_waitcnt vmcnt(2)
	v_lshlrev_b32_e32 v5, 16, v28
	v_fmac_f32_e32 v14, v7, v7
	v_and_b32_e32 v6, 0xffff0000, v28
	v_add_f32_e32 v4, v4, v5
	v_lshlrev_b32_e32 v7, 16, v29
	v_fmac_f32_e32 v14, v5, v5
	v_add_f32_e32 v4, v4, v6
	v_and_b32_e32 v10, 0xffff0000, v29
	v_fmac_f32_e32 v14, v6, v6
	v_add_f32_e32 v4, v4, v7
	v_lshlrev_b32_e32 v11, 16, v30
	v_fmac_f32_e32 v14, v7, v7
	v_add_f32_e32 v4, v4, v10
	v_and_b32_e32 v15, 0xffff0000, v30
	v_fmac_f32_e32 v14, v10, v10
	v_add_f32_e32 v4, v4, v11
	v_lshlrev_b32_e32 v24, 16, v31
	v_fmac_f32_e32 v14, v11, v11
	v_add_f32_e32 v4, v4, v15
	v_and_b32_e32 v25, 0xffff0000, v31
	v_fmac_f32_e32 v14, v15, v15
	v_add_f32_e32 v4, v4, v24
	v_fmac_f32_e32 v14, v24, v24
	v_add_f32_e32 v4, v4, v25
	v_lshlrev_b32_e32 v5, 16, v20
	v_fmac_f32_e32 v14, v25, v25
	v_and_b32_e32 v6, 0xffff0000, v20
	v_add_f32_e32 v4, v4, v5
	v_lshlrev_b32_e32 v7, 16, v21
	v_fmac_f32_e32 v14, v5, v5
	v_add_f32_e32 v4, v4, v6
	v_and_b32_e32 v10, 0xffff0000, v21
	v_fmac_f32_e32 v14, v6, v6
	v_add_f32_e32 v4, v4, v7
	v_lshlrev_b32_e32 v11, 16, v22
	v_fmac_f32_e32 v14, v7, v7
	v_add_f32_e32 v4, v4, v10
	v_and_b32_e32 v15, 0xffff0000, v22
	v_fmac_f32_e32 v14, v10, v10
	v_add_f32_e32 v4, v4, v11
	v_lshlrev_b32_e32 v20, 16, v23
	v_fmac_f32_e32 v14, v11, v11
	v_add_f32_e32 v4, v4, v15
	v_and_b32_e32 v21, 0xffff0000, v23
	v_fmac_f32_e32 v14, v15, v15
	v_add_f32_e32 v4, v4, v20
	v_fmac_f32_e32 v14, v20, v20
	v_add_f32_e32 v4, v4, v21
	s_waitcnt vmcnt(0)
; __device__ __forceinline__ u16 f2bf(float f) { return (u16)(cvt_pk(f, 0.f) & 0xffffu); }
; __device__ __forceinline__ float bflo(unsigned w) { return __uint_as_float(w << 16); }
; __device__ __forceinline__ float bfhi(unsigned w) { return __uint_as_float(w & 0xffff0000u); }
; __device__ __forceinline__ float shfl_xor_f(float v, int mask) { const int l = lane_fresh(); return __int_as_float(__builtin_amdgcn_ds_bpermute((l ^ mask) << 2, __float_as_int(v))); }
; __device__ __forceinline__ void gmlp_prompt_item(const Params& p, int item, const int wv) {
;     ...
;       for (int e = 0; e < 8; ++e) { sm += f[e]; sq += f[e] * f[e]; }
;     }
;     sm += shfl_xor_f(sm, 1); sm += shfl_xor_f(sm, 2); sq += shfl_xor_f(sq, 1); sq += shfl_xor_f(sq, 2);
;     const float mean = sm * (1.f / 512.f), var = fmaxf(sq * (1.f / 512.f) - mean * mean, 0.f), rstd = rsqrtf(var + EPS);
; #pragma unroll
;     for (int i = 0; i < 8; ++i) {
;       const int cl = qq * 64 + i * 8, col = gp * 256 + cl;
;       u32x4 w = *(const u32x4*)(vrow + col);
;       float f[8] = {bflo(w.x), bfhi(w.x), bflo(w.y), bfhi(w.y), bflo(w.z), bfhi(w.z), bflo(w.w), bfhi(w.w)};
; #pragma unroll
;       for (int e = 0; e < 8; ++e) {
;         float vn = (f[e] - mean) * rstd * p.in[9][col + e] + p.in[10][col + e];
;         VnT[(cl + e) * 136 + row] = f2bf(vn);
;       }
	v_lshlrev_b32_e32 v5, 16, v16
	v_fmac_f32_e32 v14, v21, v21
	v_and_b32_e32 v6, 0xffff0000, v16
	v_add_f32_e32 v4, v4, v5
	v_lshlrev_b32_e32 v7, 16, v17
	v_fmac_f32_e32 v14, v5, v5
	v_add_f32_e32 v4, v4, v6
	v_fmac_f32_e32 v14, v6, v6
	v_add_f32_e32 v6, v4, v7
	v_and_b32_e32 v4, 0xffff0000, v17
	v_lshlrev_b32_e32 v5, 16, v18
	v_add_f32_e32 v10, v6, v4
	v_add_f32_e32 v11, v10, v5
	v_lshlrev_b32_e32 v10, 6, v12
	v_fmac_f32_e32 v14, v7, v7
	v_pk_mul_f32 v[6:7], v[4:5], v[4:5]
	v_or_b32_e32 v25, s22, v10
	v_add_f32_e32 v4, v6, v14
	v_lshlrev_b32_e32 v64, 1, v25
	v_add_f32_e32 v24, v7, v4
	v_lshl_add_u64 v[6:7], v[8:9], 0, v[64:65]
	v_mbcnt_lo_u32_b32 v40, -1, 0
	v_mbcnt_hi_u32_b32 v40, -1, v40
	v_mbcnt_lo_u32_b32 v41, -1, 0
	v_mbcnt_hi_u32_b32 v41, -1, v41
	v_mbcnt_lo_u32_b32 v42, -1, 0
	v_mbcnt_hi_u32_b32 v42, -1, v42
	v_mbcnt_lo_u32_b32 v43, -1, 0
	v_mbcnt_hi_u32_b32 v43, -1, v43
	global_load_dwordx4 v[14:17], v[6:7], off offset:1040
	global_load_dwordx4 v[20:23], v[6:7], off offset:1024
	v_lshlrev_b32_e32 v5, 16, v19
	v_and_b32_e32 v4, 0xffff0000, v18
	v_pk_mul_f32 v[8:9], v[4:5], v[4:5]
	v_add_f32_e32 v11, v11, v4
	v_add_f32_e32 v4, v8, v24
	v_add_f32_e32 v4, v9, v4
	v_lshlrev_b32_e32 v9, 2, v25
	global_load_dwordx4 v[24:27], v9, s[62:63]
	global_load_dwordx4 v[28:31], v9, s[64:65]
	v_add_f32_e32 v8, v11, v5
	v_lshlrev_b32_e32 v18, 16, v0
	v_and_b32_e32 v19, 0xffff0000, v19
	v_add_f32_e32 v8, v8, v19
	v_pk_mul_f32 v[32:33], v[18:19], v[18:19]
	v_add_f32_e32 v8, v8, v18
	v_add_f32_e32 v4, v33, v4
	v_lshlrev_b32_e32 v19, 16, v1
	v_and_b32_e32 v18, 0xffff0000, v0
	v_add_f32_e32 v4, v32, v4
	v_pk_mul_f32 v[32:33], v[18:19], v[18:19]
	v_add_f32_e32 v0, v8, v18
	v_add_f32_e32 v4, v32, v4
	v_add_f32_e32 v0, v0, v19
	v_add_f32_e32 v4, v33, v4
	v_lshlrev_b32_e32 v19, 16, v2
	v_and_b32_e32 v18, 0xffff0000, v1
	global_load_dwordx4 v[32:35], v9, s[62:63] offset:16
	global_load_dwordx4 v[36:39], v9, s[64:65] offset:16
	v_add_f32_e32 v8, v0, v18
	v_pk_mul_f32 v[0:1], v[18:19], v[18:19]
	v_and_b32_e32 v5, 0xffff0000, v3
	v_add_f32_e32 v0, v0, v4
	v_add_f32_e32 v4, v8, v19
	v_add_f32_e32 v8, v1, v0
	v_lshlrev_b32_e32 v1, 16, v3
	v_and_b32_e32 v0, 0xffff0000, v2
	v_pk_mul_f32 v[2:3], v[0:1], v[0:1]
	v_add_f32_e32 v4, v4, v0
	v_add_f32_e32 v0, v2, v8
	v_add_f32_e32 v1, v4, v1
	v_add_f32_e32 v4, v3, v0
	v_mul_f32_e32 v0, v5, v5
	v_lshlrev_b32_e32 v2, 2, v40
	v_lshlrev_b32_e32 v3, 2, v42
	v_xor_b32_e32 v2, 4, v2
	v_xor_b32_e32 v8, 4, v3
	v_pk_add_f32 v[0:1], v[0:1], v[4:5]
	s_nop 1
	v_mov_b32_dpp v3, v1 quad_perm:[1,0,3,2] row_mask:0xf bank_mask:0xf
	s_nop 1
	v_mov_b32_dpp v2, v0 quad_perm:[1,0,3,2] row_mask:0xf bank_mask:0xf
	v_lshlrev_b32_e32 v4, 2, v41
	v_lshlrev_b32_e32 v5, 2, v43
	v_xor_b32_e32 v4, 8, v4
	v_xor_b32_e32 v5, 8, v5
	s_waitcnt lgkmcnt(0)
	v_pk_add_f32 v[0:1], v[0:1], v[2:3]
	s_nop 1
	v_mov_b32_dpp v3, v1 quad_perm:[2,3,0,1] row_mask:0xf bank_mask:0xf
	s_nop 1
	v_mov_b32_dpp v2, v0 quad_perm:[2,3,0,1] row_mask:0xf bank_mask:0xf
	global_load_dwordx4 v[40:43], v9, s[62:63] offset:32
	global_load_dwordx4 v[44:47], v9, s[64:65] offset:32
	v_lshl_add_u32 v11, v13, 1, 16
	v_or_b32_e32 v64, s23, v71
	s_addk_i32 s23, 0x80
	s_waitcnt lgkmcnt(0)
	v_pk_add_f32 v[0:1], v[0:1], v[2:3]
	s_waitcnt vmcnt(6)
	v_lshlrev_b32_e32 v8, 16, v20
	v_pk_mul_f32 v[4:5], v[0:1], s[18:19] op_sel_hi:[1,0]
	v_and_b32_e32 v13, 0xffff0000, v20
	v_fma_f32 v0, -v5, v5, v4
	v_max_f32_e32 v0, 0, v0
	v_add_f32_e32 v0, 0x358637bd, v0
	v_mul_f32_e32 v1, 0x4b800000, v0
	v_cmp_gt_f32_e32 vcc, s19, v0
	v_lshlrev_b32_e32 v56, 16, v21
	v_and_b32_e32 v57, 0xffff0000, v21
	v_cndmask_b32_e32 v0, v0, v1, vcc
	v_rsq_f32_e32 v0, v0
	v_sub_f32_e32 v8, v8, v5
	v_lshlrev_b32_e32 v59, 16, v23
	v_and_b32_e32 v60, 0xffff0000, v23
	v_mul_f32_e32 v1, 0x45800000, v0
	v_cndmask_b32_e32 v4, v0, v1, vcc
	global_load_dwordx4 v[0:3], v[6:7], off offset:1072
	global_load_dwordx4 v[48:51], v[6:7], off offset:1056
	global_load_dwordx4 v[18:21], v9, s[62:63] offset:48
	global_load_dwordx4 v[52:55], v9, s[64:65] offset:48
	v_mul_f32_e32 v8, v8, v4
	s_waitcnt vmcnt(8)
	v_fma_f32 v8, v24, v8, v28
	v_cvt_pk_bf16_f32 v23, v8, s0
	v_mad_u32_u24 v8, v12, s20, v11
	v_sub_f32_e32 v12, v13, v5
	v_mul_f32_e32 v12, v12, v4
	v_fma_f32 v12, v25, v12, v29
	v_cvt_pk_bf16_f32 v12, v12, s0
	ds_write_b16 v8, v12 offset:272
	v_sub_f32_e32 v12, v56, v5
	v_mul_f32_e32 v12, v12, v4
	v_fma_f32 v12, v26, v12, v30
	v_cvt_pk_bf16_f32 v12, v12, s0
	ds_write_b16 v8, v12 offset:544
	v_sub_f32_e32 v12, v57, v5
	v_mul_f32_e32 v12, v12, v4
	v_fmac_f32_e32 v31, v27, v12
	v_lshlrev_b32_e32 v58, 16, v22
	v_cvt_pk_bf16_f32 v12, v31, s0
	ds_write_b16 v8, v12 offset:816
	v_sub_f32_e32 v12, v58, v5
	v_mul_f32_e32 v12, v12, v4
	s_waitcnt vmcnt(6)
	v_fma_f32 v12, v32, v12, v36
	v_and_b32_e32 v22, 0xffff0000, v22
	v_cvt_pk_bf16_f32 v12, v12, s0
	ds_write_b16 v8, v23
	ds_write_b16 v8, v12 offset:1088
	v_sub_f32_e32 v12, v22, v5
	v_mul_f32_e32 v12, v12, v4
	global_load_dwordx4 v[22:25], v9, s[62:63] offset:64
	global_load_dwordx4 v[26:29], v9, s[64:65] offset:64
	v_fma_f32 v12, v33, v12, v37
	v_cvt_pk_bf16_f32 v12, v12, s0
	ds_write_b16 v8, v12 offset:1360
	v_sub_f32_e32 v12, v59, v5
	v_mul_f32_e32 v12, v12, v4
	v_fma_f32 v12, v34, v12, v38
	v_cvt_pk_bf16_f32 v12, v12, s0
	ds_write_b16 v8, v12 offset:1632
	v_sub_f32_e32 v12, v60, v5
	v_mul_f32_e32 v12, v12, v4
	v_fmac_f32_e32 v39, v35, v12
	v_lshlrev_b32_e32 v35, 16, v14
	v_lshlrev_b32_e32 v56, 16, v17
	v_and_b32_e32 v57, 0xffff0000, v17
	v_sub_f32_e32 v17, v35, v5
	v_cvt_pk_bf16_f32 v12, v39, s0
	v_mul_f32_e32 v17, v17, v4
	ds_write_b16 v8, v12 offset:1904
	v_or_b32_e32 v34, 8, v10
	s_waitcnt vmcnt(6)
; __device__ __forceinline__ u16 f2bf(float f) { return (u16)(cvt_pk(f, 0.f) & 0xffffu); }
; __device__ __forceinline__ float bflo(unsigned w) { return __uint_as_float(w << 16); }
; __device__ __forceinline__ float bfhi(unsigned w) { return __uint_as_float(w & 0xffff0000u); }
; __device__ __forceinline__ void gmlp_prompt_item(const Params& p, int item, const int wv) {
;     ...
; #pragma unroll
;     for (int i = 0; i < 8; ++i) {
;       const int cl = qq * 64 + i * 8, col = gp * 256 + cl;
;       u32x4 w = *(const u32x4*)(vrow + col);
;       float f[8] = {bflo(w.x), bfhi(w.x), bflo(w.y), bfhi(w.y), bflo(w.z), bfhi(w.z), bflo(w.w), bfhi(w.w)};
; #pragma unroll
;       for (int e = 0; e < 8; ++e) {
;         float vn = (f[e] - mean) * rstd * p.in[9][col + e] + p.in[10][col + e];
;         VnT[(cl + e) * 136 + row] = f2bf(vn);
;       }
;     }
	v_fma_f32 v17, v40, v17, v44
	v_and_b32_e32 v36, 0xffff0000, v14
	v_lshlrev_b32_e32 v37, 16, v15
	v_and_b32_e32 v38, 0xffff0000, v15
	global_load_dwordx4 v[12:15], v9, s[62:63] offset:80
	global_load_dwordx4 v[30:33], v9, s[64:65] offset:80
	v_cvt_pk_bf16_f32 v17, v17, s0
	v_mad_u32_u24 v34, v34, s21, v11
	ds_write_b16 v34, v17
	v_sub_f32_e32 v17, v36, v5
	v_mul_f32_e32 v17, v17, v4
	v_fma_f32 v17, v41, v17, v45
	v_cvt_pk_bf16_f32 v17, v17, s0
	ds_write_b16 v8, v17 offset:2448
	v_sub_f32_e32 v17, v37, v5
	v_mul_f32_e32 v17, v17, v4
	v_fma_f32 v17, v42, v17, v46
	v_cvt_pk_bf16_f32 v17, v17, s0
	ds_write_b16 v8, v17 offset:2720
	v_sub_f32_e32 v17, v38, v5
	v_mul_f32_e32 v17, v17, v4
	v_fmac_f32_e32 v47, v43, v17
	v_lshlrev_b32_e32 v39, 16, v16
	v_and_b32_e32 v16, 0xffff0000, v16
	v_cvt_pk_bf16_f32 v17, v47, s0
	ds_write_b16 v8, v17 offset:2992
	v_sub_f32_e32 v17, v39, v5
	v_sub_f32_e32 v16, v16, v5
	v_mul_f32_e32 v17, v17, v4
	v_mul_f32_e32 v16, v16, v4
	v_sub_f32_e32 v38, v56, v5
	s_waitcnt vmcnt(4)
	v_fma_f32 v17, v18, v17, v52
	v_fma_f32 v16, v19, v16, v53
	v_cvt_pk_bf16_f32 v17, v17, s0
	v_cvt_pk_bf16_f32 v16, v16, s0
	ds_write_b16 v8, v17 offset:3264
	ds_write_b16 v8, v16 offset:3536
	global_load_dwordx4 v[16:19], v9, s[62:63] offset:96
	global_load_dwordx4 v[34:37], v9, s[64:65] offset:96
	v_mul_f32_e32 v38, v38, v4
	v_fma_f32 v20, v20, v38, v54
	v_cvt_pk_bf16_f32 v20, v20, s0
	ds_write_b16 v8, v20 offset:3808
	v_sub_f32_e32 v20, v57, v5
	v_mul_f32_e32 v20, v20, v4
	v_fmac_f32_e32 v55, v21, v20
	v_cvt_pk_bf16_f32 v20, v55, s0
	ds_write_b16 v8, v20 offset:4080
	global_load_dwordx4 v[38:41], v9, s[62:63] offset:112
	global_load_dwordx4 v[42:45], v9, s[64:65] offset:112
	v_lshlrev_b32_e32 v21, 16, v48
	v_sub_f32_e32 v21, v21, v5
	v_mul_f32_e32 v21, v21, v4
	v_or_b32_e32 v20, 16, v10
	v_and_b32_e32 v46, 0xffff0000, v48
	v_mad_u32_u24 v20, v20, s21, v11
	v_lshlrev_b32_e32 v47, 16, v49
	v_and_b32_e32 v48, 0xffff0000, v49
	v_lshlrev_b32_e32 v49, 16, v50
	v_and_b32_e32 v50, 0xffff0000, v50
	v_lshlrev_b32_e32 v52, 16, v51
	v_and_b32_e32 v51, 0xffff0000, v51
	v_lshlrev_b32_e32 v54, 16, v1
	s_waitcnt vmcnt(6)
	v_fma_f32 v21, v22, v21, v26
	v_cvt_pk_bf16_f32 v21, v21, s0
	ds_write_b16 v20, v21
	v_sub_f32_e32 v20, v46, v5
	v_mul_f32_e32 v20, v20, v4
	v_fma_f32 v20, v23, v20, v27
	v_cvt_pk_bf16_f32 v20, v20, s0
	ds_write_b16 v8, v20 offset:4624
	v_sub_f32_e32 v20, v47, v5
	v_mul_f32_e32 v20, v20, v4
	v_fma_f32 v20, v24, v20, v28
	v_cvt_pk_bf16_f32 v20, v20, s0
	ds_write_b16 v8, v20 offset:4896
	v_sub_f32_e32 v20, v48, v5
	v_mul_f32_e32 v20, v20, v4
	v_sub_f32_e32 v28, v49, v5
	v_fmac_f32_e32 v29, v25, v20
	v_mul_f32_e32 v28, v28, v4
	v_cvt_pk_bf16_f32 v20, v29, s0
	ds_write_b16 v8, v20 offset:5168
	global_load_dwordx4 v[20:23], v[6:7], off offset:1104
	global_load_dwordx4 v[24:27], v[6:7], off offset:1088
	v_and_b32_e32 v1, 0xffff0000, v1
	v_lshlrev_b32_e32 v55, 16, v2
	v_and_b32_e32 v2, 0xffff0000, v2
	s_waitcnt vmcnt(6)
	v_fma_f32 v12, v12, v28, v30
	v_cvt_pk_bf16_f32 v12, v12, s0
	ds_write_b16 v8, v12 offset:5440
	v_sub_f32_e32 v12, v50, v5
	v_mul_f32_e32 v12, v12, v4
	v_fma_f32 v12, v13, v12, v31
	v_cvt_pk_bf16_f32 v12, v12, s0
	ds_write_b16 v8, v12 offset:5712
	global_load_dwordx4 v[28:31], v9, s[62:63] offset:128
	global_load_dwordx4 v[46:49], v9, s[64:65] offset:128
	v_sub_f32_e32 v12, v52, v5
	v_mul_f32_e32 v12, v12, v4
	v_fma_f32 v12, v14, v12, v32
	v_cvt_pk_bf16_f32 v12, v12, s0
	ds_write_b16 v8, v12 offset:5984
	v_sub_f32_e32 v12, v51, v5
	v_mul_f32_e32 v12, v12, v4
	v_fmac_f32_e32 v33, v15, v12
	v_cvt_pk_bf16_f32 v12, v33, s0
	v_lshlrev_b32_e32 v33, 16, v0
	v_and_b32_e32 v0, 0xffff0000, v0
	v_sub_f32_e32 v33, v33, v5
	v_sub_f32_e32 v0, v0, v5
	v_mul_f32_e32 v33, v33, v4
	v_mul_f32_e32 v0, v0, v4
	v_or_b32_e32 v32, 24, v10
	ds_write_b16 v8, v12 offset:6256
	v_mad_u32_u24 v32, v32, s21, v11
	global_load_dwordx4 v[12:15], v9, s[62:63] offset:144
	global_load_dwordx4 v[50:53], v9, s[64:65] offset:144
	v_lshlrev_b32_e32 v56, 16, v3
	v_and_b32_e32 v3, 0xffff0000, v3
	s_and_b64 vcc, exec, s[0:1]
	s_waitcnt vmcnt(8)
	v_fma_f32 v16, v16, v33, v34
	v_fma_f32 v0, v17, v0, v35
	v_cvt_pk_bf16_f32 v16, v16, s0
	v_cvt_pk_bf16_f32 v0, v0, s0
	ds_write_b16 v32, v16
	ds_write_b16 v8, v0 offset:6800
	v_sub_f32_e32 v0, v54, v5
	v_mul_f32_e32 v0, v0, v4
	v_fma_f32 v0, v18, v0, v36
	v_cvt_pk_bf16_f32 v0, v0, s0
	ds_write_b16 v8, v0 offset:7072
	v_sub_f32_e32 v0, v1, v5
	v_mul_f32_e32 v0, v0, v4
	v_fmac_f32_e32 v37, v19, v0
	v_cvt_pk_bf16_f32 v0, v37, s0
	ds_write_b16 v8, v0 offset:7344
	v_sub_f32_e32 v0, v55, v5
	v_mul_f32_e32 v0, v0, v4
	s_waitcnt vmcnt(6)
	v_fma_f32 v0, v38, v0, v42
	v_cvt_pk_bf16_f32 v0, v0, s0
	ds_write_b16 v8, v0 offset:7616
	v_sub_f32_e32 v0, v2, v5
	v_mul_f32_e32 v0, v0, v4
	v_fma_f32 v0, v39, v0, v43
	v_cvt_pk_bf16_f32 v0, v0, s0
	ds_write_b16 v8, v0 offset:7888
	global_load_dwordx4 v[16:19], v9, s[62:63] offset:160
	global_load_dwordx4 v[32:35], v9, s[64:65] offset:160
	v_sub_f32_e32 v0, v56, v5
	v_mul_f32_e32 v0, v0, v4
	v_fma_f32 v0, v40, v0, v44
	v_cvt_pk_bf16_f32 v0, v0, s0
	ds_write_b16 v8, v0 offset:8160
	v_sub_f32_e32 v0, v3, v5
	v_mul_f32_e32 v0, v0, v4
	v_fmac_f32_e32 v45, v41, v0
	v_cvt_pk_bf16_f32 v0, v45, s0
	ds_write_b16 v8, v0 offset:8432
	global_load_dwordx4 v[0:3], v[6:7], off offset:1136
	global_load_dwordx4 v[36:39], v[6:7], off offset:1120
	global_load_dwordx4 v[40:43], v9, s[62:63] offset:176
	global_load_dwordx4 v[54:57], v9, s[64:65] offset:176
	v_or_b32_e32 v44, 32, v10
	s_waitcnt vmcnt(10)
; __device__ __forceinline__ u16 f2bf(float f) { return (u16)(cvt_pk(f, 0.f) & 0xffffu); }
; __device__ __forceinline__ float bflo(unsigned w) { return __uint_as_float(w << 16); }
; __device__ __forceinline__ float bfhi(unsigned w) { return __uint_as_float(w & 0xffff0000u); }
; __device__ __forceinline__ void gmlp_prompt_item(const Params& p, int item, const int wv) {
;     ...
; #pragma unroll
;     for (int i = 0; i < 8; ++i) {
;       const int cl = qq * 64 + i * 8, col = gp * 256 + cl;
;       u32x4 w = *(const u32x4*)(vrow + col);
;       float f[8] = {bflo(w.x), bfhi(w.x), bflo(w.y), bfhi(w.y), bflo(w.z), bfhi(w.z), bflo(w.w), bfhi(w.w)};
; #pragma unroll
;       for (int e = 0; e < 8; ++e) {
;         float vn = (f[e] - mean) * rstd * p.in[9][col + e] + p.in[10][col + e];
;         VnT[(cl + e) * 136 + row] = f2bf(vn);
;       }
;     }
;   }
;   __syncthreads();
	v_lshlrev_b32_e32 v6, 16, v24
	v_sub_f32_e32 v6, v6, v5
	v_mul_f32_e32 v6, v6, v4
	v_and_b32_e32 v7, 0xffff0000, v24
	v_lshlrev_b32_e32 v58, 16, v27
	v_and_b32_e32 v59, 0xffff0000, v27
	v_mad_u32_u24 v27, v44, s21, v11
	v_lshlrev_b32_e32 v24, 16, v25
	v_and_b32_e32 v25, 0xffff0000, v25
	v_lshlrev_b32_e32 v45, 16, v26
	v_and_b32_e32 v26, 0xffff0000, v26
	s_waitcnt vmcnt(8)
	v_fma_f32 v6, v28, v6, v46
	v_cvt_pk_bf16_f32 v6, v6, s0
	ds_write_b16 v27, v6
	v_sub_f32_e32 v6, v7, v5
	v_mul_f32_e32 v6, v6, v4
	v_fma_f32 v6, v29, v6, v47
	v_cvt_pk_bf16_f32 v6, v6, s0
	ds_write_b16 v8, v6 offset:8976
	v_sub_f32_e32 v6, v24, v5
	v_mul_f32_e32 v6, v6, v4
	v_fma_f32 v6, v30, v6, v48
	v_cvt_pk_bf16_f32 v6, v6, s0
	ds_write_b16 v8, v6 offset:9248
	v_sub_f32_e32 v6, v25, v5
	v_mul_f32_e32 v6, v6, v4
	v_fmac_f32_e32 v49, v31, v6
	v_cvt_pk_bf16_f32 v6, v49, s0
	ds_write_b16 v8, v6 offset:9520
	v_sub_f32_e32 v6, v45, v5
	v_mul_f32_e32 v6, v6, v4
	s_waitcnt vmcnt(6)
	v_fma_f32 v6, v12, v6, v50
	v_cvt_pk_bf16_f32 v6, v6, s0
	ds_write_b16 v8, v6 offset:9792
	v_sub_f32_e32 v6, v26, v5
	v_mul_f32_e32 v6, v6, v4
	global_load_dwordx4 v[24:27], v9, s[62:63] offset:192
	global_load_dwordx4 v[28:31], v9, s[64:65] offset:192
	v_fma_f32 v6, v13, v6, v51
	v_cvt_pk_bf16_f32 v6, v6, s0
	ds_write_b16 v8, v6 offset:10064
	v_sub_f32_e32 v6, v58, v5
	v_mul_f32_e32 v6, v6, v4
	v_fma_f32 v6, v14, v6, v52
	v_cvt_pk_bf16_f32 v6, v6, s0
	ds_write_b16 v8, v6 offset:10336
	v_sub_f32_e32 v6, v59, v5
	v_mul_f32_e32 v6, v6, v4
	v_lshlrev_b32_e32 v7, 16, v20
	v_fmac_f32_e32 v53, v6, v15
	v_sub_f32_e32 v7, v7, v5
	v_cvt_pk_bf16_f32 v6, v53, s0
	v_mul_f32_e32 v7, v4, v7
	ds_write_b16 v8, v6 offset:10608
	v_or_b32_e32 v6, 40, v10
	v_and_b32_e32 v20, 0xffff0000, v20
	v_mad_u32_u24 v6, v6, s21, v11
	global_load_dwordx4 v[12:15], v9, s[62:63] offset:208
	global_load_dwordx4 v[44:47], v9, s[64:65] offset:208
	v_lshlrev_b32_e32 v48, 16, v21
	v_and_b32_e32 v21, 0xffff0000, v21
	v_lshlrev_b32_e32 v49, 16, v22
	v_and_b32_e32 v50, 0xffff0000, v22
	s_waitcnt vmcnt(8)
	v_fma_f32 v7, v16, v7, v32
	v_cvt_pk_bf16_f32 v7, v7, s0
	ds_write_b16 v6, v7
	v_sub_f32_e32 v6, v20, v5
	v_mul_f32_e32 v6, v4, v6
	v_fma_f32 v6, v17, v6, v33
	v_cvt_pk_bf16_f32 v6, v6, s0
	ds_write_b16 v8, v6 offset:11152
	v_sub_f32_e32 v6, v48, v5
	v_mul_f32_e32 v6, v4, v6
	v_fma_f32 v6, v6, v18, v34
	v_cvt_pk_bf16_f32 v6, v6, s0
	ds_write_b16 v8, v6 offset:11424
	v_sub_f32_e32 v6, v21, v5
	v_mul_f32_e32 v6, v4, v6
	v_fmac_f32_e32 v35, v6, v19
	v_cvt_pk_bf16_f32 v6, v35, s0
	ds_write_b16 v8, v6 offset:11696
	v_sub_f32_e32 v6, v49, v5
	v_mul_f32_e32 v6, v4, v6
	s_waitcnt vmcnt(4)
	v_fma_f32 v6, v6, v40, v54
	v_cvt_pk_bf16_f32 v6, v6, s0
	v_lshlrev_b32_e32 v51, 16, v23
	v_and_b32_e32 v52, 0xffff0000, v23
	global_load_dwordx4 v[16:19], v9, s[62:63] offset:224
	global_load_dwordx4 v[20:23], v9, s[64:65] offset:224
	ds_write_b16 v8, v6 offset:11968
	v_sub_f32_e32 v6, v50, v5
	v_mul_f32_e32 v6, v4, v6
	v_fma_f32 v6, v6, v41, v55
	v_cvt_pk_bf16_f32 v6, v6, s0
	ds_write_b16 v8, v6 offset:12240
	v_sub_f32_e32 v6, v51, v5
	v_mul_f32_e32 v6, v4, v6
	v_fma_f32 v6, v6, v42, v56
	v_cvt_pk_bf16_f32 v6, v6, s0
	ds_write_b16 v8, v6 offset:12512
	v_sub_f32_e32 v6, v52, v5
	v_mul_f32_e32 v6, v4, v6
	v_fmac_f32_e32 v57, v6, v43
	v_cvt_pk_bf16_f32 v6, v57, s0
	ds_write_b16 v8, v6 offset:12784
	global_load_dwordx4 v[32:35], v9, s[62:63] offset:240
	global_load_dwordx4 v[40:43], v9, s[64:65] offset:240
	v_lshlrev_b32_e32 v7, 16, v36
	v_sub_f32_e32 v7, v7, v5
	v_mul_f32_e32 v7, v4, v7
	v_or_b32_e32 v6, 48, v10
	v_and_b32_e32 v36, 0xffff0000, v36
	v_mad_u32_u24 v6, v6, s21, v11
	v_lshlrev_b32_e32 v9, 16, v37
	v_and_b32_e32 v37, 0xffff0000, v37
	v_lshlrev_b32_e32 v48, 16, v38
	v_and_b32_e32 v38, 0xffff0000, v38
	v_lshlrev_b32_e32 v49, 16, v39
	v_and_b32_e32 v39, 0xffff0000, v39
	s_waitcnt vmcnt(6)
	v_fma_f32 v7, v24, v7, v28
	v_cvt_pk_bf16_f32 v7, v7, s0
	ds_write_b16 v6, v7
	v_sub_f32_e32 v6, v36, v5
	v_mul_f32_e32 v6, v4, v6
	v_fma_f32 v6, v25, v6, v29
	v_cvt_pk_bf16_f32 v6, v6, s0
	ds_write_b16 v8, v6 offset:13328
	v_sub_f32_e32 v6, v9, v5
	v_mul_f32_e32 v6, v4, v6
	v_fma_f32 v6, v6, v26, v30
	v_cvt_pk_bf16_f32 v6, v6, s0
	ds_write_b16 v8, v6 offset:13600
	v_sub_f32_e32 v6, v37, v5
	v_mul_f32_e32 v6, v4, v6
	v_fmac_f32_e32 v31, v6, v27
	v_cvt_pk_bf16_f32 v6, v31, s0
	ds_write_b16 v8, v6 offset:13872
	v_sub_f32_e32 v6, v48, v5
	v_mul_f32_e32 v6, v4, v6
	s_waitcnt vmcnt(4)
	v_fma_f32 v6, v6, v12, v44
	v_cvt_pk_bf16_f32 v6, v6, s0
	ds_write_b16 v8, v6 offset:14144
	v_sub_f32_e32 v6, v38, v5
	v_mul_f32_e32 v6, v4, v6
	v_fma_f32 v6, v6, v13, v45
	v_cvt_pk_bf16_f32 v6, v6, s0
	ds_write_b16 v8, v6 offset:14416
	v_sub_f32_e32 v6, v49, v5
	v_mul_f32_e32 v6, v4, v6
	v_fma_f32 v6, v6, v14, v46
	v_cvt_pk_bf16_f32 v6, v6, s0
	ds_write_b16 v8, v6 offset:14688
	v_sub_f32_e32 v6, v39, v5
	v_mul_f32_e32 v6, v4, v6
	v_lshlrev_b32_e32 v7, 16, v0
	v_and_b32_e32 v0, 0xffff0000, v0
	v_fmac_f32_e32 v47, v6, v15
	v_sub_f32_e32 v7, v7, v5
	v_sub_f32_e32 v0, v0, v5
	v_cvt_pk_bf16_f32 v6, v47, s0
	v_mul_f32_e32 v7, v4, v7
	v_mul_f32_e32 v0, v4, v0
	ds_write_b16 v8, v6 offset:14960
	v_or_b32_e32 v6, 56, v10
	v_lshlrev_b32_e32 v9, 16, v1
	v_mad_u32_u24 v6, v6, s21, v11
	v_and_b32_e32 v1, 0xffff0000, v1
	v_lshlrev_b32_e32 v10, 16, v2
	s_waitcnt vmcnt(2)
	v_fma_f32 v7, v16, v7, v20
	v_fma_f32 v0, v17, v0, v21
	v_cvt_pk_bf16_f32 v7, v7, s0
	v_cvt_pk_bf16_f32 v0, v0, s0
	ds_write_b16 v6, v7
	ds_write_b16 v8, v0 offset:15504
	v_sub_f32_e32 v0, v9, v5
	v_mul_f32_e32 v0, v4, v0
	v_fma_f32 v0, v0, v18, v22
	v_cvt_pk_bf16_f32 v0, v0, s0
	ds_write_b16 v8, v0 offset:15776
	v_sub_f32_e32 v0, v1, v5
	v_mul_f32_e32 v0, v4, v0
	v_fmac_f32_e32 v23, v0, v19
	v_cvt_pk_bf16_f32 v0, v23, s0
	ds_write_b16 v8, v0 offset:16048
	v_sub_f32_e32 v0, v10, v5
	v_mul_f32_e32 v0, v4, v0
	s_waitcnt vmcnt(0)
	v_fma_f32 v0, v0, v32, v40
	v_and_b32_e32 v2, 0xffff0000, v2
	v_cvt_pk_bf16_f32 v0, v0, s0
	ds_write_b16 v8, v0 offset:16320
	v_sub_f32_e32 v0, v2, v5
	v_mul_f32_e32 v0, v4, v0
	v_fma_f32 v0, v0, v33, v41
	v_lshlrev_b32_e32 v12, 16, v3
	v_cvt_pk_bf16_f32 v0, v0, s0
	ds_write_b16 v8, v0 offset:16592
	v_sub_f32_e32 v0, v12, v5
	v_mul_f32_e32 v0, v4, v0
	v_fma_f32 v0, v0, v34, v42
	v_and_b32_e32 v3, 0xffff0000, v3
	v_cvt_pk_bf16_f32 v0, v0, s0
	ds_write_b16 v8, v0 offset:16864
	v_sub_f32_e32 v0, v3, v5
	v_mul_f32_e32 v0, v4, v0
	v_fmac_f32_e32 v43, v0, v35
	v_cvt_pk_bf16_f32 v0, v43, s0
	v_lshlrev_b32_e32 v2, 3, v70
	ds_write_b16 v8, v0 offset:17136
	v_lshlrev_b64 v[0:1], 8, v[64:65]
	v_ashrrev_i32_e32 v3, 31, v2
	v_lshl_add_u64 v[0:1], s[2:3], 0, v[0:1]
	v_lshlrev_b64 v[4:5], 1, v[2:3]
	v_lshl_add_u64 v[66:67], v[0:1], 0, v[4:5]
	s_waitcnt lgkmcnt(0)
	s_barrier
; #define MFMA16(a, b, c) __builtin_amdgcn_mfma_f32_16x16x32_bf16((a), (b), (c), 0, 0, 0)
; __device__ __forceinline__ void gmlp_prompt_item(const Params& p, int item, const int wv) {
;     ...
;   f32x4 acc[16];
; #pragma unroll
;   for (int db = 0; db < 16; ++db) acc[db] = (f32x4){0.f, 0.f, 0.f, 0.f};
; #pragma unroll
;   for (int ks = 0; ks < 4; ++ks) {
;     if (ks <= (wid >> 1)) {
;       bf16x8 w0 = *(const bf16x8*)(WSB + ((size_t)(gp * 2) * 128 + wid * 16 + fr) * 128 + ks * 32 + fq * 8);
;       bf16x8 w1 = *(const bf16x8*)(WSB + ((size_t)(gp * 2 + 1) * 128 + wid * 16 + fr) * 128 + ks * 32 + fq * 8);
; #pragma unroll
;       for (int db = 0; db < 16; ++db) {
;         bf16x8 vf = *(const bf16x8*)(VnT + (db * 16 + fr) * 136 + ks * 32 + fq * 8);
;         acc[db] = MFMA16(vf, db < 8 ? w0 : w1, acc[db]);
;       }
;     }
;   }
	global_load_dwordx4 v[0:3], v[66:67], off
	v_or_b32_e32 v64, s23, v71
	v_lshlrev_b64 v[6:7], 8, v[64:65]
	v_lshl_add_u64 v[6:7], s[2:3], 0, v[6:7]
	v_lshl_add_u64 v[68:69], v[6:7], 0, v[4:5]
	global_load_dwordx4 v[4:7], v[68:69], off
	v_and_b32_e32 v8, -16, v72
	v_mul_u32_u24_e32 v9, 0x110, v71
	v_add3_u32 v64, 16, v8, v9
	ds_read_b128 v[8:11], v64
	ds_read_b128 v[12:15], v64 offset:4352
	s_waitcnt vmcnt(1) lgkmcnt(1)
	v_mfma_f32_16x16x32_bf16 v[56:59], v[8:11], v[0:3], 0
	ds_read_b128 v[8:11], v64 offset:8704
	ds_read_b128 v[74:77], v64 offset:60928
	ds_read_b128 v[78:81], v64 offset:65280
	s_waitcnt lgkmcnt(3)
	v_mfma_f32_16x16x32_bf16 v[60:63], v[12:15], v[0:3], 0
	ds_read_b128 v[12:15], v64 offset:13056
	s_waitcnt lgkmcnt(3)
	v_mfma_f32_16x16x32_bf16 v[52:55], v[8:11], v[0:3], 0
	ds_read_b128 v[8:11], v64 offset:17408
	s_waitcnt lgkmcnt(1)
	v_mfma_f32_16x16x32_bf16 v[48:51], v[12:15], v[0:3], 0
	ds_read_b128 v[12:15], v64 offset:21760
	s_waitcnt lgkmcnt(1)
	v_mfma_f32_16x16x32_bf16 v[44:47], v[8:11], v[0:3], 0
	ds_read_b128 v[8:11], v64 offset:26112
	s_waitcnt lgkmcnt(1)
	v_mfma_f32_16x16x32_bf16 v[40:43], v[12:15], v[0:3], 0
	ds_read_b128 v[12:15], v64 offset:30464
	s_waitcnt lgkmcnt(1)
	v_mfma_f32_16x16x32_bf16 v[36:39], v[8:11], v[0:3], 0
	ds_read_b128 v[8:11], v64 offset:34816
	s_waitcnt lgkmcnt(1)
	v_mfma_f32_16x16x32_bf16 v[32:35], v[12:15], v[0:3], 0
	ds_read_b128 v[0:3], v64 offset:39168
	s_waitcnt vmcnt(0) lgkmcnt(1)
	v_mfma_f32_16x16x32_bf16 v[28:31], v[8:11], v[4:7], 0
	ds_read_b128 v[8:11], v64 offset:43520
	s_waitcnt lgkmcnt(1)
	v_mfma_f32_16x16x32_bf16 v[24:27], v[0:3], v[4:7], 0
	ds_read_b128 v[0:3], v64 offset:47872
	s_waitcnt lgkmcnt(1)
	v_mfma_f32_16x16x32_bf16 v[20:23], v[8:11], v[4:7], 0
	ds_read_b128 v[8:11], v64 offset:52224
	s_waitcnt lgkmcnt(1)
	v_mfma_f32_16x16x32_bf16 v[16:19], v[0:3], v[4:7], 0
	ds_read_b128 v[0:3], v64 offset:56576
	s_waitcnt lgkmcnt(1)
	v_mfma_f32_16x16x32_bf16 v[12:15], v[8:11], v[4:7], 0
	s_waitcnt lgkmcnt(0)
	v_mfma_f32_16x16x32_bf16 v[8:11], v[0:3], v[4:7], 0
	v_mfma_f32_16x16x32_bf16 v[0:3], v[74:77], v[4:7], 0
	v_mfma_f32_16x16x32_bf16 v[4:7], v[78:81], v[4:7], 0
	s_cbranch_vccnz .LBB0_555
	global_load_dwordx4 v[74:77], v[66:67], off offset:64
	global_load_dwordx4 v[78:81], v[68:69], off offset:64
	ds_read_b128 v[82:85], v64 offset:64
	ds_read_b128 v[86:89], v64 offset:4416
	s_waitcnt vmcnt(1) lgkmcnt(1)
	v_mfma_f32_16x16x32_bf16 v[56:59], v[82:85], v[74:77], v[56:59]
	ds_read_b128 v[82:85], v64 offset:8768
	s_waitcnt lgkmcnt(1)
	v_mfma_f32_16x16x32_bf16 v[60:63], v[86:89], v[74:77], v[60:63]
	ds_read_b128 v[86:89], v64 offset:13120
	s_waitcnt lgkmcnt(1)
	v_mfma_f32_16x16x32_bf16 v[52:55], v[82:85], v[74:77], v[52:55]
	ds_read_b128 v[82:85], v64 offset:17472
	s_waitcnt lgkmcnt(1)
	v_mfma_f32_16x16x32_bf16 v[48:51], v[86:89], v[74:77], v[48:51]
	ds_read_b128 v[86:89], v64 offset:21824
	s_waitcnt lgkmcnt(1)
	v_mfma_f32_16x16x32_bf16 v[44:47], v[82:85], v[74:77], v[44:47]
	ds_read_b128 v[82:85], v64 offset:26176
	s_waitcnt lgkmcnt(1)
	v_mfma_f32_16x16x32_bf16 v[40:43], v[86:89], v[74:77], v[40:43]
	ds_read_b128 v[86:89], v64 offset:30528
	s_waitcnt lgkmcnt(1)
	v_mfma_f32_16x16x32_bf16 v[36:39], v[82:85], v[74:77], v[36:39]
	ds_read_b128 v[82:85], v64 offset:34880
	s_waitcnt lgkmcnt(1)
	v_mfma_f32_16x16x32_bf16 v[32:35], v[86:89], v[74:77], v[32:35]
	ds_read_b128 v[74:77], v64 offset:39232
	s_waitcnt vmcnt(0) lgkmcnt(1)
	v_mfma_f32_16x16x32_bf16 v[28:31], v[82:85], v[78:81], v[28:31]
	ds_read_b128 v[82:85], v64 offset:43584
	s_waitcnt lgkmcnt(1)
	v_mfma_f32_16x16x32_bf16 v[24:27], v[74:77], v[78:81], v[24:27]
	ds_read_b128 v[74:77], v64 offset:47936
	s_waitcnt lgkmcnt(1)
	v_mfma_f32_16x16x32_bf16 v[20:23], v[82:85], v[78:81], v[20:23]
	ds_read_b128 v[82:85], v64 offset:52288
	s_waitcnt lgkmcnt(1)
	v_mfma_f32_16x16x32_bf16 v[16:19], v[74:77], v[78:81], v[16:19]
	ds_read_b128 v[74:77], v64 offset:56640
	s_waitcnt lgkmcnt(1)
	v_mfma_f32_16x16x32_bf16 v[12:15], v[82:85], v[78:81], v[12:15]
	ds_read_b128 v[82:85], v64 offset:60992
	s_waitcnt lgkmcnt(1)
	v_mfma_f32_16x16x32_bf16 v[8:11], v[74:77], v[78:81], v[8:11]
	ds_read_b128 v[74:77], v64 offset:65344
	s_waitcnt lgkmcnt(1)
	v_mfma_f32_16x16x32_bf16 v[0:3], v[82:85], v[78:81], v[0:3]
	s_waitcnt lgkmcnt(0)
	v_mfma_f32_16x16x32_bf16 v[4:7], v[74:77], v[78:81], v[4:7]
	s_andn2_b64 vcc, exec, s[8:9]
	s_cbranch_vccz .LBB0_556

; __device__ __forceinline__ float shfl_xor_f(float v, int mask) { const int l = lane_fresh(); return __int_as_float(__builtin_amdgcn_ds_bpermute((l ^ mask) << 2, __float_as_int(v))); }
; __device__ __forceinline__ void phaseG(const Params& p, const int wv, const int rep, unsigned* bar, const bool fused) {
;     ...
;       if (last_l[0]) {
;         __builtin_amdgcn_fence(__ATOMIC_ACQUIRE, "agent");
;         const int r = tid >> 5, c32 = tid & 31;
;         float* yrow = p.out + O_Y + (size_t)(TP + mt * 16 + r) * 1024;
;         float sq = __hip_atomic_load(XSS + (size_t)(mt * 16 + r) * 64 + c32 * 2, __ATOMIC_RELAXED, __HIP_MEMORY_SCOPE_AGENT)
;                  + __hip_atomic_load(XSS + (size_t)(mt * 16 + r) * 64 + c32 * 2 + 1, __ATOMIC_RELAXED, __HIP_MEMORY_SCOPE_AGENT);
;         sq += shfl_xor_f(sq, 16); sq += shfl_xor_f(sq, 8); sq += shfl_xor_f(sq, 4); sq += shfl_xor_f(sq, 2); sq += shfl_xor_f(sq, 1);
;         const float rs = rsqrtf(sq * (1.f / 1024.f) + EPS);
; #pragma unroll
;         for (int i = 0; i < 8; ++i) {
;           const int col = i * 128 + c32 * 4;
;           f32x4 v = *(const f32x4*)(yrow + col);
;           *(f32x4*)(yrow + col) = v * rs * *(const f32x4*)(wfin + col);
;         }
.LBB0_1200:
	s_or_b64 exec, exec, s[24:25]
	s_waitcnt lgkmcnt(0)
	s_barrier
	ds_read_b32 v2, v15 offset:32768
	s_waitcnt lgkmcnt(0)
	v_cmp_eq_u32_e32 vcc, 0, v2
	s_cbranch_vccnz .LBB0_1182
	v_ashrrev_i32_e32 v2, 5, v1
	v_and_b32_e32 v3, 31, v0
	v_add_u32_e32 v0, s22, v2
	v_ashrrev_i32_e32 v1, 31, v0
	v_lshlrev_b64 v[0:1], 8, v[0:1]
	v_lshl_add_u64 v[0:1], s[10:11], 0, v[0:1]
	v_lshlrev_b32_e32 v4, 3, v3
	v_lshl_add_u64 v[0:1], v[0:1], 0, v[4:5]
	s_waitcnt vmcnt(0)
	buffer_inv sc1
	global_load_dword v10, v[0:1], off sc1
	global_load_dword v11, v[0:1], off offset:4 sc1
	v_add_u32_e32 v0, s20, v2
	v_ashrrev_i32_e32 v1, 31, v0
	v_lshlrev_b64 v[0:1], 12, v[0:1]
	v_lshl_add_u64 v[0:1], s[48:49], 0, v[0:1]
	v_lshlrev_b32_e32 v4, 4, v3
	v_lshl_add_u64 v[16:17], v[0:1], 0, v[4:5]
	v_mbcnt_lo_u32_b32 v12, -1, 0
	v_mbcnt_hi_u32_b32 v12, -1, v12
	v_mbcnt_lo_u32_b32 v13, -1, 0
	v_mbcnt_hi_u32_b32 v13, -1, v13
	v_mbcnt_lo_u32_b32 v18, -1, 0
	v_mbcnt_hi_u32_b32 v18, -1, v18
	v_mbcnt_lo_u32_b32 v19, -1, 0
	v_mbcnt_hi_u32_b32 v19, -1, v19
	v_mbcnt_lo_u32_b32 v20, -1, 0
	v_mbcnt_hi_u32_b32 v20, -1, v20
	global_load_dwordx4 v[60:63], v[16:17], off
	global_load_dwordx4 v[92:95], v4, s[46:47]
	global_load_dwordx4 v[64:67], v[16:17], off offset:512
	global_load_dwordx4 v[96:99], v4, s[46:47] offset:512
	global_load_dwordx4 v[68:71], v[16:17], off offset:1024
	global_load_dwordx4 v[100:103], v4, s[46:47] offset:1024
	global_load_dwordx4 v[72:75], v[16:17], off offset:1536
	global_load_dwordx4 v[104:107], v4, s[46:47] offset:1536
	global_load_dwordx4 v[76:79], v[16:17], off offset:2048
	global_load_dwordx4 v[108:111], v4, s[46:47] offset:2048
	global_load_dwordx4 v[80:83], v[16:17], off offset:2560
	global_load_dwordx4 v[112:115], v4, s[46:47] offset:2560
	global_load_dwordx4 v[84:87], v[16:17], off offset:3072
	global_load_dwordx4 v[116:119], v4, s[46:47] offset:3072
	global_load_dwordx4 v[88:91], v[16:17], off offset:3584
	global_load_dwordx4 v[120:123], v4, s[46:47] offset:3584
	v_lshlrev_b32_e32 v12, 2, v12
	v_xor_b32_e32 v12, 64, v12
	s_waitcnt vmcnt(16)
	v_add_f32_e32 v10, v11, v10
	ds_bpermute_b32 v11, v12, v10
	v_lshlrev_b32_e32 v12, 2, v13
	v_xor_b32_e32 v12, 32, v12
	s_waitcnt lgkmcnt(0)
	v_add_f32_e32 v10, v10, v11
	s_nop 1
	v_mov_b32_dpp v11, v10 row_ror:8 row_mask:0xf bank_mask:0xf
	v_lshlrev_b32_e32 v12, 2, v18
	v_xor_b32_e32 v12, 16, v12
	s_waitcnt lgkmcnt(0)
	v_add_f32_e32 v10, v10, v11
	s_nop 1
	v_mov_b32_dpp v11, v10 row_shl:4 row_mask:0xf bank_mask:0x5
	v_mov_b32_dpp v11, v10 row_shr:4 row_mask:0xf bank_mask:0xa
	v_lshlrev_b32_e32 v12, 2, v19
	v_xor_b32_e32 v12, 8, v12
	s_waitcnt lgkmcnt(0)
	v_add_f32_e32 v10, v10, v11
	s_nop 1
	v_mov_b32_dpp v11, v10 quad_perm:[2,3,0,1] row_mask:0xf bank_mask:0xf
	v_lshlrev_b32_e32 v12, 2, v20
	v_xor_b32_e32 v12, 4, v12
	s_waitcnt lgkmcnt(0)
	v_add_f32_e32 v10, v10, v11
	s_nop 1
	v_mov_b32_dpp v11, v10 quad_perm:[1,0,3,2] row_mask:0xf bank_mask:0xf
	s_waitcnt lgkmcnt(0)
	v_add_f32_e32 v10, v10, v11
	v_fmamk_f32 v10, v10, 0x3a800000, v14
	v_mul_f32_e32 v11, 0x4b800000, v10
	v_cmp_gt_f32_e32 vcc, s37, v10
	s_nop 1
	v_cndmask_b32_e32 v10, v10, v11, vcc
	v_rsq_f32_e32 v18, v10
	v_mul_f32_e32 v19, 0x45800000, v18
	v_cndmask_b32_e32 v18, v18, v19, vcc
	s_waitcnt vmcnt(14)
	v_pk_mul_f32 v[60:61], v[60:61], v[18:19] op_sel_hi:[1,0]
	v_pk_mul_f32 v[62:63], v[62:63], v[18:19] op_sel_hi:[1,0]
	v_pk_mul_f32 v[60:61], v[92:93], v[60:61]
	v_pk_mul_f32 v[62:63], v[94:95], v[62:63]
	global_store_dwordx4 v[16:17], v[60:63], off sc1
	s_waitcnt vmcnt(13)
	v_pk_mul_f32 v[64:65], v[64:65], v[18:19] op_sel_hi:[1,0]
	v_pk_mul_f32 v[66:67], v[66:67], v[18:19] op_sel_hi:[1,0]
	v_pk_mul_f32 v[64:65], v[96:97], v[64:65]
	v_pk_mul_f32 v[66:67], v[98:99], v[66:67]
	global_store_dwordx4 v[16:17], v[64:67], off offset:512 sc1
	s_waitcnt vmcnt(12)
	v_pk_mul_f32 v[68:69], v[68:69], v[18:19] op_sel_hi:[1,0]
	v_pk_mul_f32 v[70:71], v[70:71], v[18:19] op_sel_hi:[1,0]
	v_pk_mul_f32 v[68:69], v[100:101], v[68:69]
	v_pk_mul_f32 v[70:71], v[102:103], v[70:71]
	global_store_dwordx4 v[16:17], v[68:71], off offset:1024 sc1
	s_waitcnt vmcnt(11)
	v_pk_mul_f32 v[72:73], v[72:73], v[18:19] op_sel_hi:[1,0]
	v_pk_mul_f32 v[74:75], v[74:75], v[18:19] op_sel_hi:[1,0]
	v_pk_mul_f32 v[72:73], v[104:105], v[72:73]
	v_pk_mul_f32 v[74:75], v[106:107], v[74:75]
	global_store_dwordx4 v[16:17], v[72:75], off offset:1536 sc1
	s_waitcnt vmcnt(10)
	v_pk_mul_f32 v[76:77], v[76:77], v[18:19] op_sel_hi:[1,0]
	v_pk_mul_f32 v[78:79], v[78:79], v[18:19] op_sel_hi:[1,0]
	v_pk_mul_f32 v[76:77], v[108:109], v[76:77]
	v_pk_mul_f32 v[78:79], v[110:111], v[78:79]
	global_store_dwordx4 v[16:17], v[76:79], off offset:2048 sc1
	s_waitcnt vmcnt(9)
	v_pk_mul_f32 v[80:81], v[80:81], v[18:19] op_sel_hi:[1,0]
	v_pk_mul_f32 v[82:83], v[82:83], v[18:19] op_sel_hi:[1,0]
	v_pk_mul_f32 v[80:81], v[112:113], v[80:81]
	v_pk_mul_f32 v[82:83], v[114:115], v[82:83]
	global_store_dwordx4 v[16:17], v[80:83], off offset:2560 sc1
	s_waitcnt vmcnt(8)
	v_pk_mul_f32 v[84:85], v[84:85], v[18:19] op_sel_hi:[1,0]
	v_pk_mul_f32 v[86:87], v[86:87], v[18:19] op_sel_hi:[1,0]
	v_pk_mul_f32 v[84:85], v[116:117], v[84:85]
	v_pk_mul_f32 v[86:87], v[118:119], v[86:87]
	global_store_dwordx4 v[16:17], v[84:87], off offset:3072 sc1
	s_waitcnt vmcnt(7)
	v_pk_mul_f32 v[88:89], v[88:89], v[18:19] op_sel_hi:[1,0]
	v_pk_mul_f32 v[90:91], v[90:91], v[18:19] op_sel_hi:[1,0]
	v_pk_mul_f32 v[88:89], v[120:121], v[88:89]
	v_pk_mul_f32 v[90:91], v[122:123], v[90:91]
	global_store_dwordx4 v[16:17], v[88:91], off offset:3584 sc1
	s_branch .LBB0_1182

; __device__ __forceinline__ void phaseH(const Params& p, const int wv, const int rep) {
;     ...
;   for (int r_ = gw; r_ < T * rep; r_ += nw) {
;     const int r = r_ >= T ? r_ - T : r_;
;     float* x = p.out + O_Y + (size_t)r * 1024;
;     f32x4 v[4]; float ss = 0.f;
; #pragma unroll
;     for (int i = 0; i < 4; ++i) { v[i] = *(const f32x4*)(x + (i * 64 + lane) * 4); ss += v[i][0] * v[i][0] + v[i][1] * v[i][1] + v[i][2] * v[i][2] + v[i][3] * v[i][3]; }
;     ss = wave_sum(ss);
;     const float rstd = rsqrtf(ss * (1.f / 1024.f) + EPS);
; #pragma unroll
;     for (int i = 0; i < 4; ++i) { f32x4 wv = *(const f32x4*)(w + (i * 64 + lane) * 4); *(f32x4*)(x + (i * 64 + lane) * 4) = v[i] * rstd * wv; }
;   }
.LBB0_1259:
	global_load_dwordx4 v[6:9], v[2:3], off offset:-3072
	global_load_dwordx4 v[10:13], v[2:3], off offset:-2048
	global_load_dwordx4 v[14:17], v[2:3], off offset:-1024
	global_load_dwordx4 v[18:21], v[2:3], off
	v_mbcnt_lo_u32_b32 v5, -1, 0
	v_mbcnt_hi_u32_b32 v5, -1, v5
	v_mbcnt_lo_u32_b32 v42, -1, 0
	v_mbcnt_hi_u32_b32 v42, -1, v42
	v_mbcnt_lo_u32_b32 v43, -1, 0
	v_mbcnt_hi_u32_b32 v43, -1, v43
	v_mbcnt_lo_u32_b32 v44, -1, 0
	v_mbcnt_hi_u32_b32 v44, -1, v44
	v_mbcnt_lo_u32_b32 v45, -1, 0
	v_mbcnt_hi_u32_b32 v45, -1, v45
	v_mbcnt_lo_u32_b32 v46, -1, 0
	v_mbcnt_hi_u32_b32 v46, -1, v46
	global_load_dwordx4 v[22:25], v[0:1], off
	v_lshlrev_b32_e32 v5, 2, v5
	v_xor_b32_e32 v5, 0x80, v5
	s_add_i32 s4, s4, s6
	s_cmpk_lt_i32 s4, 0x4080
	s_waitcnt vmcnt(4)
	v_mov_b32_e32 v28, v7
	s_waitcnt vmcnt(3)
	v_mov_b32_e32 v29, v11
	v_mov_b32_e32 v26, v6
	v_mov_b32_e32 v27, v10
	s_waitcnt vmcnt(2)
	v_mov_b32_e32 v36, v15
	s_waitcnt vmcnt(1)
	v_mov_b32_e32 v37, v19
	v_pk_mul_f32 v[28:29], v[28:29], v[28:29]
	v_mov_b32_e32 v30, v8
	v_mov_b32_e32 v31, v12
	v_mov_b32_e32 v34, v14
	v_mov_b32_e32 v35, v18
	v_pk_mul_f32 v[36:37], v[36:37], v[36:37]
	v_pk_fma_f32 v[26:27], v[26:27], v[26:27], v[28:29]
	v_mov_b32_e32 v32, v9
	v_mov_b32_e32 v33, v13
	v_mov_b32_e32 v38, v16
	v_mov_b32_e32 v39, v20
	v_pk_fma_f32 v[28:29], v[34:35], v[34:35], v[36:37]
	v_pk_fma_f32 v[26:27], v[30:31], v[30:31], v[26:27]
	v_mov_b32_e32 v40, v17
	v_mov_b32_e32 v41, v21
	v_pk_fma_f32 v[28:29], v[38:39], v[38:39], v[28:29]
	v_pk_fma_f32 v[26:27], v[32:33], v[32:33], v[26:27]
	v_pk_fma_f32 v[28:29], v[40:41], v[40:41], v[28:29]
	v_add_f32_e32 v26, v26, v27
	v_add_f32_e32 v26, v26, v28
	v_add_f32_e32 v26, v26, v29
	ds_bpermute_b32 v5, v5, v26
	v_lshlrev_b32_e32 v27, 2, v42
	v_xor_b32_e32 v27, 64, v27
	s_waitcnt lgkmcnt(0)
	v_add_f32_e32 v5, v26, v5
	ds_bpermute_b32 v26, v27, v5
	v_lshlrev_b32_e32 v27, 2, v43
	v_xor_b32_e32 v27, 32, v27
	s_waitcnt lgkmcnt(0)
	v_add_f32_e32 v5, v5, v26
	s_nop 1
	v_mov_b32_dpp v26, v5 row_ror:8 row_mask:0xf bank_mask:0xf
	v_lshlrev_b32_e32 v27, 2, v44
	v_xor_b32_e32 v27, 16, v27
	s_waitcnt lgkmcnt(0)
	v_add_f32_e32 v5, v5, v26
	s_nop 1
	v_mov_b32_dpp v26, v5 row_shl:4 row_mask:0xf bank_mask:0x5
	v_mov_b32_dpp v26, v5 row_shr:4 row_mask:0xf bank_mask:0xa
	v_lshlrev_b32_e32 v27, 2, v45
	v_xor_b32_e32 v27, 8, v27
	s_waitcnt lgkmcnt(0)
	v_add_f32_e32 v5, v5, v26
	s_nop 1
	v_mov_b32_dpp v26, v5 quad_perm:[2,3,0,1] row_mask:0xf bank_mask:0xf
	v_lshlrev_b32_e32 v27, 2, v46
	v_xor_b32_e32 v27, 4, v27
	s_waitcnt lgkmcnt(0)
	v_add_f32_e32 v5, v5, v26
	s_nop 1
	v_mov_b32_dpp v26, v5 quad_perm:[1,0,3,2] row_mask:0xf bank_mask:0xf
	s_waitcnt lgkmcnt(0)
	v_add_f32_e32 v5, v5, v26
	v_fmamk_f32 v5, v5, 0x3a800000, v4
	v_mul_f32_e32 v26, 0x4b800000, v5
	v_cmp_gt_f32_e32 vcc, s2, v5
	s_nop 1
	v_cndmask_b32_e32 v5, v5, v26, vcc
	v_rsq_f32_e32 v5, v5
	s_nop 0
	v_mul_f32_e32 v26, 0x45800000, v5
	v_cndmask_b32_e32 v26, v5, v26, vcc
	v_pk_mul_f32 v[6:7], v[6:7], v[26:27] op_sel_hi:[1,0]
	v_pk_mul_f32 v[8:9], v[8:9], v[26:27] op_sel_hi:[1,0]
	s_waitcnt vmcnt(0)
	v_pk_mul_f32 v[6:7], v[22:23], v[6:7]
	v_pk_mul_f32 v[8:9], v[24:25], v[8:9]
	global_store_dwordx4 v[2:3], v[6:9], off offset:-3072 sc1
	global_load_dwordx4 v[6:9], v[0:1], off offset:1024
	v_pk_mul_f32 v[12:13], v[12:13], v[26:27] op_sel_hi:[1,0]
	v_pk_mul_f32 v[10:11], v[10:11], v[26:27] op_sel_hi:[1,0]
	s_waitcnt vmcnt(0)
	v_pk_mul_f32 v[8:9], v[8:9], v[12:13]
	v_pk_mul_f32 v[6:7], v[6:7], v[10:11]
	global_store_dwordx4 v[2:3], v[6:9], off offset:-2048 sc1
	global_load_dwordx4 v[6:9], v[0:1], off offset:2048
	v_pk_mul_f32 v[10:11], v[16:17], v[26:27] op_sel_hi:[1,0]
	v_pk_mul_f32 v[12:13], v[14:15], v[26:27] op_sel_hi:[1,0]
	s_waitcnt vmcnt(0)
	v_pk_mul_f32 v[8:9], v[8:9], v[10:11]
	v_pk_mul_f32 v[6:7], v[6:7], v[12:13]
	global_store_dwordx4 v[2:3], v[6:9], off offset:-1024 sc1
	global_load_dwordx4 v[6:9], v[0:1], off offset:3072
	v_pk_mul_f32 v[10:11], v[20:21], v[26:27] op_sel_hi:[1,0]
	v_pk_mul_f32 v[12:13], v[18:19], v[26:27] op_sel_hi:[1,0]
	s_waitcnt vmcnt(0)
	v_pk_mul_f32 v[8:9], v[8:9], v[10:11]
	v_pk_mul_f32 v[6:7], v[6:7], v[12:13]
	global_store_dwordx4 v[2:3], v[6:9], off sc1
	v_lshl_add_u64 v[2:3], v[2:3], 0, s[0:1]
	s_cbranch_scc1 .LBB0_1259
